# GEMM K loops: per-phase s_setprio flips removed, one static s_setprio 1 for waves 4..7 at loop entry (reset after the loop)
# speedup vs baseline: 1.0074x; 1.0074x over previous
.LBB0_117:
	s_ashr_i32 s45, s44, 31
	v_cmp_lt_i64_e32 vcc, s[10:11], v[186:187]
	s_lshl_b64 s[10:11], s[44:45], 20
	v_readlane_b32 s46, v254, 52
	v_readlane_b32 s47, v254, 53
	s_add_u32 s46, s46, s10
	s_addc_u32 s47, s47, s11
	s_and_b64 s[10:11], vcc, exec
	v_readlane_b32 s52, v254, 2
	s_cselect_b32 s5, s47, s7
	s_cselect_b32 s33, s46, s6
	s_ashr_i32 s43, s42, 31
	v_readlane_b32 s53, v254, 3
	s_lshl_b64 s[10:11], s[42:43], 20
	s_mov_b64 s[48:49], s[52:53]
	s_add_u32 s48, s48, s10
	s_addc_u32 s49, s49, s11
	s_and_b64 s[10:11], vcc, exec
	s_cselect_b32 s43, s49, s9
	s_cselect_b32 s45, s48, s8
	s_add_u32 s6, s6, 0x80080
	s_addc_u32 s7, s7, 0
	s_add_u32 s51, s8, 0x100
	s_waitcnt lgkmcnt(0)
	v_mov_b32_e32 v0, 0
	s_addc_u32 s52, s9, 0
	s_mov_b32 s53, -2
	v_mov_b32_e32 v1, v0
	v_mov_b32_e32 v2, v0
	v_mov_b32_e32 v3, v0
	v_mov_b32_e32 v8, v0
	v_mov_b32_e32 v9, v0
	v_mov_b32_e32 v10, v0
	v_mov_b32_e32 v11, v0
	v_mov_b32_e32 v16, v0
	v_mov_b32_e32 v17, v0
	v_mov_b32_e32 v18, v0
	v_mov_b32_e32 v19, v0
	v_mov_b32_e32 v24, v0
	v_mov_b32_e32 v25, v0
	v_mov_b32_e32 v26, v0
	v_mov_b32_e32 v27, v0
	v_mov_b32_e32 v32, v0
	v_mov_b32_e32 v33, v0
	v_mov_b32_e32 v34, v0
	v_mov_b32_e32 v35, v0
	v_mov_b32_e32 v40, v0
	v_mov_b32_e32 v41, v0
	v_mov_b32_e32 v42, v0
	v_mov_b32_e32 v43, v0
	v_mov_b32_e32 v48, v0
	v_mov_b32_e32 v49, v0
	v_mov_b32_e32 v50, v0
	v_mov_b32_e32 v51, v0
	v_mov_b32_e32 v56, v0
	v_mov_b32_e32 v57, v0
	v_mov_b32_e32 v58, v0
	v_mov_b32_e32 v59, v0
	v_mov_b32_e32 v4, v0
	v_mov_b32_e32 v5, v0
	v_mov_b32_e32 v6, v0
	v_mov_b32_e32 v7, v0
	v_mov_b32_e32 v12, v0
	v_mov_b32_e32 v13, v0
	v_mov_b32_e32 v14, v0
	v_mov_b32_e32 v15, v0
	v_mov_b32_e32 v20, v0
	v_mov_b32_e32 v21, v0
	v_mov_b32_e32 v22, v0
	v_mov_b32_e32 v23, v0
	v_mov_b32_e32 v28, v0
	v_mov_b32_e32 v29, v0
	v_mov_b32_e32 v30, v0
	v_mov_b32_e32 v31, v0
	v_mov_b32_e32 v36, v0
	v_mov_b32_e32 v37, v0
	v_mov_b32_e32 v38, v0
	v_mov_b32_e32 v39, v0
	v_mov_b32_e32 v44, v0
	v_mov_b32_e32 v45, v0
	v_mov_b32_e32 v46, v0
	v_mov_b32_e32 v47, v0
	v_mov_b32_e32 v52, v0
	v_mov_b32_e32 v53, v0
	v_mov_b32_e32 v54, v0
	v_mov_b32_e32 v55, v0
	v_mov_b32_e32 v60, v0
	v_mov_b32_e32 v61, v0
	v_mov_b32_e32 v62, v0
	v_mov_b32_e32 v63, v0
	v_mov_b32_e32 v64, v0
	v_mov_b32_e32 v65, v0
	v_mov_b32_e32 v66, v0
	v_mov_b32_e32 v67, v0
	v_mov_b32_e32 v72, v0
	v_mov_b32_e32 v73, v0
	v_mov_b32_e32 v74, v0
	v_mov_b32_e32 v75, v0
	v_mov_b32_e32 v80, v0
	v_mov_b32_e32 v81, v0
	v_mov_b32_e32 v82, v0
	v_mov_b32_e32 v83, v0
	v_mov_b32_e32 v88, v0
	v_mov_b32_e32 v89, v0
	v_mov_b32_e32 v90, v0
	v_mov_b32_e32 v91, v0
	v_mov_b32_e32 v96, v0
	v_mov_b32_e32 v97, v0
	v_mov_b32_e32 v98, v0
	v_mov_b32_e32 v99, v0
	v_mov_b32_e32 v104, v0
	v_mov_b32_e32 v105, v0
	v_mov_b32_e32 v106, v0
	v_mov_b32_e32 v107, v0
	v_mov_b32_e32 v112, v0
	v_mov_b32_e32 v113, v0
	v_mov_b32_e32 v114, v0
	v_mov_b32_e32 v115, v0
	v_mov_b32_e32 v120, v0
	v_mov_b32_e32 v121, v0
	v_mov_b32_e32 v122, v0
	v_mov_b32_e32 v123, v0
	v_mov_b32_e32 v68, v0
	v_mov_b32_e32 v69, v0
	v_mov_b32_e32 v70, v0
	v_mov_b32_e32 v71, v0
	v_mov_b32_e32 v76, v0
	v_mov_b32_e32 v77, v0
	v_mov_b32_e32 v78, v0
	v_mov_b32_e32 v79, v0
	v_mov_b32_e32 v84, v0
	v_mov_b32_e32 v85, v0
	v_mov_b32_e32 v86, v0
	v_mov_b32_e32 v87, v0
	v_mov_b32_e32 v92, v0
	v_mov_b32_e32 v93, v0
	v_mov_b32_e32 v94, v0
	v_mov_b32_e32 v95, v0
	v_mov_b32_e32 v100, v0
	v_mov_b32_e32 v101, v0
	v_mov_b32_e32 v102, v0
	v_mov_b32_e32 v103, v0
	v_mov_b32_e32 v108, v0
	v_mov_b32_e32 v109, v0
	v_mov_b32_e32 v110, v0
	v_mov_b32_e32 v111, v0
	v_mov_b32_e32 v116, v0
	v_mov_b32_e32 v117, v0
	v_mov_b32_e32 v118, v0
	v_mov_b32_e32 v119, v0
	v_mov_b32_e32 v124, v0
	v_mov_b32_e32 v125, v0
	v_mov_b32_e32 v126, v0
	v_mov_b32_e32 v127, v0
	v_readlane_b32 s54, v254, 4
	v_readlane_b32 s55, v254, 5
	v_readlane_b32 s70, v254, 44
	s_cmp_lt_u32 s70, 4
	s_cbranch_scc1 .Lsp_0
	s_setprio 1
.Lsp_0:
.LBB0_118:
	ds_read_b128 v[128:131], v221
	ds_read_b128 v[132:135], v221 offset:1024
	ds_read_b128 v[136:139], v221 offset:2048
	ds_read_b128 v[140:143], v221 offset:3072
	s_add_u32 s8, s6, 0xfff80080
	s_addc_u32 s9, s7, -1
	s_cmp_eq_u32 s53, 28
	s_cselect_b32 s11, s5, s9
	s_cselect_b32 s10, s33, s8
	s_cselect_b32 s9, s43, s52
	s_cselect_b32 s8, s45, s51
	v_lshl_add_u64 v[198:199], s[6:7], 0, v[182:183]
	s_add_i32 m0, s58, 0xc000
	ds_read_b128 v[144:147], v222
	ds_read_b128 v[148:151], v222 offset:1024
	ds_read_b128 v[152:155], v222 offset:2048
	ds_read_b128 v[156:159], v222 offset:3072
	ds_read_b128 v[160:163], v222 offset:4096
	ds_read_b128 v[164:167], v222 offset:5120
	ds_read_b128 v[190:193], v222 offset:6144
	ds_read_b128 v[194:197], v222 offset:7168
	global_load_lds_dwordx4 v[198:199], off
	v_lshl_add_u64 v[198:199], s[6:7], 0, v[184:185]
	s_add_i32 m0, s58, 0xe000
	s_nop 0
	global_load_lds_dwordx4 v[198:199], off
	s_waitcnt lgkmcnt(8)
	s_barrier
	s_waitcnt lgkmcnt(0)

	s_waitcnt lgkmcnt(0)
	v_mfma_f32_16x16x32_bf16 v[124:127], v[128:131], v[144:147], v[124:127]
	v_mfma_f32_16x16x32_bf16 v[116:119], v[136:139], v[144:147], v[116:119]
	v_mfma_f32_16x16x32_bf16 v[108:111], v[128:131], v[152:155], v[108:111]
	v_mfma_f32_16x16x32_bf16 v[100:103], v[136:139], v[152:155], v[100:103]
	v_mfma_f32_16x16x32_bf16 v[92:95], v[128:131], v[160:163], v[92:95]
	v_mfma_f32_16x16x32_bf16 v[84:87], v[136:139], v[160:163], v[84:87]
	v_mfma_f32_16x16x32_bf16 v[76:79], v[128:131], v[190:193], v[76:79]
	v_mfma_f32_16x16x32_bf16 v[68:71], v[136:139], v[190:193], v[68:71]
	v_mfma_f32_16x16x32_bf16 v[124:127], v[132:135], v[148:151], v[124:127]
	v_mfma_f32_16x16x32_bf16 v[116:119], v[140:143], v[148:151], v[116:119]
	v_mfma_f32_16x16x32_bf16 v[108:111], v[132:135], v[156:159], v[108:111]
	v_mfma_f32_16x16x32_bf16 v[100:103], v[140:143], v[156:159], v[100:103]
	v_mfma_f32_16x16x32_bf16 v[92:95], v[132:135], v[164:167], v[92:95]
	v_mfma_f32_16x16x32_bf16 v[84:87], v[140:143], v[164:167], v[84:87]
	v_mfma_f32_16x16x32_bf16 v[76:79], v[132:135], v[194:197], v[76:79]
	v_mfma_f32_16x16x32_bf16 v[68:71], v[140:143], v[194:197], v[68:71]

	s_barrier
	s_add_i32 s54, s81, s57
	v_lshl_add_u64 v[230:231], s[8:9], 0, v[172:173]
	s_mov_b32 m0, s54
	ds_read_b128 v[198:201], v223
	ds_read_b128 v[202:205], v223 offset:1024
	ds_read_b128 v[206:209], v223 offset:2048
	ds_read_b128 v[226:229], v223 offset:3072
	global_load_lds_dwordx4 v[230:231], off
	v_lshl_add_u64 v[232:233], s[8:9], 0, v[174:175]
	s_add_i32 m0, s54, 0x2000
	s_nop 0
	global_load_lds_dwordx4 v[232:233], off
	s_barrier
	s_waitcnt lgkmcnt(0)

	s_waitcnt lgkmcnt(0)
	v_mfma_f32_16x16x32_bf16 v[120:123], v[198:201], v[144:147], v[120:123]
	v_mfma_f32_16x16x32_bf16 v[112:115], v[206:209], v[144:147], v[112:115]
	v_mfma_f32_16x16x32_bf16 v[104:107], v[198:201], v[152:155], v[104:107]
	v_mfma_f32_16x16x32_bf16 v[96:99], v[206:209], v[152:155], v[96:99]
	v_mfma_f32_16x16x32_bf16 v[88:91], v[198:201], v[160:163], v[88:91]
	v_mfma_f32_16x16x32_bf16 v[80:83], v[206:209], v[160:163], v[80:83]
	v_mfma_f32_16x16x32_bf16 v[72:75], v[198:201], v[190:193], v[72:75]
	v_mfma_f32_16x16x32_bf16 v[64:67], v[206:209], v[190:193], v[64:67]
	v_mfma_f32_16x16x32_bf16 v[120:123], v[202:205], v[148:151], v[120:123]
	v_mfma_f32_16x16x32_bf16 v[112:115], v[226:229], v[148:151], v[112:115]
	v_mfma_f32_16x16x32_bf16 v[104:107], v[202:205], v[156:159], v[104:107]
	v_mfma_f32_16x16x32_bf16 v[96:99], v[226:229], v[156:159], v[96:99]
	v_mfma_f32_16x16x32_bf16 v[88:91], v[202:205], v[164:167], v[88:91]
	v_mfma_f32_16x16x32_bf16 v[80:83], v[226:229], v[164:167], v[80:83]
	v_mfma_f32_16x16x32_bf16 v[72:75], v[202:205], v[194:197], v[72:75]
	v_mfma_f32_16x16x32_bf16 v[64:67], v[226:229], v[194:197], v[64:67]

	s_mov_b32 m0, s58
	v_lshl_add_u64 v[234:235], s[10:11], 0, v[172:173]
	s_barrier
	ds_read_b128 v[144:147], v222 offset:16384
	ds_read_b128 v[148:151], v222 offset:17408
	ds_read_b128 v[152:155], v222 offset:18432
	ds_read_b128 v[156:159], v222 offset:19456
	ds_read_b128 v[160:163], v222 offset:20480
	ds_read_b128 v[164:167], v222 offset:21504
	ds_read_b128 v[190:193], v222 offset:22528
	ds_read_b128 v[194:197], v222 offset:23552
	global_load_lds_dwordx4 v[234:235], off
	v_lshl_add_u64 v[236:237], s[10:11], 0, v[174:175]
	s_mov_b32 m0, s59
	s_nop 0
	global_load_lds_dwordx4 v[236:237], off
	s_barrier
	s_waitcnt lgkmcnt(0)

	s_waitcnt lgkmcnt(0)
	v_mfma_f32_16x16x32_bf16 v[60:63], v[128:131], v[144:147], v[60:63]
	v_mfma_f32_16x16x32_bf16 v[52:55], v[136:139], v[144:147], v[52:55]
	v_mfma_f32_16x16x32_bf16 v[44:47], v[128:131], v[152:155], v[44:47]
	v_mfma_f32_16x16x32_bf16 v[36:39], v[136:139], v[152:155], v[36:39]
	v_mfma_f32_16x16x32_bf16 v[28:31], v[128:131], v[160:163], v[28:31]
	v_mfma_f32_16x16x32_bf16 v[20:23], v[136:139], v[160:163], v[20:23]
	v_mfma_f32_16x16x32_bf16 v[12:15], v[128:131], v[190:193], v[12:15]
	v_mfma_f32_16x16x32_bf16 v[4:7], v[136:139], v[190:193], v[4:7]
	v_mfma_f32_16x16x32_bf16 v[60:63], v[132:135], v[148:151], v[60:63]
	v_mfma_f32_16x16x32_bf16 v[52:55], v[140:143], v[148:151], v[52:55]
	v_mfma_f32_16x16x32_bf16 v[44:47], v[132:135], v[156:159], v[44:47]
	v_mfma_f32_16x16x32_bf16 v[36:39], v[140:143], v[156:159], v[36:39]
	v_mfma_f32_16x16x32_bf16 v[28:31], v[132:135], v[164:167], v[28:31]
	v_mfma_f32_16x16x32_bf16 v[20:23], v[140:143], v[164:167], v[20:23]
	v_mfma_f32_16x16x32_bf16 v[12:15], v[132:135], v[194:197], v[12:15]
	v_mfma_f32_16x16x32_bf16 v[4:7], v[140:143], v[194:197], v[4:7]

	s_barrier
	s_add_u32 s54, s8, 0x80000
	s_addc_u32 s55, s9, 0
	s_add_i32 vcc_lo, s30, s57
	v_lshl_add_u64 v[128:129], s[54:55], 0, v[172:173]
	s_mov_b32 m0, vcc_lo
	s_nop 0
	global_load_lds_dwordx4 v[128:129], off
	v_lshl_add_u64 v[128:129], s[54:55], 0, v[174:175]
	s_add_i32 m0, vcc_lo, 0x2000
	s_nop 0
	global_load_lds_dwordx4 v[128:129], off
	s_waitcnt vmcnt(6)
	s_barrier

	v_mfma_f32_16x16x32_bf16 v[56:59], v[198:201], v[144:147], v[56:59]
	v_mfma_f32_16x16x32_bf16 v[48:51], v[206:209], v[144:147], v[48:51]
	v_mfma_f32_16x16x32_bf16 v[40:43], v[198:201], v[152:155], v[40:43]
	v_mfma_f32_16x16x32_bf16 v[32:35], v[206:209], v[152:155], v[32:35]
	v_mfma_f32_16x16x32_bf16 v[24:27], v[198:201], v[160:163], v[24:27]
	v_mfma_f32_16x16x32_bf16 v[16:19], v[206:209], v[160:163], v[16:19]
	v_mfma_f32_16x16x32_bf16 v[8:11], v[198:201], v[190:193], v[8:11]
	v_mfma_f32_16x16x32_bf16 v[0:3], v[206:209], v[190:193], v[0:3]
	v_mfma_f32_16x16x32_bf16 v[56:59], v[202:205], v[148:151], v[56:59]
	v_mfma_f32_16x16x32_bf16 v[48:51], v[226:229], v[148:151], v[48:51]
	v_mfma_f32_16x16x32_bf16 v[40:43], v[202:205], v[156:159], v[40:43]
	v_mfma_f32_16x16x32_bf16 v[32:35], v[226:229], v[156:159], v[32:35]
	v_mfma_f32_16x16x32_bf16 v[24:27], v[202:205], v[164:167], v[24:27]
	v_mfma_f32_16x16x32_bf16 v[16:19], v[226:229], v[164:167], v[16:19]
	v_mfma_f32_16x16x32_bf16 v[8:11], v[202:205], v[194:197], v[8:11]
	v_mfma_f32_16x16x32_bf16 v[0:3], v[226:229], v[194:197], v[0:3]

	s_add_i32 s54, 0, 0x18000
	v_add_u32_e32 v140, s54, v179
	s_barrier
	ds_read_b128 v[128:131], v140
	ds_read_b128 v[132:135], v140 offset:1024
	ds_read_b128 v[136:139], v140 offset:2048
	ds_read_b128 v[140:143], v140 offset:3072
	s_add_u32 s10, s10, 0x80000
	s_addc_u32 s11, s11, 0
	s_mov_b32 m0, s2
	v_lshl_add_u64 v[198:199], s[10:11], 0, v[172:173]
	ds_read_b128 v[144:147], v222 offset:32768
	ds_read_b128 v[148:151], v222 offset:33792
	ds_read_b128 v[152:155], v222 offset:34816
	ds_read_b128 v[156:159], v222 offset:35840
	ds_read_b128 v[160:163], v222 offset:36864
	ds_read_b128 v[164:167], v222 offset:37888
	ds_read_b128 v[190:193], v222 offset:38912
	ds_read_b128 v[194:197], v222 offset:39936
	global_load_lds_dwordx4 v[198:199], off
	v_lshl_add_u64 v[198:199], s[10:11], 0, v[174:175]
	s_mov_b32 m0, s3
	s_nop 0
	global_load_lds_dwordx4 v[198:199], off
	s_waitcnt lgkmcnt(8)
	s_barrier
	s_waitcnt lgkmcnt(0)

	s_waitcnt lgkmcnt(0)
	v_mfma_f32_16x16x32_bf16 v[124:127], v[128:131], v[144:147], v[124:127]
	v_mfma_f32_16x16x32_bf16 v[116:119], v[136:139], v[144:147], v[116:119]
	v_mfma_f32_16x16x32_bf16 v[108:111], v[128:131], v[152:155], v[108:111]
	v_mfma_f32_16x16x32_bf16 v[100:103], v[136:139], v[152:155], v[100:103]
	v_mfma_f32_16x16x32_bf16 v[92:95], v[128:131], v[160:163], v[92:95]
	v_mfma_f32_16x16x32_bf16 v[84:87], v[136:139], v[160:163], v[84:87]
	v_mfma_f32_16x16x32_bf16 v[76:79], v[128:131], v[190:193], v[76:79]
	v_mfma_f32_16x16x32_bf16 v[68:71], v[136:139], v[190:193], v[68:71]
	v_mfma_f32_16x16x32_bf16 v[124:127], v[132:135], v[148:151], v[124:127]
	v_mfma_f32_16x16x32_bf16 v[116:119], v[140:143], v[148:151], v[116:119]
	v_mfma_f32_16x16x32_bf16 v[108:111], v[132:135], v[156:159], v[108:111]
	v_mfma_f32_16x16x32_bf16 v[100:103], v[140:143], v[156:159], v[100:103]
	v_mfma_f32_16x16x32_bf16 v[92:95], v[132:135], v[164:167], v[92:95]
	v_mfma_f32_16x16x32_bf16 v[84:87], v[140:143], v[164:167], v[84:87]
	v_mfma_f32_16x16x32_bf16 v[76:79], v[132:135], v[194:197], v[76:79]
	v_mfma_f32_16x16x32_bf16 v[68:71], v[140:143], v[194:197], v[68:71]

	s_barrier
	s_add_i32 s10, 0, 0x1c000
	s_add_i32 s11, s54, s57
	v_add_u32_e32 v180, s10, v179
	v_lshl_add_u64 v[230:231], v[230:231], 0, s[20:21]
	s_mov_b32 m0, s11
	ds_read_b128 v[198:201], v180
	ds_read_b128 v[202:205], v180 offset:1024
	ds_read_b128 v[206:209], v180 offset:2048
	ds_read_b128 v[226:229], v180 offset:3072
	global_load_lds_dwordx4 v[230:231], off
	v_lshl_add_u64 v[230:231], v[232:233], 0, s[20:21]
	s_add_i32 m0, s11, 0x2000
	s_nop 0
	global_load_lds_dwordx4 v[230:231], off
	s_barrier
	s_waitcnt lgkmcnt(0)

	s_waitcnt lgkmcnt(0)
	v_mfma_f32_16x16x32_bf16 v[120:123], v[198:201], v[144:147], v[120:123]
	v_mfma_f32_16x16x32_bf16 v[112:115], v[206:209], v[144:147], v[112:115]
	v_mfma_f32_16x16x32_bf16 v[104:107], v[198:201], v[152:155], v[104:107]
	v_mfma_f32_16x16x32_bf16 v[96:99], v[206:209], v[152:155], v[96:99]
	v_mfma_f32_16x16x32_bf16 v[88:91], v[198:201], v[160:163], v[88:91]
	v_mfma_f32_16x16x32_bf16 v[80:83], v[206:209], v[160:163], v[80:83]
	v_mfma_f32_16x16x32_bf16 v[72:75], v[198:201], v[190:193], v[72:75]
	v_mfma_f32_16x16x32_bf16 v[64:67], v[206:209], v[190:193], v[64:67]
	v_mfma_f32_16x16x32_bf16 v[120:123], v[202:205], v[148:151], v[120:123]
	v_mfma_f32_16x16x32_bf16 v[112:115], v[226:229], v[148:151], v[112:115]
	v_mfma_f32_16x16x32_bf16 v[104:107], v[202:205], v[156:159], v[104:107]
	v_mfma_f32_16x16x32_bf16 v[96:99], v[226:229], v[156:159], v[96:99]
	v_mfma_f32_16x16x32_bf16 v[88:91], v[202:205], v[164:167], v[88:91]
	v_mfma_f32_16x16x32_bf16 v[80:83], v[226:229], v[164:167], v[80:83]
	v_mfma_f32_16x16x32_bf16 v[72:75], v[202:205], v[194:197], v[72:75]
	v_mfma_f32_16x16x32_bf16 v[64:67], v[226:229], v[194:197], v[64:67]

	s_mov_b32 m0, s96
	v_lshl_add_u64 v[230:231], v[234:235], 0, s[20:21]
	s_barrier
	ds_read_b128 v[144:147], v222 offset:49152
	ds_read_b128 v[148:151], v222 offset:50176
	ds_read_b128 v[152:155], v222 offset:51200
	ds_read_b128 v[156:159], v222 offset:52224
	ds_read_b128 v[160:163], v222 offset:53248
	ds_read_b128 v[164:167], v222 offset:54272
	ds_read_b128 v[190:193], v222 offset:55296
	ds_read_b128 v[194:197], v222 offset:56320
	global_load_lds_dwordx4 v[230:231], off
	v_lshl_add_u64 v[230:231], v[236:237], 0, s[20:21]
	s_mov_b32 m0, s97
	s_nop 0
	global_load_lds_dwordx4 v[230:231], off
	s_barrier
	s_waitcnt lgkmcnt(0)

	s_waitcnt lgkmcnt(0)
	v_mfma_f32_16x16x32_bf16 v[60:63], v[128:131], v[144:147], v[60:63]
	v_mfma_f32_16x16x32_bf16 v[52:55], v[136:139], v[144:147], v[52:55]
	v_mfma_f32_16x16x32_bf16 v[44:47], v[128:131], v[152:155], v[44:47]
	v_mfma_f32_16x16x32_bf16 v[36:39], v[136:139], v[152:155], v[36:39]
	v_mfma_f32_16x16x32_bf16 v[28:31], v[128:131], v[160:163], v[28:31]
	v_mfma_f32_16x16x32_bf16 v[20:23], v[136:139], v[160:163], v[20:23]
	v_mfma_f32_16x16x32_bf16 v[12:15], v[128:131], v[190:193], v[12:15]
	v_mfma_f32_16x16x32_bf16 v[4:7], v[136:139], v[190:193], v[4:7]
	v_mfma_f32_16x16x32_bf16 v[60:63], v[132:135], v[148:151], v[60:63]
	v_mfma_f32_16x16x32_bf16 v[52:55], v[140:143], v[148:151], v[52:55]
	v_mfma_f32_16x16x32_bf16 v[44:47], v[132:135], v[156:159], v[44:47]
	v_mfma_f32_16x16x32_bf16 v[36:39], v[140:143], v[156:159], v[36:39]
	v_mfma_f32_16x16x32_bf16 v[28:31], v[132:135], v[164:167], v[28:31]
	v_mfma_f32_16x16x32_bf16 v[20:23], v[140:143], v[164:167], v[20:23]
	v_mfma_f32_16x16x32_bf16 v[12:15], v[132:135], v[194:197], v[12:15]
	v_mfma_f32_16x16x32_bf16 v[4:7], v[140:143], v[194:197], v[4:7]

	s_barrier
	s_add_u32 s8, s8, 0x80080
	s_addc_u32 s9, s9, 0
	s_add_i32 s10, s10, s57
	v_lshl_add_u64 v[128:129], s[8:9], 0, v[172:173]
	s_mov_b32 m0, s10
	s_nop 0
	global_load_lds_dwordx4 v[128:129], off
	v_lshl_add_u64 v[128:129], s[8:9], 0, v[174:175]
	s_add_i32 m0, s10, 0x2000
	s_nop 0
	global_load_lds_dwordx4 v[128:129], off
	s_waitcnt vmcnt(6)
	s_barrier

	v_mfma_f32_16x16x32_bf16 v[56:59], v[198:201], v[144:147], v[56:59]
	v_mfma_f32_16x16x32_bf16 v[48:51], v[206:209], v[144:147], v[48:51]
	v_mfma_f32_16x16x32_bf16 v[40:43], v[198:201], v[152:155], v[40:43]
	v_mfma_f32_16x16x32_bf16 v[32:35], v[206:209], v[152:155], v[32:35]
	v_mfma_f32_16x16x32_bf16 v[24:27], v[198:201], v[160:163], v[24:27]
	v_mfma_f32_16x16x32_bf16 v[16:19], v[206:209], v[160:163], v[16:19]
	v_mfma_f32_16x16x32_bf16 v[8:11], v[198:201], v[190:193], v[8:11]
	v_mfma_f32_16x16x32_bf16 v[0:3], v[206:209], v[190:193], v[0:3]
	v_mfma_f32_16x16x32_bf16 v[56:59], v[202:205], v[148:151], v[56:59]
	v_mfma_f32_16x16x32_bf16 v[48:51], v[226:229], v[148:151], v[48:51]
	v_mfma_f32_16x16x32_bf16 v[40:43], v[202:205], v[156:159], v[40:43]
	v_mfma_f32_16x16x32_bf16 v[32:35], v[226:229], v[156:159], v[32:35]
	v_mfma_f32_16x16x32_bf16 v[24:27], v[202:205], v[164:167], v[24:27]
	v_mfma_f32_16x16x32_bf16 v[16:19], v[226:229], v[164:167], v[16:19]
	v_mfma_f32_16x16x32_bf16 v[8:11], v[202:205], v[194:197], v[8:11]
	v_mfma_f32_16x16x32_bf16 v[0:3], v[226:229], v[194:197], v[0:3]

	s_add_i32 s53, s53, 2
	s_add_u32 s6, s6, 0x100
	s_addc_u32 s7, s7, 0
	s_add_u32 s51, s51, 0x100
	s_addc_u32 s52, s52, 0
	s_cmp_gt_u32 s53, 29
	s_barrier
	s_cbranch_scc0 .LBB0_118
	s_setprio 0
	v_mov_b32_e32 v142, v210
	v_mov_b32_e32 v143, v169
	s_lshl_b32 s33, s4, 8
	s_add_i32 s33, s33, s34
	v_lshl_add_u32 v133, v142, 4, v143
	v_ashrrev_i32_e32 v198, 2, v133
	v_and_b32_e32 v192, 3, v143
	v_and_b32_e32 v128, -4, v133
	s_cmp_gt_i32 s4, 30
	v_lshl_add_u32 v226, v192, 6, v128
	v_add_u32_e32 v190, s33, v198
	s_cselect_b64 s[52:53], -1, 0
	s_cmp_gt_i32 s50, 8
	s_mov_b64 s[4:5], -1
	s_cbranch_scc0 .LBB0_419
	s_cmp_lg_u32 s50, 9
	s_cbranch_scc0 .LBB0_225
	s_cmp_gt_u32 s50, 25
	s_cbranch_scc0 .LBB0_127
	v_mul_f32_e32 v130, 0xbfb8aa3b, v120
	v_mul_f32_e32 v131, 0xbfb8aa3b, v121
	v_mul_f32_e32 v132, 0xbfb8aa3b, v122
	v_mul_f32_e32 v134, 0xbfb8aa3b, v123
	v_mul_f32_e32 v135, 0xbfb8aa3b, v112
	v_mul_f32_e32 v136, 0xbfb8aa3b, v113
	v_mul_f32_e32 v137, 0xbfb8aa3b, v114
	v_mul_f32_e32 v138, 0xbfb8aa3b, v115
	v_mul_f32_e32 v139, 0xbfb8aa3b, v104
	v_mul_f32_e32 v140, 0xbfb8aa3b, v105
	v_mul_f32_e32 v141, 0xbfb8aa3b, v106
	v_mul_f32_e32 v144, 0xbfb8aa3b, v107
	v_mul_f32_e32 v145, 0xbfb8aa3b, v96
	v_mul_f32_e32 v146, 0xbfb8aa3b, v97
	v_mul_f32_e32 v147, 0xbfb8aa3b, v98
	v_mul_f32_e32 v148, 0xbfb8aa3b, v99
	v_mul_f32_e32 v149, 0xbfb8aa3b, v88
	v_mul_f32_e32 v150, 0xbfb8aa3b, v89
	v_mul_f32_e32 v151, 0xbfb8aa3b, v90
	v_mul_f32_e32 v152, 0xbfb8aa3b, v91
	v_mul_f32_e32 v153, 0xbfb8aa3b, v80
	v_mul_f32_e32 v154, 0xbfb8aa3b, v81
	v_mul_f32_e32 v155, 0xbfb8aa3b, v82
	v_mul_f32_e32 v180, 0xbfb8aa3b, v83
	v_mul_f32_e32 v206, 0xbfb8aa3b, v72
	v_mul_f32_e32 v207, 0xbfb8aa3b, v73
	v_mul_f32_e32 v208, 0xbfb8aa3b, v74
	v_mul_f32_e32 v209, 0xbfb8aa3b, v75
	v_mul_f32_e32 v227, 0xbfb8aa3b, v64
	v_mul_f32_e32 v228, 0xbfb8aa3b, v65
	v_mul_f32_e32 v229, 0xbfb8aa3b, v66
	v_mul_f32_e32 v230, 0xbfb8aa3b, v67
	v_exp_f32_e32 v205, v130
	v_exp_f32_e32 v204, v131
	v_exp_f32_e32 v203, v132
	v_exp_f32_e32 v202, v134
	v_exp_f32_e32 v200, v135
	v_exp_f32_e32 v199, v136
	v_exp_f32_e32 v197, v137
	v_exp_f32_e32 v196, v138
	v_exp_f32_e32 v195, v139
	v_exp_f32_e32 v194, v140
	v_exp_f32_e32 v193, v141
	v_exp_f32_e32 v167, v144
	v_exp_f32_e32 v166, v145
	v_exp_f32_e32 v165, v146
	v_exp_f32_e32 v164, v147
	v_exp_f32_e32 v163, v148
	v_exp_f32_e32 v162, v149
	v_exp_f32_e32 v161, v150
	v_exp_f32_e32 v160, v151
	v_exp_f32_e32 v159, v152
	v_exp_f32_e32 v158, v153
	v_exp_f32_e32 v157, v154
	v_exp_f32_e32 v156, v155
	v_exp_f32_e32 v155, v180
	v_exp_f32_e32 v154, v206
	v_exp_f32_e32 v153, v207
	v_exp_f32_e32 v152, v208
	v_exp_f32_e32 v151, v209
	v_exp_f32_e32 v150, v227
	v_exp_f32_e32 v149, v228
	v_exp_f32_e32 v148, v229
	v_exp_f32_e32 v147, v230
	v_ashrrev_i32_e32 v191, 31, v190
	s_cmp_lt_u32 s50, 42
	v_lshlrev_b32_e32 v201, 2, v192
	v_lshlrev_b64 v[128:129], 12, v[190:191]
	v_mul_f32_e32 v146, 0xbfb8aa3b, v56
	v_mul_f32_e32 v145, 0xbfb8aa3b, v57
	v_mul_f32_e32 v144, 0xbfb8aa3b, v58
	v_mul_f32_e32 v141, 0xbfb8aa3b, v59
	v_mul_f32_e32 v140, 0xbfb8aa3b, v48
	v_mul_f32_e32 v139, 0xbfb8aa3b, v49
	v_mul_f32_e32 v138, 0xbfb8aa3b, v50
	v_mul_f32_e32 v137, 0xbfb8aa3b, v51
	v_mul_f32_e32 v136, 0xbfb8aa3b, v40
	v_mul_f32_e32 v135, 0xbfb8aa3b, v41
	v_mul_f32_e32 v134, 0xbfb8aa3b, v42
	v_mul_f32_e32 v132, 0xbfb8aa3b, v43
	s_cbranch_scc1 .LBB0_124
	v_mul_f32_e32 v130, 0xbfb8aa3b, v124
	v_mul_f32_e32 v131, 0xbfb8aa3b, v125
	v_mul_f32_e32 v206, 0xbfb8aa3b, v126
	v_mul_f32_e32 v207, 0xbfb8aa3b, v127
	v_exp_f32_e32 v130, v130
	v_exp_f32_e32 v131, v131
	v_exp_f32_e32 v206, v206
	v_exp_f32_e32 v207, v207
	v_add_f32_e32 v130, 1.0, v130
	v_add_f32_e32 v131, 1.0, v131
	v_add_f32_e32 v206, 1.0, v206
	v_add_f32_e32 v207, 1.0, v207
	v_rcp_f32_e32 v130, v130
	v_rcp_f32_e32 v131, v131
	v_rcp_f32_e32 v206, v206
	v_rcp_f32_e32 v207, v207
	s_lshl_b32 s4, s50, 8
	v_cvt_pk_bf16_f32 v130, v130, v131
	s_add_i32 s4, s28, s4
	v_cvt_pk_bf16_f32 v131, v206, v207
	ds_bpermute_b32 v206, v226, v130
	ds_bpermute_b32 v207, v226, v131
	v_or_b32_e32 v180, s4, v201
	v_lshl_add_u64 v[130:131], s[40:41], 0, v[128:129]
	v_lshlrev_b64 v[208:209], 1, v[180:181]
	v_lshl_add_u64 v[130:131], v[130:131], 0, v[208:209]
	s_waitcnt lgkmcnt(0)
	global_store_dwordx2 v[130:131], v[206:207], off
	v_mul_f32_e32 v180, 0xbfb8aa3b, v116
	v_mul_f32_e32 v206, 0xbfb8aa3b, v117
	v_mul_f32_e32 v207, 0xbfb8aa3b, v118
	v_mul_f32_e32 v208, 0xbfb8aa3b, v119
	v_exp_f32_e32 v180, v180
	v_exp_f32_e32 v206, v206
	v_exp_f32_e32 v207, v207
	v_exp_f32_e32 v208, v208
	v_add_f32_e32 v180, 1.0, v180
	v_add_f32_e32 v206, 1.0, v206
	v_add_f32_e32 v207, 1.0, v207
	v_add_f32_e32 v208, 1.0, v208
	v_rcp_f32_e32 v180, v180
	v_rcp_f32_e32 v206, v206
	v_rcp_f32_e32 v207, v207
	v_rcp_f32_e32 v208, v208
	s_mov_b64 s[4:5], 0x10000
	v_cvt_pk_bf16_f32 v180, v180, v206
	ds_bpermute_b32 v206, v226, v180
	v_cvt_pk_bf16_f32 v207, v207, v208
	ds_bpermute_b32 v207, v226, v207
	v_add_f32_e32 v180, 1.0, v205
	v_add_f32_e32 v208, 1.0, v202
	v_rcp_f32_e32 v180, v180
	v_rcp_f32_e32 v208, v208
	s_waitcnt lgkmcnt(0)
	global_store_dwordx2 v[130:131], v[206:207], off offset:32
	v_add_f32_e32 v206, 1.0, v204
	v_add_f32_e32 v207, 1.0, v203
	v_rcp_f32_e32 v206, v206
	v_rcp_f32_e32 v207, v207
	v_mul_f32_e32 v227, 0xbfb8aa3b, v103
	v_exp_f32_e32 v227, v227
	v_cvt_pk_bf16_f32 v180, v180, v206
	v_cvt_pk_bf16_f32 v207, v207, v208
	ds_bpermute_b32 v206, v226, v180
	ds_bpermute_b32 v207, v226, v207
	v_add_f32_e32 v180, 1.0, v200
	v_add_f32_e32 v208, 1.0, v196
	v_rcp_f32_e32 v180, v180
	v_rcp_f32_e32 v208, v208
	s_waitcnt lgkmcnt(0)
	global_store_dwordx2 v[130:131], v[206:207], off offset:256
	v_add_f32_e32 v206, 1.0, v199
	v_add_f32_e32 v207, 1.0, v197
	v_rcp_f32_e32 v206, v206
	v_rcp_f32_e32 v207, v207
	v_add_f32_e32 v227, 1.0, v227
	v_rcp_f32_e32 v227, v227
	v_cvt_pk_bf16_f32 v180, v180, v206
	v_cvt_pk_bf16_f32 v207, v207, v208
	ds_bpermute_b32 v206, v226, v180
	ds_bpermute_b32 v207, v226, v207
	v_mul_f32_e32 v180, 0xbfb8aa3b, v108
	v_mul_f32_e32 v208, 0xbfb8aa3b, v111
	v_exp_f32_e32 v180, v180
	v_exp_f32_e32 v208, v208
	s_waitcnt lgkmcnt(0)
	global_store_dwordx2 v[130:131], v[206:207], off offset:288
	v_mul_f32_e32 v206, 0xbfb8aa3b, v109
	v_mul_f32_e32 v207, 0xbfb8aa3b, v110
	v_exp_f32_e32 v206, v206
	v_exp_f32_e32 v207, v207
	v_add_f32_e32 v180, 1.0, v180
	v_add_f32_e32 v208, 1.0, v208
	v_add_f32_e32 v206, 1.0, v206
	v_add_f32_e32 v207, 1.0, v207
	v_rcp_f32_e32 v180, v180
	v_rcp_f32_e32 v206, v206
	v_rcp_f32_e32 v207, v207
	v_rcp_f32_e32 v208, v208
	v_cvt_pk_bf16_f32 v180, v180, v206
	ds_bpermute_b32 v206, v226, v180
	v_cvt_pk_bf16_f32 v207, v207, v208
	ds_bpermute_b32 v207, v226, v207
	v_lshl_add_u64 v[208:209], v[130:131], 0, s[4:5]
	s_mov_b32 s4, 0x10000
	v_add_co_u32_e32 v228, vcc, s4, v130
	v_mul_f32_e32 v180, 0xbfb8aa3b, v100
	s_nop 0
	v_addc_co_u32_e32 v229, vcc, 0, v131, vcc
	s_waitcnt lgkmcnt(0)
	global_store_dwordx2 v[228:229], v[206:207], off
	v_mul_f32_e32 v206, 0xbfb8aa3b, v101
	v_mul_f32_e32 v207, 0xbfb8aa3b, v102
	v_exp_f32_e32 v180, v180
	v_exp_f32_e32 v206, v206
	v_exp_f32_e32 v207, v207
	s_mov_b64 s[4:5], 0x20000
	v_add_f32_e32 v180, 1.0, v180
	v_add_f32_e32 v206, 1.0, v206
	v_add_f32_e32 v207, 1.0, v207
	v_rcp_f32_e32 v180, v180
	v_rcp_f32_e32 v206, v206
	v_rcp_f32_e32 v207, v207
	v_cvt_pk_bf16_f32 v180, v180, v206
	v_cvt_pk_bf16_f32 v207, v207, v227
	ds_bpermute_b32 v206, v226, v180
	ds_bpermute_b32 v207, v226, v207
	v_add_f32_e32 v180, 1.0, v195
	v_add_f32_e32 v227, 1.0, v167
	v_rcp_f32_e32 v180, v180
	v_rcp_f32_e32 v227, v227
	s_waitcnt lgkmcnt(0)
	global_store_dwordx2 v[208:209], v[206:207], off offset:32
	v_add_f32_e32 v206, 1.0, v194
	v_add_f32_e32 v207, 1.0, v193
	v_rcp_f32_e32 v206, v206
	v_rcp_f32_e32 v207, v207
	v_cvt_pk_bf16_f32 v180, v180, v206
	v_cvt_pk_bf16_f32 v207, v207, v227
	ds_bpermute_b32 v206, v226, v180
	ds_bpermute_b32 v207, v226, v207
	v_add_f32_e32 v180, 1.0, v166
	v_add_f32_e32 v227, 1.0, v163
	v_rcp_f32_e32 v180, v180
	v_rcp_f32_e32 v227, v227
	s_waitcnt lgkmcnt(0)
	global_store_dwordx2 v[208:209], v[206:207], off offset:256
	v_add_f32_e32 v206, 1.0, v165
	v_add_f32_e32 v207, 1.0, v164
	v_rcp_f32_e32 v206, v206
	v_rcp_f32_e32 v207, v207
	v_cvt_pk_bf16_f32 v180, v180, v206
	v_cvt_pk_bf16_f32 v207, v207, v227
	ds_bpermute_b32 v206, v226, v180
	ds_bpermute_b32 v207, v226, v207
	v_mul_f32_e32 v180, 0xbfb8aa3b, v92
	v_exp_f32_e32 v180, v180
	v_mul_f32_e32 v227, 0xbfb8aa3b, v87
	v_exp_f32_e32 v227, v227
	s_waitcnt lgkmcnt(0)
	global_store_dwordx2 v[208:209], v[206:207], off offset:288
	v_mul_f32_e32 v206, 0xbfb8aa3b, v93
	v_mul_f32_e32 v207, 0xbfb8aa3b, v94
	v_mul_f32_e32 v208, 0xbfb8aa3b, v95
	v_exp_f32_e32 v206, v206
	v_exp_f32_e32 v207, v207
	v_exp_f32_e32 v208, v208
	v_add_f32_e32 v180, 1.0, v180
	v_add_f32_e32 v206, 1.0, v206
	v_add_f32_e32 v207, 1.0, v207
	v_add_f32_e32 v208, 1.0, v208
	v_rcp_f32_e32 v180, v180
	v_rcp_f32_e32 v206, v206
	v_rcp_f32_e32 v207, v207
	v_rcp_f32_e32 v208, v208
	v_add_f32_e32 v227, 1.0, v227
	v_cvt_pk_bf16_f32 v180, v180, v206
	ds_bpermute_b32 v206, v226, v180
	v_cvt_pk_bf16_f32 v207, v207, v208
	ds_bpermute_b32 v207, v226, v207
	v_lshl_add_u64 v[208:209], v[130:131], 0, s[4:5]
	s_mov_b32 s4, 0x20000
	v_add_co_u32_e32 v228, vcc, s4, v130
	v_mul_f32_e32 v180, 0xbfb8aa3b, v84
	s_nop 0
	v_addc_co_u32_e32 v229, vcc, 0, v131, vcc
	s_waitcnt lgkmcnt(0)
	global_store_dwordx2 v[228:229], v[206:207], off
	v_mul_f32_e32 v206, 0xbfb8aa3b, v85
	v_mul_f32_e32 v207, 0xbfb8aa3b, v86
	v_exp_f32_e32 v180, v180
	v_exp_f32_e32 v206, v206
	v_exp_f32_e32 v207, v207
	v_rcp_f32_e32 v227, v227
	v_add_f32_e32 v180, 1.0, v180
	v_add_f32_e32 v206, 1.0, v206
	v_add_f32_e32 v207, 1.0, v207
	v_rcp_f32_e32 v180, v180
	v_rcp_f32_e32 v206, v206
	v_rcp_f32_e32 v207, v207
	s_mov_b64 s[4:5], 0x30000
	v_cvt_pk_bf16_f32 v180, v180, v206
	v_cvt_pk_bf16_f32 v207, v207, v227
	ds_bpermute_b32 v206, v226, v180
	ds_bpermute_b32 v207, v226, v207
	v_add_f32_e32 v180, 1.0, v162
	v_add_f32_e32 v227, 1.0, v159
	v_rcp_f32_e32 v180, v180
	v_rcp_f32_e32 v227, v227
	s_waitcnt lgkmcnt(0)
	global_store_dwordx2 v[208:209], v[206:207], off offset:32
	v_add_f32_e32 v206, 1.0, v161
	v_add_f32_e32 v207, 1.0, v160
	v_rcp_f32_e32 v206, v206
	v_rcp_f32_e32 v207, v207
	v_cvt_pk_bf16_f32 v180, v180, v206
	v_cvt_pk_bf16_f32 v207, v207, v227
	ds_bpermute_b32 v206, v226, v180
	ds_bpermute_b32 v207, v226, v207
	v_add_f32_e32 v180, 1.0, v158
	v_add_f32_e32 v227, 1.0, v155
	v_rcp_f32_e32 v180, v180
	v_rcp_f32_e32 v227, v227
	s_waitcnt lgkmcnt(0)
	global_store_dwordx2 v[208:209], v[206:207], off offset:256
	v_add_f32_e32 v206, 1.0, v157
	v_add_f32_e32 v207, 1.0, v156
	v_rcp_f32_e32 v206, v206
	v_rcp_f32_e32 v207, v207
	v_cvt_pk_bf16_f32 v180, v180, v206
	v_cvt_pk_bf16_f32 v207, v207, v227
	ds_bpermute_b32 v206, v226, v180
	ds_bpermute_b32 v207, v226, v207
	v_mul_f32_e32 v180, 0xbfb8aa3b, v76
	v_exp_f32_e32 v180, v180
	v_mul_f32_e32 v227, 0xbfb8aa3b, v71
	v_exp_f32_e32 v227, v227
	s_waitcnt lgkmcnt(0)
	global_store_dwordx2 v[208:209], v[206:207], off offset:288
	v_mul_f32_e32 v206, 0xbfb8aa3b, v77
	v_mul_f32_e32 v207, 0xbfb8aa3b, v78
	v_mul_f32_e32 v208, 0xbfb8aa3b, v79
	v_exp_f32_e32 v206, v206
	v_exp_f32_e32 v207, v207
	v_exp_f32_e32 v208, v208
	v_add_f32_e32 v180, 1.0, v180
	v_add_f32_e32 v206, 1.0, v206
	v_add_f32_e32 v207, 1.0, v207
	v_add_f32_e32 v208, 1.0, v208
	v_rcp_f32_e32 v180, v180
	v_rcp_f32_e32 v206, v206
	v_rcp_f32_e32 v207, v207
	v_rcp_f32_e32 v208, v208
	v_add_f32_e32 v227, 1.0, v227
	v_cvt_pk_bf16_f32 v180, v180, v206
	ds_bpermute_b32 v206, v226, v180
	v_cvt_pk_bf16_f32 v207, v207, v208
	ds_bpermute_b32 v207, v226, v207
	v_lshl_add_u64 v[208:209], v[130:131], 0, s[4:5]
	s_mov_b32 s4, 0x30000
	v_add_co_u32_e32 v228, vcc, s4, v130
	v_mul_f32_e32 v180, 0xbfb8aa3b, v68
	s_nop 0
	v_addc_co_u32_e32 v229, vcc, 0, v131, vcc
	s_waitcnt lgkmcnt(0)
	global_store_dwordx2 v[228:229], v[206:207], off
	v_mul_f32_e32 v206, 0xbfb8aa3b, v69
	v_mul_f32_e32 v207, 0xbfb8aa3b, v70
	v_exp_f32_e32 v180, v180
	v_exp_f32_e32 v206, v206
	v_exp_f32_e32 v207, v207
	v_rcp_f32_e32 v227, v227
	v_add_f32_e32 v180, 1.0, v180
	v_add_f32_e32 v206, 1.0, v206
	v_add_f32_e32 v207, 1.0, v207
	v_rcp_f32_e32 v180, v180
	v_rcp_f32_e32 v206, v206
	v_rcp_f32_e32 v207, v207
	s_mov_b64 s[4:5], 0x80000
	v_cvt_pk_bf16_f32 v180, v180, v206
	v_cvt_pk_bf16_f32 v207, v207, v227
	ds_bpermute_b32 v206, v226, v180
	ds_bpermute_b32 v207, v226, v207
	v_add_f32_e32 v180, 1.0, v154
	v_add_f32_e32 v227, 1.0, v151
	v_rcp_f32_e32 v180, v180
	v_rcp_f32_e32 v227, v227
	s_waitcnt lgkmcnt(0)
	global_store_dwordx2 v[208:209], v[206:207], off offset:32
	v_add_f32_e32 v206, 1.0, v153
	v_add_f32_e32 v207, 1.0, v152
	v_rcp_f32_e32 v206, v206
	v_rcp_f32_e32 v207, v207
	v_cvt_pk_bf16_f32 v180, v180, v206
	v_cvt_pk_bf16_f32 v207, v207, v227
	ds_bpermute_b32 v206, v226, v180
	ds_bpermute_b32 v207, v226, v207
	v_add_f32_e32 v180, 1.0, v150
	v_add_f32_e32 v227, 1.0, v147
	v_rcp_f32_e32 v180, v180
	v_rcp_f32_e32 v227, v227
	s_waitcnt lgkmcnt(0)
	global_store_dwordx2 v[208:209], v[206:207], off offset:256
	v_add_f32_e32 v206, 1.0, v149
	v_add_f32_e32 v207, 1.0, v148
	v_rcp_f32_e32 v206, v206
	v_rcp_f32_e32 v207, v207
	v_cvt_pk_bf16_f32 v180, v180, v206
	v_cvt_pk_bf16_f32 v207, v207, v227
	ds_bpermute_b32 v206, v226, v180
	ds_bpermute_b32 v207, v226, v207
	v_mul_f32_e32 v180, 0xbfb8aa3b, v60
	v_exp_f32_e32 v180, v180
	v_mul_f32_e32 v227, 0xbfb8aa3b, v55
	v_exp_f32_e32 v227, v227
	s_waitcnt lgkmcnt(0)
	global_store_dwordx2 v[208:209], v[206:207], off offset:288
	v_mul_f32_e32 v206, 0xbfb8aa3b, v61
	v_mul_f32_e32 v207, 0xbfb8aa3b, v62
	v_mul_f32_e32 v208, 0xbfb8aa3b, v63
	v_exp_f32_e32 v206, v206
	v_exp_f32_e32 v207, v207
	v_exp_f32_e32 v208, v208
	v_add_f32_e32 v180, 1.0, v180
	v_add_f32_e32 v206, 1.0, v206
	v_add_f32_e32 v207, 1.0, v207
	v_add_f32_e32 v208, 1.0, v208
	v_rcp_f32_e32 v180, v180
	v_rcp_f32_e32 v206, v206
	v_rcp_f32_e32 v207, v207
	v_rcp_f32_e32 v208, v208
	v_add_f32_e32 v227, 1.0, v227
	v_cvt_pk_bf16_f32 v180, v180, v206
	ds_bpermute_b32 v206, v226, v180
	v_cvt_pk_bf16_f32 v207, v207, v208
	ds_bpermute_b32 v207, v226, v207
	v_lshl_add_u64 v[208:209], v[130:131], 0, s[4:5]
	s_mov_b32 s4, 0x80000
	v_add_co_u32_e32 v228, vcc, s4, v130
	v_mul_f32_e32 v180, 0xbfb8aa3b, v52
	s_nop 0
	v_addc_co_u32_e32 v229, vcc, 0, v131, vcc
	s_waitcnt lgkmcnt(0)
	global_store_dwordx2 v[228:229], v[206:207], off
	v_mul_f32_e32 v206, 0xbfb8aa3b, v53
	v_mul_f32_e32 v207, 0xbfb8aa3b, v54
	v_exp_f32_e32 v180, v180
	v_exp_f32_e32 v206, v206
	v_exp_f32_e32 v207, v207
	v_rcp_f32_e32 v227, v227
	v_add_f32_e32 v180, 1.0, v180
	v_add_f32_e32 v206, 1.0, v206
	v_add_f32_e32 v207, 1.0, v207
	v_rcp_f32_e32 v180, v180
	v_rcp_f32_e32 v206, v206
	v_rcp_f32_e32 v207, v207
	s_mov_b64 s[4:5], 0x90000
	v_cvt_pk_bf16_f32 v180, v180, v206
	v_cvt_pk_bf16_f32 v207, v207, v227
	ds_bpermute_b32 v206, v226, v180
	ds_bpermute_b32 v207, v226, v207
	v_exp_f32_e32 v180, v146
	v_exp_f32_e32 v227, v141
	s_waitcnt lgkmcnt(0)
	global_store_dwordx2 v[208:209], v[206:207], off offset:32
	v_exp_f32_e32 v206, v145
	v_exp_f32_e32 v207, v144
	v_add_f32_e32 v180, 1.0, v180
	v_add_f32_e32 v227, 1.0, v227
	v_add_f32_e32 v206, 1.0, v206
	v_add_f32_e32 v207, 1.0, v207
	v_rcp_f32_e32 v180, v180
	v_rcp_f32_e32 v206, v206
	v_rcp_f32_e32 v207, v207
	v_rcp_f32_e32 v227, v227
	v_cvt_pk_bf16_f32 v180, v180, v206
	ds_bpermute_b32 v206, v226, v180
	v_cvt_pk_bf16_f32 v207, v207, v227
	ds_bpermute_b32 v207, v226, v207
	v_exp_f32_e32 v180, v140
	v_exp_f32_e32 v227, v137
	s_waitcnt lgkmcnt(0)
	global_store_dwordx2 v[208:209], v[206:207], off offset:256
	v_exp_f32_e32 v206, v139
	v_exp_f32_e32 v207, v138
	v_add_f32_e32 v180, 1.0, v180
	v_add_f32_e32 v227, 1.0, v227
	v_add_f32_e32 v206, 1.0, v206
	v_add_f32_e32 v207, 1.0, v207
	v_rcp_f32_e32 v180, v180
	v_rcp_f32_e32 v206, v206
	v_rcp_f32_e32 v207, v207
	v_rcp_f32_e32 v227, v227
	v_cvt_pk_bf16_f32 v180, v180, v206
	ds_bpermute_b32 v206, v226, v180
	v_cvt_pk_bf16_f32 v207, v207, v227
	ds_bpermute_b32 v207, v226, v207
	v_mul_f32_e32 v180, 0xbfb8aa3b, v44
	v_exp_f32_e32 v180, v180
	v_mul_f32_e32 v227, 0xbfb8aa3b, v39
	v_exp_f32_e32 v227, v227
	s_waitcnt lgkmcnt(0)
	global_store_dwordx2 v[208:209], v[206:207], off offset:288
	v_mul_f32_e32 v206, 0xbfb8aa3b, v45
	v_mul_f32_e32 v207, 0xbfb8aa3b, v46
	v_mul_f32_e32 v208, 0xbfb8aa3b, v47
	v_exp_f32_e32 v206, v206
	v_exp_f32_e32 v207, v207
	v_exp_f32_e32 v208, v208
	v_add_f32_e32 v180, 1.0, v180
	v_add_f32_e32 v206, 1.0, v206
	v_add_f32_e32 v207, 1.0, v207
	v_add_f32_e32 v208, 1.0, v208
	v_rcp_f32_e32 v180, v180
	v_rcp_f32_e32 v206, v206
	v_rcp_f32_e32 v207, v207
	v_rcp_f32_e32 v208, v208
	v_add_f32_e32 v227, 1.0, v227
	v_cvt_pk_bf16_f32 v180, v180, v206
	ds_bpermute_b32 v206, v226, v180
	v_cvt_pk_bf16_f32 v207, v207, v208
	ds_bpermute_b32 v207, v226, v207
	v_lshl_add_u64 v[208:209], v[130:131], 0, s[4:5]
	s_mov_b32 s4, 0x90000
	v_add_co_u32_e32 v228, vcc, s4, v130
	v_mul_f32_e32 v180, 0xbfb8aa3b, v36
	s_nop 0
	v_addc_co_u32_e32 v229, vcc, 0, v131, vcc
	s_waitcnt lgkmcnt(0)
	global_store_dwordx2 v[228:229], v[206:207], off
	v_mul_f32_e32 v206, 0xbfb8aa3b, v37
	v_mul_f32_e32 v207, 0xbfb8aa3b, v38
	v_exp_f32_e32 v180, v180
	v_exp_f32_e32 v206, v206
	v_exp_f32_e32 v207, v207
	v_rcp_f32_e32 v227, v227
	v_add_f32_e32 v180, 1.0, v180
	v_add_f32_e32 v206, 1.0, v206
	v_add_f32_e32 v207, 1.0, v207
	v_rcp_f32_e32 v180, v180
	v_rcp_f32_e32 v206, v206
	v_rcp_f32_e32 v207, v207
	s_mov_b64 s[4:5], 0xa0000
	v_cvt_pk_bf16_f32 v180, v180, v206
	v_cvt_pk_bf16_f32 v207, v207, v227
	ds_bpermute_b32 v206, v226, v180
	ds_bpermute_b32 v207, v226, v207
	v_exp_f32_e32 v180, v136
	v_exp_f32_e32 v227, v132
	s_waitcnt lgkmcnt(0)
	global_store_dwordx2 v[208:209], v[206:207], off offset:32
	v_exp_f32_e32 v206, v135
	v_exp_f32_e32 v207, v134
	v_add_f32_e32 v180, 1.0, v180
	v_add_f32_e32 v227, 1.0, v227
	v_add_f32_e32 v206, 1.0, v206
	v_add_f32_e32 v207, 1.0, v207
	v_rcp_f32_e32 v180, v180
	v_rcp_f32_e32 v206, v206
	v_rcp_f32_e32 v207, v207
	v_rcp_f32_e32 v227, v227
	v_cvt_pk_bf16_f32 v180, v180, v206
	ds_bpermute_b32 v206, v226, v180
	v_cvt_pk_bf16_f32 v207, v207, v227
	ds_bpermute_b32 v207, v226, v207
	v_mul_f32_e32 v180, 0xbfb8aa3b, v32
	v_mul_f32_e32 v227, 0xbfb8aa3b, v35
	v_exp_f32_e32 v180, v180
	v_exp_f32_e32 v227, v227
	s_waitcnt lgkmcnt(0)
	global_store_dwordx2 v[208:209], v[206:207], off offset:256
	v_mul_f32_e32 v206, 0xbfb8aa3b, v33
	v_mul_f32_e32 v207, 0xbfb8aa3b, v34
	v_exp_f32_e32 v206, v206
	v_exp_f32_e32 v207, v207
	v_add_f32_e32 v180, 1.0, v180
	v_add_f32_e32 v227, 1.0, v227
	v_add_f32_e32 v206, 1.0, v206
	v_add_f32_e32 v207, 1.0, v207
	v_rcp_f32_e32 v180, v180
	v_rcp_f32_e32 v206, v206
	v_rcp_f32_e32 v207, v207
	v_rcp_f32_e32 v227, v227
	v_cvt_pk_bf16_f32 v180, v180, v206
	ds_bpermute_b32 v206, v226, v180
	v_cvt_pk_bf16_f32 v207, v207, v227
	ds_bpermute_b32 v207, v226, v207
	v_mul_f32_e32 v180, 0xbfb8aa3b, v28
	v_exp_f32_e32 v180, v180
	v_mul_f32_e32 v227, 0xbfb8aa3b, v23
	v_exp_f32_e32 v227, v227
	s_waitcnt lgkmcnt(0)
	global_store_dwordx2 v[208:209], v[206:207], off offset:288
	v_mul_f32_e32 v206, 0xbfb8aa3b, v29
	v_mul_f32_e32 v207, 0xbfb8aa3b, v30
	v_mul_f32_e32 v208, 0xbfb8aa3b, v31
	v_exp_f32_e32 v206, v206
	v_exp_f32_e32 v207, v207
	v_exp_f32_e32 v208, v208
	v_add_f32_e32 v180, 1.0, v180
	v_add_f32_e32 v206, 1.0, v206
	v_add_f32_e32 v207, 1.0, v207
	v_add_f32_e32 v208, 1.0, v208
	v_rcp_f32_e32 v180, v180
	v_rcp_f32_e32 v206, v206
	v_rcp_f32_e32 v207, v207
	v_rcp_f32_e32 v208, v208
	v_add_f32_e32 v227, 1.0, v227
	v_cvt_pk_bf16_f32 v180, v180, v206
	ds_bpermute_b32 v206, v226, v180
	v_cvt_pk_bf16_f32 v207, v207, v208
	ds_bpermute_b32 v207, v226, v207
	v_lshl_add_u64 v[208:209], v[130:131], 0, s[4:5]
	s_mov_b32 s4, 0xa0000
	v_add_co_u32_e32 v228, vcc, s4, v130
	v_mul_f32_e32 v180, 0xbfb8aa3b, v20
	s_nop 0
	v_addc_co_u32_e32 v229, vcc, 0, v131, vcc
	s_waitcnt lgkmcnt(0)
	global_store_dwordx2 v[228:229], v[206:207], off
	v_mul_f32_e32 v206, 0xbfb8aa3b, v21
	v_mul_f32_e32 v207, 0xbfb8aa3b, v22
	v_exp_f32_e32 v180, v180
	v_exp_f32_e32 v206, v206
	v_exp_f32_e32 v207, v207
	v_rcp_f32_e32 v227, v227
	v_add_f32_e32 v180, 1.0, v180
	v_add_f32_e32 v206, 1.0, v206
	v_add_f32_e32 v207, 1.0, v207
	v_rcp_f32_e32 v180, v180
	v_rcp_f32_e32 v206, v206
	v_rcp_f32_e32 v207, v207
	s_mov_b64 s[4:5], 0xb0000
	v_cvt_pk_bf16_f32 v180, v180, v206
	v_cvt_pk_bf16_f32 v207, v207, v227
	ds_bpermute_b32 v206, v226, v180
	ds_bpermute_b32 v207, v226, v207
	v_mul_f32_e32 v180, 0xbfb8aa3b, v24
	v_mul_f32_e32 v227, 0xbfb8aa3b, v27
	v_exp_f32_e32 v180, v180
	v_exp_f32_e32 v227, v227
	s_waitcnt lgkmcnt(0)
	global_store_dwordx2 v[208:209], v[206:207], off offset:32
	v_mul_f32_e32 v206, 0xbfb8aa3b, v25
	v_mul_f32_e32 v207, 0xbfb8aa3b, v26
	v_exp_f32_e32 v206, v206
	v_exp_f32_e32 v207, v207
	v_add_f32_e32 v180, 1.0, v180
	v_add_f32_e32 v227, 1.0, v227
	v_add_f32_e32 v206, 1.0, v206
	v_add_f32_e32 v207, 1.0, v207
	v_rcp_f32_e32 v180, v180
	v_rcp_f32_e32 v206, v206
	v_rcp_f32_e32 v207, v207
	v_rcp_f32_e32 v227, v227
	v_cvt_pk_bf16_f32 v180, v180, v206
	ds_bpermute_b32 v206, v226, v180
	v_cvt_pk_bf16_f32 v207, v207, v227
	ds_bpermute_b32 v207, v226, v207
	v_mul_f32_e32 v180, 0xbfb8aa3b, v16
	v_mul_f32_e32 v227, 0xbfb8aa3b, v19
	v_exp_f32_e32 v180, v180
	v_exp_f32_e32 v227, v227
	s_waitcnt lgkmcnt(0)
	global_store_dwordx2 v[208:209], v[206:207], off offset:256
	v_mul_f32_e32 v206, 0xbfb8aa3b, v17
	v_mul_f32_e32 v207, 0xbfb8aa3b, v18
	v_exp_f32_e32 v206, v206
	v_exp_f32_e32 v207, v207
	v_add_f32_e32 v180, 1.0, v180
	v_add_f32_e32 v227, 1.0, v227
	v_add_f32_e32 v206, 1.0, v206
	v_add_f32_e32 v207, 1.0, v207
	v_rcp_f32_e32 v180, v180
	v_rcp_f32_e32 v206, v206
	v_rcp_f32_e32 v207, v207
	v_rcp_f32_e32 v227, v227
	v_cvt_pk_bf16_f32 v180, v180, v206
	ds_bpermute_b32 v206, v226, v180
	v_cvt_pk_bf16_f32 v207, v207, v227
	ds_bpermute_b32 v207, v226, v207
	v_mul_f32_e32 v180, 0xbfb8aa3b, v12
	v_exp_f32_e32 v180, v180
	s_waitcnt lgkmcnt(0)
	global_store_dwordx2 v[208:209], v[206:207], off offset:288
	v_mul_f32_e32 v206, 0xbfb8aa3b, v13
	v_mul_f32_e32 v207, 0xbfb8aa3b, v14
	v_mul_f32_e32 v208, 0xbfb8aa3b, v15
	v_exp_f32_e32 v206, v206
	v_exp_f32_e32 v207, v207
	v_exp_f32_e32 v208, v208
	v_add_f32_e32 v180, 1.0, v180
	v_add_f32_e32 v206, 1.0, v206
	v_add_f32_e32 v207, 1.0, v207
	v_add_f32_e32 v208, 1.0, v208
	v_rcp_f32_e32 v180, v180
	v_rcp_f32_e32 v206, v206
	v_rcp_f32_e32 v207, v207
	v_rcp_f32_e32 v208, v208
	v_cvt_pk_bf16_f32 v180, v180, v206
	ds_bpermute_b32 v206, v226, v180
	v_cvt_pk_bf16_f32 v207, v207, v208
	ds_bpermute_b32 v207, v226, v207
	v_lshl_add_u64 v[208:209], v[130:131], 0, s[4:5]
	s_mov_b32 s4, 0xb0000
	v_add_co_u32_e32 v130, vcc, s4, v130
	v_mul_f32_e32 v180, 0xbfb8aa3b, v6
	s_nop 0
	v_addc_co_u32_e32 v131, vcc, 0, v131, vcc
	s_waitcnt lgkmcnt(0)
	global_store_dwordx2 v[130:131], v[206:207], off
	v_mul_f32_e32 v130, 0xbfb8aa3b, v4
	v_mul_f32_e32 v131, 0xbfb8aa3b, v5
	v_mul_f32_e32 v206, 0xbfb8aa3b, v7
	v_exp_f32_e32 v130, v130
	v_exp_f32_e32 v131, v131
	v_exp_f32_e32 v180, v180
	v_exp_f32_e32 v206, v206
	v_add_f32_e32 v130, 1.0, v130
	v_add_f32_e32 v131, 1.0, v131
	v_add_f32_e32 v180, 1.0, v180
	v_add_f32_e32 v206, 1.0, v206
	v_rcp_f32_e32 v130, v130
	v_rcp_f32_e32 v131, v131
	v_rcp_f32_e32 v180, v180
	v_rcp_f32_e32 v206, v206
	s_mov_b64 s[4:5], 0
	v_cvt_pk_bf16_f32 v130, v130, v131
	ds_bpermute_b32 v130, v226, v130
	v_cvt_pk_bf16_f32 v131, v180, v206
	ds_bpermute_b32 v131, v226, v131
	v_mul_f32_e32 v180, 0xbfb8aa3b, v10
	v_mul_f32_e32 v206, 0xbfb8aa3b, v11
	v_exp_f32_e32 v180, v180
	v_exp_f32_e32 v206, v206
	s_waitcnt lgkmcnt(0)
	global_store_dwordx2 v[208:209], v[130:131], off offset:32
	v_mul_f32_e32 v130, 0xbfb8aa3b, v8
	v_mul_f32_e32 v131, 0xbfb8aa3b, v9
	v_exp_f32_e32 v130, v130
	v_exp_f32_e32 v131, v131
	v_add_f32_e32 v180, 1.0, v180
	v_add_f32_e32 v206, 1.0, v206
	v_add_f32_e32 v130, 1.0, v130
	v_add_f32_e32 v131, 1.0, v131
	v_rcp_f32_e32 v130, v130
	v_rcp_f32_e32 v131, v131
	v_rcp_f32_e32 v180, v180
	v_rcp_f32_e32 v206, v206
	v_cvt_pk_bf16_f32 v130, v130, v131
	ds_bpermute_b32 v130, v226, v130
	v_cvt_pk_bf16_f32 v131, v180, v206
	ds_bpermute_b32 v131, v226, v131
	v_mul_f32_e32 v180, 0xbfb8aa3b, v2
	v_mul_f32_e32 v206, 0xbfb8aa3b, v3
	v_exp_f32_e32 v180, v180
	v_exp_f32_e32 v206, v206
	s_waitcnt lgkmcnt(0)
	global_store_dwordx2 v[208:209], v[130:131], off offset:256
	v_mul_f32_e32 v130, 0xbfb8aa3b, v0
	v_mul_f32_e32 v131, 0xbfb8aa3b, v1
	v_exp_f32_e32 v130, v130
	v_exp_f32_e32 v131, v131
	v_add_f32_e32 v180, 1.0, v180
	v_add_f32_e32 v206, 1.0, v206
	v_add_f32_e32 v130, 1.0, v130
	v_add_f32_e32 v131, 1.0, v131
	v_rcp_f32_e32 v130, v130
	v_rcp_f32_e32 v131, v131
	v_rcp_f32_e32 v180, v180
	v_rcp_f32_e32 v206, v206
	v_cvt_pk_bf16_f32 v130, v130, v131
	ds_bpermute_b32 v130, v226, v130
	v_cvt_pk_bf16_f32 v131, v180, v206
	ds_bpermute_b32 v131, v226, v131
	s_waitcnt lgkmcnt(0)
	global_store_dwordx2 v[208:209], v[130:131], off offset:288

.LBB0_1023:
	s_ashr_i32 s21, s20, 31
	s_lshl_b64 s[26:27], s[20:21], 20
	v_readlane_b32 s2, v254, 52
	v_readlane_b32 s3, v254, 53
	s_add_u32 s21, s2, s26
	s_addc_u32 s23, s3, s27
	s_ashr_i32 s25, s24, 31
	s_lshl_b64 s[28:29], s[24:25], 7
	s_add_u32 s26, s21, s28
	s_addc_u32 s27, s23, s29
	s_and_b64 s[58:59], s[38:39], exec
	s_cselect_b32 s21, s27, s5
	s_cselect_b32 s25, s26, s4
	s_ashr_i32 s23, s22, 31
	s_lshl_b64 s[58:59], s[22:23], 20
	s_add_u32 s23, s40, s58
	s_addc_u32 s58, s41, s59
	s_add_u32 s28, s23, s28
	s_addc_u32 s29, s58, s29
	s_and_b64 s[38:39], s[38:39], exec
	s_cselect_b32 s23, s29, s37
	s_cselect_b32 s58, s28, s36
	s_add_i32 s59, s17, -2
	s_add_u32 s4, s4, 0x80080
	s_addc_u32 s5, s5, 0
	s_add_u32 s60, s36, 0x100
	v_mov_b32_e32 v0, 0
	s_addc_u32 s61, s37, 0
	s_mov_b32 s36, 0
	v_mov_b32_e32 v1, v0
	v_mov_b32_e32 v2, v0
	v_mov_b32_e32 v3, v0
	v_mov_b32_e32 v4, v0
	v_mov_b32_e32 v5, v0
	v_mov_b32_e32 v6, v0
	v_mov_b32_e32 v7, v0
	v_mov_b32_e32 v12, v0
	v_mov_b32_e32 v13, v0
	v_mov_b32_e32 v14, v0
	v_mov_b32_e32 v15, v0
	v_mov_b32_e32 v16, v0
	v_mov_b32_e32 v17, v0
	v_mov_b32_e32 v18, v0
	v_mov_b32_e32 v19, v0
	v_mov_b32_e32 v28, v0
	v_mov_b32_e32 v29, v0
	v_mov_b32_e32 v30, v0
	v_mov_b32_e32 v31, v0
	v_mov_b32_e32 v32, v0
	v_mov_b32_e32 v33, v0
	v_mov_b32_e32 v34, v0
	v_mov_b32_e32 v35, v0
	v_mov_b32_e32 v44, v0
	v_mov_b32_e32 v45, v0
	v_mov_b32_e32 v46, v0
	v_mov_b32_e32 v47, v0
	v_mov_b32_e32 v48, v0
	v_mov_b32_e32 v49, v0
	v_mov_b32_e32 v50, v0
	v_mov_b32_e32 v51, v0
	v_mov_b32_e32 v8, v0
	v_mov_b32_e32 v9, v0
	v_mov_b32_e32 v10, v0
	v_mov_b32_e32 v11, v0
	v_mov_b32_e32 v20, v0
	v_mov_b32_e32 v21, v0
	v_mov_b32_e32 v22, v0
	v_mov_b32_e32 v23, v0
	v_mov_b32_e32 v24, v0
	v_mov_b32_e32 v25, v0
	v_mov_b32_e32 v26, v0
	v_mov_b32_e32 v27, v0
	v_mov_b32_e32 v36, v0
	v_mov_b32_e32 v37, v0
	v_mov_b32_e32 v38, v0
	v_mov_b32_e32 v39, v0
	v_mov_b32_e32 v40, v0
	v_mov_b32_e32 v41, v0
	v_mov_b32_e32 v42, v0
	v_mov_b32_e32 v43, v0
	v_mov_b32_e32 v52, v0
	v_mov_b32_e32 v53, v0
	v_mov_b32_e32 v54, v0
	v_mov_b32_e32 v55, v0
	v_mov_b32_e32 v56, v0
	v_mov_b32_e32 v57, v0
	v_mov_b32_e32 v58, v0
	v_mov_b32_e32 v59, v0
	v_mov_b32_e32 v60, v0
	v_mov_b32_e32 v61, v0
	v_mov_b32_e32 v62, v0
	v_mov_b32_e32 v63, v0
	v_mov_b32_e32 v64, v0
	v_mov_b32_e32 v65, v0
	v_mov_b32_e32 v66, v0
	v_mov_b32_e32 v67, v0
	v_mov_b32_e32 v68, v0
	v_mov_b32_e32 v69, v0
	v_mov_b32_e32 v70, v0
	v_mov_b32_e32 v71, v0
	v_mov_b32_e32 v76, v0
	v_mov_b32_e32 v77, v0
	v_mov_b32_e32 v78, v0
	v_mov_b32_e32 v79, v0
	v_mov_b32_e32 v84, v0
	v_mov_b32_e32 v85, v0
	v_mov_b32_e32 v86, v0
	v_mov_b32_e32 v87, v0
	v_mov_b32_e32 v92, v0
	v_mov_b32_e32 v93, v0
	v_mov_b32_e32 v94, v0
	v_mov_b32_e32 v95, v0
	v_mov_b32_e32 v100, v0
	v_mov_b32_e32 v101, v0
	v_mov_b32_e32 v102, v0
	v_mov_b32_e32 v103, v0
	v_mov_b32_e32 v108, v0
	v_mov_b32_e32 v109, v0
	v_mov_b32_e32 v110, v0
	v_mov_b32_e32 v111, v0
	v_mov_b32_e32 v112, v0
	v_mov_b32_e32 v113, v0
	v_mov_b32_e32 v114, v0
	v_mov_b32_e32 v115, v0
	v_mov_b32_e32 v72, v0
	v_mov_b32_e32 v73, v0
	v_mov_b32_e32 v74, v0
	v_mov_b32_e32 v75, v0
	v_mov_b32_e32 v80, v0
	v_mov_b32_e32 v81, v0
	v_mov_b32_e32 v82, v0
	v_mov_b32_e32 v83, v0
	v_mov_b32_e32 v88, v0
	v_mov_b32_e32 v89, v0
	v_mov_b32_e32 v90, v0
	v_mov_b32_e32 v91, v0
	v_mov_b32_e32 v96, v0
	v_mov_b32_e32 v97, v0
	v_mov_b32_e32 v98, v0
	v_mov_b32_e32 v99, v0
	v_mov_b32_e32 v104, v0
	v_mov_b32_e32 v105, v0
	v_mov_b32_e32 v106, v0
	v_mov_b32_e32 v107, v0
	v_mov_b32_e32 v116, v0
	v_mov_b32_e32 v117, v0
	v_mov_b32_e32 v118, v0
	v_mov_b32_e32 v119, v0
	v_mov_b32_e32 v120, v0
	v_mov_b32_e32 v121, v0
	v_mov_b32_e32 v122, v0
	v_mov_b32_e32 v123, v0
	v_mov_b32_e32 v124, v0
	v_mov_b32_e32 v125, v0
	v_mov_b32_e32 v126, v0
	v_mov_b32_e32 v127, v0
	v_readlane_b32 s70, v254, 44
	s_cmp_lt_u32 s70, 4
	s_cbranch_scc1 .Lsp_1
	s_setprio 1
.Lsp_1:
.LBB0_1024:
	s_waitcnt lgkmcnt(0)
	ds_read_b128 v[128:131], v179
	ds_read_b128 v[132:135], v179 offset:1024
	ds_read_b128 v[136:139], v179 offset:2048
	ds_read_b128 v[140:143], v179 offset:3072
	s_add_i32 s62, s36, 2
	s_add_u32 s37, s4, 0xfff80080
	s_addc_u32 s38, s5, -1
	s_cmp_eq_u32 s59, s36
	s_cselect_b32 s36, s58, s60
	s_cselect_b32 s39, s21, s38
	s_cselect_b32 s38, s25, s37
	s_cselect_b32 s37, s23, s61
	v_lshl_add_u64 v[166:167], s[4:5], 0, v[162:163]
	s_add_i32 m0, s31, 0xc000
	ds_read_b128 v[144:147], v190
	ds_read_b128 v[148:151], v190 offset:1024
	ds_read_b128 v[152:155], v190 offset:2048
	ds_read_b128 v[156:159], v190 offset:3072
	ds_read_b128 v[180:183], v190 offset:4096
	ds_read_b128 v[184:187], v190 offset:5120
	ds_read_b128 v[194:197], v190 offset:6144
	ds_read_b128 v[198:201], v190 offset:7168
	global_load_lds_dwordx4 v[166:167], off
	v_lshl_add_u64 v[166:167], s[4:5], 0, v[164:165]
	s_add_i32 m0, s31, 0xe000
	s_nop 0
	global_load_lds_dwordx4 v[166:167], off
	s_waitcnt lgkmcnt(8)
	s_barrier
	s_waitcnt lgkmcnt(0)

	s_waitcnt lgkmcnt(0)
	v_mfma_f32_16x16x32_bf16 v[124:127], v[128:131], v[144:147], v[124:127]
	v_mfma_f32_16x16x32_bf16 v[120:123], v[136:139], v[144:147], v[120:123]
	v_mfma_f32_16x16x32_bf16 v[116:119], v[128:131], v[152:155], v[116:119]
	v_mfma_f32_16x16x32_bf16 v[104:107], v[136:139], v[152:155], v[104:107]
	v_mfma_f32_16x16x32_bf16 v[96:99], v[128:131], v[180:183], v[96:99]
	v_mfma_f32_16x16x32_bf16 v[88:91], v[136:139], v[180:183], v[88:91]
	v_mfma_f32_16x16x32_bf16 v[80:83], v[128:131], v[194:197], v[80:83]
	v_mfma_f32_16x16x32_bf16 v[72:75], v[136:139], v[194:197], v[72:75]
	v_mfma_f32_16x16x32_bf16 v[124:127], v[132:135], v[148:151], v[124:127]
	v_mfma_f32_16x16x32_bf16 v[120:123], v[140:143], v[148:151], v[120:123]
	v_mfma_f32_16x16x32_bf16 v[116:119], v[132:135], v[156:159], v[116:119]
	v_mfma_f32_16x16x32_bf16 v[104:107], v[140:143], v[156:159], v[104:107]
	v_mfma_f32_16x16x32_bf16 v[96:99], v[132:135], v[184:187], v[96:99]
	v_mfma_f32_16x16x32_bf16 v[88:91], v[140:143], v[184:187], v[88:91]
	v_mfma_f32_16x16x32_bf16 v[80:83], v[132:135], v[198:201], v[80:83]
	v_mfma_f32_16x16x32_bf16 v[72:75], v[140:143], v[198:201], v[72:75]

	s_barrier
	s_add_i32 s63, s52, s42
	v_lshl_add_u64 v[166:167], s[36:37], 0, v[172:173]
	s_mov_b32 m0, s63
	ds_read_b128 v[202:205], v191
	ds_read_b128 v[206:209], v191 offset:1024
	ds_read_b128 v[222:225], v191 offset:2048
	ds_read_b128 v[226:229], v191 offset:3072
	global_load_lds_dwordx4 v[166:167], off
	v_lshl_add_u64 v[188:189], s[36:37], 0, v[174:175]
	s_add_i32 m0, s63, 0x2000
	s_nop 0
	global_load_lds_dwordx4 v[188:189], off
	s_barrier
	s_waitcnt lgkmcnt(0)

	s_waitcnt lgkmcnt(0)
	v_mfma_f32_16x16x32_bf16 v[112:115], v[202:205], v[144:147], v[112:115]
	v_mfma_f32_16x16x32_bf16 v[108:111], v[222:225], v[144:147], v[108:111]
	v_mfma_f32_16x16x32_bf16 v[100:103], v[202:205], v[152:155], v[100:103]
	v_mfma_f32_16x16x32_bf16 v[92:95], v[222:225], v[152:155], v[92:95]
	v_mfma_f32_16x16x32_bf16 v[84:87], v[202:205], v[180:183], v[84:87]
	v_mfma_f32_16x16x32_bf16 v[76:79], v[222:225], v[180:183], v[76:79]
	v_mfma_f32_16x16x32_bf16 v[68:71], v[202:205], v[194:197], v[68:71]
	v_mfma_f32_16x16x32_bf16 v[64:67], v[222:225], v[194:197], v[64:67]
	v_mfma_f32_16x16x32_bf16 v[112:115], v[206:209], v[148:151], v[112:115]
	v_mfma_f32_16x16x32_bf16 v[108:111], v[226:229], v[148:151], v[108:111]
	v_mfma_f32_16x16x32_bf16 v[100:103], v[206:209], v[156:159], v[100:103]
	v_mfma_f32_16x16x32_bf16 v[92:95], v[226:229], v[156:159], v[92:95]
	v_mfma_f32_16x16x32_bf16 v[84:87], v[206:209], v[184:187], v[84:87]
	v_mfma_f32_16x16x32_bf16 v[76:79], v[226:229], v[184:187], v[76:79]
	v_mfma_f32_16x16x32_bf16 v[68:71], v[206:209], v[198:201], v[68:71]
	v_mfma_f32_16x16x32_bf16 v[64:67], v[226:229], v[198:201], v[64:67]

	s_mov_b32 m0, s31
	v_lshl_add_u64 v[230:231], s[38:39], 0, v[172:173]
	s_barrier
	ds_read_b128 v[144:147], v190 offset:16384
	ds_read_b128 v[148:151], v190 offset:17408
	ds_read_b128 v[152:155], v190 offset:18432
	ds_read_b128 v[156:159], v190 offset:19456
	ds_read_b128 v[180:183], v190 offset:20480
	ds_read_b128 v[184:187], v190 offset:21504
	ds_read_b128 v[194:197], v190 offset:22528
	ds_read_b128 v[198:201], v190 offset:23552
	global_load_lds_dwordx4 v[230:231], off
	v_lshl_add_u64 v[232:233], s[38:39], 0, v[174:175]
	s_mov_b32 m0, s35
	s_nop 0
	global_load_lds_dwordx4 v[232:233], off
	s_barrier
	s_waitcnt lgkmcnt(0)

	s_waitcnt lgkmcnt(0)
	v_mfma_f32_16x16x32_bf16 v[60:63], v[128:131], v[144:147], v[60:63]
	v_mfma_f32_16x16x32_bf16 v[56:59], v[136:139], v[144:147], v[56:59]
	v_mfma_f32_16x16x32_bf16 v[52:55], v[128:131], v[152:155], v[52:55]
	v_mfma_f32_16x16x32_bf16 v[40:43], v[136:139], v[152:155], v[40:43]
	v_mfma_f32_16x16x32_bf16 v[36:39], v[128:131], v[180:183], v[36:39]
	v_mfma_f32_16x16x32_bf16 v[24:27], v[136:139], v[180:183], v[24:27]
	v_mfma_f32_16x16x32_bf16 v[20:23], v[128:131], v[194:197], v[20:23]
	v_mfma_f32_16x16x32_bf16 v[8:11], v[136:139], v[194:197], v[8:11]
	v_mfma_f32_16x16x32_bf16 v[60:63], v[132:135], v[148:151], v[60:63]
	v_mfma_f32_16x16x32_bf16 v[56:59], v[140:143], v[148:151], v[56:59]
	v_mfma_f32_16x16x32_bf16 v[52:55], v[132:135], v[156:159], v[52:55]
	v_mfma_f32_16x16x32_bf16 v[40:43], v[140:143], v[156:159], v[40:43]
	v_mfma_f32_16x16x32_bf16 v[36:39], v[132:135], v[184:187], v[36:39]
	v_mfma_f32_16x16x32_bf16 v[24:27], v[140:143], v[184:187], v[24:27]
	v_mfma_f32_16x16x32_bf16 v[20:23], v[132:135], v[198:201], v[20:23]
	v_mfma_f32_16x16x32_bf16 v[8:11], v[140:143], v[198:201], v[8:11]

	s_barrier
	s_add_u32 s64, s36, 0x80000
	s_addc_u32 s65, s37, 0
	s_add_i32 s63, s53, s42
	v_lshl_add_u64 v[128:129], s[64:65], 0, v[172:173]
	s_mov_b32 m0, s63
	s_nop 0
	global_load_lds_dwordx4 v[128:129], off
	v_lshl_add_u64 v[128:129], s[64:65], 0, v[174:175]
	s_add_i32 m0, s63, 0x2000
	s_nop 0
	global_load_lds_dwordx4 v[128:129], off
	s_waitcnt vmcnt(6)
	s_barrier

	v_mfma_f32_16x16x32_bf16 v[48:51], v[202:205], v[144:147], v[48:51]
	v_mfma_f32_16x16x32_bf16 v[44:47], v[222:225], v[144:147], v[44:47]
	v_mfma_f32_16x16x32_bf16 v[32:35], v[202:205], v[152:155], v[32:35]
	v_mfma_f32_16x16x32_bf16 v[28:31], v[222:225], v[152:155], v[28:31]
	v_mfma_f32_16x16x32_bf16 v[16:19], v[202:205], v[180:183], v[16:19]
	v_mfma_f32_16x16x32_bf16 v[12:15], v[222:225], v[180:183], v[12:15]
	v_mfma_f32_16x16x32_bf16 v[4:7], v[202:205], v[194:197], v[4:7]
	v_mfma_f32_16x16x32_bf16 v[0:3], v[222:225], v[194:197], v[0:3]
	v_mfma_f32_16x16x32_bf16 v[48:51], v[206:209], v[148:151], v[48:51]
	v_mfma_f32_16x16x32_bf16 v[44:47], v[226:229], v[148:151], v[44:47]
	v_mfma_f32_16x16x32_bf16 v[32:35], v[206:209], v[156:159], v[32:35]
	v_mfma_f32_16x16x32_bf16 v[28:31], v[226:229], v[156:159], v[28:31]
	v_mfma_f32_16x16x32_bf16 v[16:19], v[206:209], v[184:187], v[16:19]
	v_mfma_f32_16x16x32_bf16 v[12:15], v[226:229], v[184:187], v[12:15]
	v_mfma_f32_16x16x32_bf16 v[4:7], v[206:209], v[198:201], v[4:7]
	v_mfma_f32_16x16x32_bf16 v[0:3], v[226:229], v[198:201], v[0:3]

	s_add_i32 s63, 0, 0x18000
	v_add_u32_e32 v140, s63, v177
	s_barrier
	ds_read_b128 v[128:131], v140
	ds_read_b128 v[132:135], v140 offset:1024
	ds_read_b128 v[136:139], v140 offset:2048
	ds_read_b128 v[140:143], v140 offset:3072
	s_add_u32 s38, s38, 0x80000
	s_addc_u32 s39, s39, 0
	s_mov_b32 m0, s43
	v_lshl_add_u64 v[202:203], s[38:39], 0, v[172:173]
	ds_read_b128 v[144:147], v190 offset:32768
	ds_read_b128 v[148:151], v190 offset:33792
	ds_read_b128 v[152:155], v190 offset:34816
	ds_read_b128 v[156:159], v190 offset:35840
	ds_read_b128 v[180:183], v190 offset:36864
	ds_read_b128 v[184:187], v190 offset:37888
	ds_read_b128 v[194:197], v190 offset:38912
	ds_read_b128 v[198:201], v190 offset:39936
	global_load_lds_dwordx4 v[202:203], off
	v_lshl_add_u64 v[202:203], s[38:39], 0, v[174:175]
	s_mov_b32 m0, s44
	s_nop 0
	global_load_lds_dwordx4 v[202:203], off
	s_waitcnt lgkmcnt(8)
	s_barrier
	s_waitcnt lgkmcnt(0)

	s_waitcnt lgkmcnt(0)
	v_mfma_f32_16x16x32_bf16 v[124:127], v[128:131], v[144:147], v[124:127]
	v_mfma_f32_16x16x32_bf16 v[120:123], v[136:139], v[144:147], v[120:123]
	v_mfma_f32_16x16x32_bf16 v[116:119], v[128:131], v[152:155], v[116:119]
	v_mfma_f32_16x16x32_bf16 v[104:107], v[136:139], v[152:155], v[104:107]
	v_mfma_f32_16x16x32_bf16 v[96:99], v[128:131], v[180:183], v[96:99]
	v_mfma_f32_16x16x32_bf16 v[88:91], v[136:139], v[180:183], v[88:91]
	v_mfma_f32_16x16x32_bf16 v[80:83], v[128:131], v[194:197], v[80:83]
	v_mfma_f32_16x16x32_bf16 v[72:75], v[136:139], v[194:197], v[72:75]
	v_mfma_f32_16x16x32_bf16 v[124:127], v[132:135], v[148:151], v[124:127]
	v_mfma_f32_16x16x32_bf16 v[120:123], v[140:143], v[148:151], v[120:123]
	v_mfma_f32_16x16x32_bf16 v[116:119], v[132:135], v[156:159], v[116:119]
	v_mfma_f32_16x16x32_bf16 v[104:107], v[140:143], v[156:159], v[104:107]
	v_mfma_f32_16x16x32_bf16 v[96:99], v[132:135], v[184:187], v[96:99]
	v_mfma_f32_16x16x32_bf16 v[88:91], v[140:143], v[184:187], v[88:91]
	v_mfma_f32_16x16x32_bf16 v[80:83], v[132:135], v[198:201], v[80:83]
	v_mfma_f32_16x16x32_bf16 v[72:75], v[140:143], v[198:201], v[72:75]

	s_barrier
	s_add_i32 s38, 0, 0x1c000
	s_add_i32 s39, s63, s42
	v_add_u32_e32 v160, s38, v177
	v_lshl_add_u64 v[166:167], v[166:167], 0, s[14:15]
	s_mov_b32 m0, s39
	ds_read_b128 v[202:205], v160
	ds_read_b128 v[206:209], v160 offset:1024
	ds_read_b128 v[222:225], v160 offset:2048
	ds_read_b128 v[226:229], v160 offset:3072
	global_load_lds_dwordx4 v[166:167], off
	v_lshl_add_u64 v[166:167], v[188:189], 0, s[14:15]
	s_add_i32 m0, s39, 0x2000
	s_nop 0
	global_load_lds_dwordx4 v[166:167], off
	s_barrier
	s_waitcnt lgkmcnt(0)

	s_waitcnt lgkmcnt(0)
	v_mfma_f32_16x16x32_bf16 v[112:115], v[202:205], v[144:147], v[112:115]
	v_mfma_f32_16x16x32_bf16 v[108:111], v[222:225], v[144:147], v[108:111]
	v_mfma_f32_16x16x32_bf16 v[100:103], v[202:205], v[152:155], v[100:103]
	v_mfma_f32_16x16x32_bf16 v[92:95], v[222:225], v[152:155], v[92:95]
	v_mfma_f32_16x16x32_bf16 v[84:87], v[202:205], v[180:183], v[84:87]
	v_mfma_f32_16x16x32_bf16 v[76:79], v[222:225], v[180:183], v[76:79]
	v_mfma_f32_16x16x32_bf16 v[68:71], v[202:205], v[194:197], v[68:71]
	v_mfma_f32_16x16x32_bf16 v[64:67], v[222:225], v[194:197], v[64:67]
	v_mfma_f32_16x16x32_bf16 v[112:115], v[206:209], v[148:151], v[112:115]
	v_mfma_f32_16x16x32_bf16 v[108:111], v[226:229], v[148:151], v[108:111]
	v_mfma_f32_16x16x32_bf16 v[100:103], v[206:209], v[156:159], v[100:103]
	v_mfma_f32_16x16x32_bf16 v[92:95], v[226:229], v[156:159], v[92:95]
	v_mfma_f32_16x16x32_bf16 v[84:87], v[206:209], v[184:187], v[84:87]
	v_mfma_f32_16x16x32_bf16 v[76:79], v[226:229], v[184:187], v[76:79]
	v_mfma_f32_16x16x32_bf16 v[68:71], v[206:209], v[198:201], v[68:71]
	v_mfma_f32_16x16x32_bf16 v[64:67], v[226:229], v[198:201], v[64:67]

	s_mov_b32 m0, s48
	v_lshl_add_u64 v[166:167], v[230:231], 0, s[14:15]
	s_barrier
	ds_read_b128 v[144:147], v190 offset:49152
	ds_read_b128 v[148:151], v190 offset:50176
	ds_read_b128 v[152:155], v190 offset:51200
	ds_read_b128 v[156:159], v190 offset:52224
	ds_read_b128 v[180:183], v190 offset:53248
	ds_read_b128 v[184:187], v190 offset:54272
	ds_read_b128 v[194:197], v190 offset:55296
	ds_read_b128 v[198:201], v190 offset:56320
	global_load_lds_dwordx4 v[166:167], off
	v_lshl_add_u64 v[166:167], v[232:233], 0, s[14:15]
	s_mov_b32 m0, s49
	s_nop 0
	global_load_lds_dwordx4 v[166:167], off
	s_barrier
	s_waitcnt lgkmcnt(0)

	s_waitcnt lgkmcnt(0)
	v_mfma_f32_16x16x32_bf16 v[60:63], v[128:131], v[144:147], v[60:63]
	v_mfma_f32_16x16x32_bf16 v[56:59], v[136:139], v[144:147], v[56:59]
	v_mfma_f32_16x16x32_bf16 v[52:55], v[128:131], v[152:155], v[52:55]
	v_mfma_f32_16x16x32_bf16 v[40:43], v[136:139], v[152:155], v[40:43]
	v_mfma_f32_16x16x32_bf16 v[36:39], v[128:131], v[180:183], v[36:39]
	v_mfma_f32_16x16x32_bf16 v[24:27], v[136:139], v[180:183], v[24:27]
	v_mfma_f32_16x16x32_bf16 v[20:23], v[128:131], v[194:197], v[20:23]
	v_mfma_f32_16x16x32_bf16 v[8:11], v[136:139], v[194:197], v[8:11]
	v_mfma_f32_16x16x32_bf16 v[60:63], v[132:135], v[148:151], v[60:63]
	v_mfma_f32_16x16x32_bf16 v[56:59], v[140:143], v[148:151], v[56:59]
	v_mfma_f32_16x16x32_bf16 v[52:55], v[132:135], v[156:159], v[52:55]
	v_mfma_f32_16x16x32_bf16 v[40:43], v[140:143], v[156:159], v[40:43]
	v_mfma_f32_16x16x32_bf16 v[36:39], v[132:135], v[184:187], v[36:39]
	v_mfma_f32_16x16x32_bf16 v[24:27], v[140:143], v[184:187], v[24:27]
	v_mfma_f32_16x16x32_bf16 v[20:23], v[132:135], v[198:201], v[20:23]
	v_mfma_f32_16x16x32_bf16 v[8:11], v[140:143], v[198:201], v[8:11]

	s_barrier
	s_add_u32 s36, s36, 0x80080
	s_addc_u32 s37, s37, 0
	s_add_i32 s38, s38, s42
	v_lshl_add_u64 v[128:129], s[36:37], 0, v[172:173]
	s_mov_b32 m0, s38
	s_nop 0
	global_load_lds_dwordx4 v[128:129], off
	v_lshl_add_u64 v[128:129], s[36:37], 0, v[174:175]
	s_add_i32 m0, s38, 0x2000
	s_nop 0
	global_load_lds_dwordx4 v[128:129], off
	s_waitcnt vmcnt(6)
	s_barrier

	v_mfma_f32_16x16x32_bf16 v[48:51], v[202:205], v[144:147], v[48:51]
	v_mfma_f32_16x16x32_bf16 v[44:47], v[222:225], v[144:147], v[44:47]
	v_mfma_f32_16x16x32_bf16 v[32:35], v[202:205], v[152:155], v[32:35]
	v_mfma_f32_16x16x32_bf16 v[28:31], v[222:225], v[152:155], v[28:31]
	v_mfma_f32_16x16x32_bf16 v[16:19], v[202:205], v[180:183], v[16:19]
	v_mfma_f32_16x16x32_bf16 v[12:15], v[222:225], v[180:183], v[12:15]
	v_mfma_f32_16x16x32_bf16 v[4:7], v[202:205], v[194:197], v[4:7]
	v_mfma_f32_16x16x32_bf16 v[0:3], v[222:225], v[194:197], v[0:3]
	v_mfma_f32_16x16x32_bf16 v[48:51], v[206:209], v[148:151], v[48:51]
	v_mfma_f32_16x16x32_bf16 v[44:47], v[226:229], v[148:151], v[44:47]
	v_mfma_f32_16x16x32_bf16 v[32:35], v[206:209], v[156:159], v[32:35]
	v_mfma_f32_16x16x32_bf16 v[28:31], v[226:229], v[156:159], v[28:31]
	v_mfma_f32_16x16x32_bf16 v[16:19], v[206:209], v[184:187], v[16:19]
	v_mfma_f32_16x16x32_bf16 v[12:15], v[226:229], v[184:187], v[12:15]
	v_mfma_f32_16x16x32_bf16 v[4:7], v[206:209], v[198:201], v[4:7]
	v_mfma_f32_16x16x32_bf16 v[0:3], v[226:229], v[198:201], v[0:3]

	s_add_u32 s4, s4, 0x100
	s_addc_u32 s5, s5, 0
	s_add_u32 s60, s60, 0x100
	s_addc_u32 s61, s61, 0
	s_cmp_ge_i32 s62, s17
	s_mov_b32 s36, s62
	s_barrier
	s_cbranch_scc0 .LBB0_1024
	s_setprio 0
	v_mov_b32_e32 v128, v210
	v_mov_b32_e32 v129, v169
	s_cmp_lt_i32 s12, 0
	v_lshl_add_u32 v128, v128, 4, v129
	v_ashrrev_i32_e32 v166, 2, v128
	v_and_b32_e32 v160, 3, v129
	v_and_b32_e32 v128, -4, v128
	v_lshl_add_u32 v193, v160, 6, v128
	s_mov_b64 s[4:5], -1
	s_cbranch_scc0 .LBB0_1043
	s_lshl_b32 s4, s30, 8
	v_lshl_or_b32 v128, v160, 2, s4
	s_lshl_b32 s4, s34, 8
	v_or_b32_e32 v180, s47, v128
	s_add_i32 s4, s4, s46
	v_readlane_b32 s60, v254, 6
	v_ashrrev_i32_e32 v181, 31, v180
	v_add_u32_e32 v184, s4, v166
	s_cmp_lt_i32 s34, 32
	v_readlane_b32 s61, v254, 7
	v_lshlrev_b64 v[128:129], 2, v[180:181]
	v_readlane_b32 s62, v254, 8
	v_readlane_b32 s63, v254, 9
	v_readlane_b32 s64, v254, 10
	v_readlane_b32 s65, v254, 11
	v_readlane_b32 s66, v254, 12
	v_readlane_b32 s67, v254, 13
	v_readlane_b32 s68, v254, 14
	v_readlane_b32 s69, v254, 15
	v_readlane_b32 s70, v254, 16
	v_readlane_b32 s71, v254, 17
	v_readlane_b32 s72, v254, 18
	v_readlane_b32 s73, v254, 19
	v_readlane_b32 s74, v254, 20
	v_readlane_b32 s75, v254, 21
	s_cselect_b32 s5, s61, s51
	s_cselect_b32 s4, s60, s50
	v_ashrrev_i32_e32 v185, 31, v184
	v_lshl_add_u64 v[182:183], s[4:5], 0, v[128:129]
	v_lshlrev_b64 v[130:131], 13, v[184:185]
	v_readlane_b32 s60, v254, 22
	v_lshl_add_u64 v[136:137], v[182:183], 0, v[130:131]
	v_readlane_b32 s61, v254, 23
	v_readlane_b32 s68, v254, 30
	v_readlane_b32 s69, v254, 31
	global_load_dwordx4 v[196:199], v[136:137], off nt
	global_load_dwordx4 v[200:203], v[136:137], off offset:64 nt
	global_load_dwordx4 v[204:207], v[136:137], off offset:512 nt
	s_mov_b64 s[60:61], s[68:69]
	v_lshl_add_u64 v[138:139], s[60:61], 0, v[128:129]
	global_load_dwordx4 v[140:143], v[138:139], off
	global_load_dwordx4 v[132:135], v[138:139], off offset:64
	global_load_dwordx4 v[128:131], v[138:139], off offset:512
	global_load_dwordx4 v[222:225], v[136:137], off offset:576 nt
	v_and_b32_e32 v145, 64, v192
	global_load_dwordx4 v[136:139], v[138:139], off offset:576
	v_xor_b32_e32 v144, 1, v192
	v_add_u32_e32 v194, 64, v145
	v_add_u32_e32 v186, 16, v184
	v_cmp_lt_i32_e64 s[4:5], v144, v194
	v_ashrrev_i32_e32 v187, 31, v186
	ds_bpermute_b32 v188, v193, v124
	v_cndmask_b32_e64 v195, v192, v144, s[4:5]
	v_lshlrev_b64 v[144:145], 13, v[186:187]
	v_lshl_add_u64 v[144:145], v[182:183], 0, v[144:145]
	global_load_dwordx4 v[156:159], v[144:145], off nt
	global_load_dwordx4 v[152:155], v[144:145], off offset:64 nt
	global_load_dwordx4 v[148:151], v[144:145], off offset:512 nt
	s_nop 0
	global_load_dwordx4 v[144:147], v[144:145], off offset:576 nt
	ds_bpermute_b32 v189, v193, v125
	ds_bpermute_b32 v208, v193, v126
	ds_bpermute_b32 v209, v193, v127
	ds_bpermute_b32 v226, v193, v120
	ds_bpermute_b32 v227, v193, v121
	ds_bpermute_b32 v228, v193, v122
	ds_bpermute_b32 v229, v193, v123
	ds_bpermute_b32 v230, v193, v112
	ds_bpermute_b32 v231, v193, v113
	v_readlane_b32 s64, v254, 26
	v_readlane_b32 s65, v254, 27
	v_readlane_b32 s66, v254, 28
	v_readlane_b32 s67, v254, 29
	v_readlane_b32 s72, v254, 34
	v_readlane_b32 s73, v254, 35
	v_readlane_b32 s74, v254, 36
	v_readlane_b32 s75, v254, 37
	s_mov_b64 s[64:65], s[72:73]
	ds_bpermute_b32 v232, v193, v114
	ds_bpermute_b32 v233, v193, v115
	v_lshlrev_b64 v[234:235], 11, v[184:185]
	s_mov_b64 s[66:67], s[74:75]
	v_lshl_add_u64 v[234:235], v[234:235], 0, v[180:181]
	v_xor_b32_e32 v167, 2, v192
	v_lshl_add_u64 v[236:237], v[234:235], 2, s[66:67]
	v_readlane_b32 s2, v254, 54
	v_cmp_lt_i32_e64 s[4:5], v167, v194
	v_lshlrev_b32_e32 v194, 2, v195
	v_lshlrev_b64 v[234:235], 1, v[234:235]
	v_readlane_b32 s3, v254, 55
	v_or_b32_e32 v240, 32, v234
	v_mov_b32_e32 v241, v235
	v_lshl_add_u64 v[238:239], s[2:3], 0, v[234:235]
	v_lshl_add_u64 v[240:241], s[2:3], 0, v[240:241]
	v_cndmask_b32_e64 v167, v192, v167, s[4:5]
	v_lshlrev_b32_e32 v167, 2, v167
	v_cmp_eq_u32_e32 vcc, 0, v160
	v_readlane_b32 s62, v254, 24
	v_readlane_b32 s63, v254, 25
	v_readlane_b32 s70, v254, 32
	v_readlane_b32 s71, v254, 33
	s_waitcnt vmcnt(0) lgkmcnt(0)
	v_pk_add_f32 v[198:199], v[198:199], v[208:209]
	v_pk_add_f32 v[196:197], v[196:197], v[188:189]
	v_pk_add_f32 v[202:203], v[202:203], v[228:229]
	v_pk_add_f32 v[200:201], v[200:201], v[226:227]
	v_pk_add_f32 v[204:205], v[204:205], v[230:231]
	v_mul_f32_e32 v195, v197, v197
	v_mul_f32_e32 v221, v199, v199
	global_store_dwordx4 v[236:237], v[196:199], off
	v_pk_mul_f32 v[188:189], v[142:143], v[198:199]
	v_pk_mul_f32 v[208:209], v[140:141], v[196:197]
	v_mul_f32_e32 v199, v201, v201
	v_mul_f32_e32 v230, v203, v203
	v_pk_mul_f32 v[226:227], v[134:135], v[202:203]
	v_pk_mul_f32 v[228:229], v[132:133], v[200:201]
	v_fmac_f32_e32 v195, v196, v196
	v_fmac_f32_e32 v221, v198, v198
	v_cvt_pk_bf16_f32 v196, v208, v209
	v_cvt_pk_bf16_f32 v197, v188, v189
	v_fmac_f32_e32 v199, v200, v200
	v_fmac_f32_e32 v230, v202, v202
	v_pk_add_f32 v[206:207], v[206:207], v[232:233]
	v_cvt_pk_bf16_f32 v188, v228, v229
	v_cvt_pk_bf16_f32 v189, v226, v227
	v_add_f32_e32 v195, v195, v221
	global_store_dwordx2 v[238:239], v[196:197], off
	v_add_f32_e32 v196, v199, v230
	global_store_dwordx4 v[236:237], v[200:203], off offset:64
	global_store_dwordx2 v[240:241], v[188:189], off
	v_add_f32_e32 v188, v195, v196
	v_mul_f32_e32 v189, v205, v205
	v_mul_f32_e32 v195, v207, v207
	v_fmac_f32_e32 v189, v204, v204
	v_fmac_f32_e32 v195, v206, v206
	ds_bpermute_b32 v200, v193, v108
	ds_bpermute_b32 v198, v193, v110
	ds_bpermute_b32 v199, v193, v111
	ds_bpermute_b32 v201, v193, v109
	v_add_f32_e32 v189, v189, v195
	v_add_f32_e32 v195, v188, v189
	v_pk_mul_f32 v[188:189], v[130:131], v[206:207]
	v_pk_mul_f32 v[196:197], v[128:129], v[204:205]
	global_store_dwordx4 v[236:237], v[204:207], off offset:512
	v_cvt_pk_bf16_f32 v196, v196, v197
	v_cvt_pk_bf16_f32 v197, v188, v189
	v_or_b32_e32 v188, 0x100, v234
	v_mov_b32_e32 v189, v235
	v_lshl_add_u64 v[188:189], s[2:3], 0, v[188:189]
	global_store_dwordx2 v[188:189], v[196:197], off
	s_waitcnt lgkmcnt(1)
	v_pk_add_f32 v[198:199], v[224:225], v[198:199]
	s_waitcnt lgkmcnt(0)
	v_pk_add_f32 v[196:197], v[222:223], v[200:201]
	v_mul_f32_e32 v189, v199, v199
	v_mul_f32_e32 v188, v197, v197
	v_fmac_f32_e32 v188, v196, v196
	v_fmac_f32_e32 v189, v198, v198
	v_add_f32_e32 v188, v188, v189
	v_add_f32_e32 v195, v195, v188
	ds_bpermute_b32 v200, v194, v195
	v_pk_mul_f32 v[188:189], v[136:137], v[196:197]
	global_store_dwordx4 v[236:237], v[196:199], off offset:576
	v_or_b32_e32 v234, 0x120, v234
	s_nop 0
	v_cvt_pk_bf16_f32 v196, v188, v189
	s_waitcnt lgkmcnt(0)
	v_add_f32_e32 v188, v195, v200
	ds_bpermute_b32 v189, v167, v188
	v_pk_mul_f32 v[198:199], v[138:139], v[198:199]
	s_nop 0
	v_cvt_pk_bf16_f32 v197, v198, v199
	v_lshl_add_u64 v[198:199], s[2:3], 0, v[234:235]
	global_store_dwordx2 v[198:199], v[196:197], off
	s_and_saveexec_b64 s[4:5], vcc
	s_cbranch_execz .LBB0_1028
	s_waitcnt lgkmcnt(0)
	v_add_f32_e32 v195, v188, v189
	s_lshl_b32 s36, s30, 2
	v_lshlrev_b64 v[188:189], 7, v[184:185]
	s_ashr_i32 s37, s36, 31
	v_lshl_add_u64 v[188:189], s[10:11], 0, v[188:189]
	v_lshl_add_u64 v[188:189], s[36:37], 2, v[188:189]
	s_lshl_b32 s36, s45, 2
	s_mov_b32 s37, s13
	v_lshl_add_u64 v[188:189], v[188:189], 0, s[36:37]
	global_store_dword v[188:189], v195, off

.LBB0_1166:
	s_ashr_i32 s15, s14, 31
	v_cmp_lt_i64_e32 vcc, s[16:17], v[132:133]
	s_lshl_b64 s[16:17], s[14:15], 20
	v_readlane_b32 s18, v254, 54
	v_readlane_b32 s19, v254, 55
	s_add_u32 s16, s18, s16
	s_addc_u32 s17, s19, s17
	s_and_b64 s[18:19], vcc, exec
	s_cselect_b32 s15, s17, s23
	s_cselect_b32 s49, s16, s22
	s_ashr_i32 s13, s12, 31
	s_lshl_b64 s[18:19], s[12:13], 20
	s_add_u32 s18, s29, s18
	s_addc_u32 s19, s30, s19
	s_and_b64 s[26:27], vcc, exec
	s_cselect_b32 s13, s19, s25
	s_cselect_b32 s50, s18, s24
	s_add_u32 s22, s22, 0x80080
	s_addc_u32 s23, s23, 0
	s_add_u32 s51, s24, 0x100
	v_mov_b32_e32 v0, 0
	s_addc_u32 s52, s25, 0
	s_mov_b32 s53, -2
	v_mov_b32_e32 v1, v0
	v_mov_b32_e32 v2, v0
	v_mov_b32_e32 v3, v0
	v_mov_b32_e32 v4, v0
	v_mov_b32_e32 v5, v0
	v_mov_b32_e32 v6, v0
	v_mov_b32_e32 v7, v0
	v_mov_b32_e32 v12, v0
	v_mov_b32_e32 v13, v0
	v_mov_b32_e32 v14, v0
	v_mov_b32_e32 v15, v0
	v_mov_b32_e32 v20, v0
	v_mov_b32_e32 v21, v0
	v_mov_b32_e32 v22, v0
	v_mov_b32_e32 v23, v0
	v_mov_b32_e32 v28, v0
	v_mov_b32_e32 v29, v0
	v_mov_b32_e32 v30, v0
	v_mov_b32_e32 v31, v0
	v_mov_b32_e32 v36, v0
	v_mov_b32_e32 v37, v0
	v_mov_b32_e32 v38, v0
	v_mov_b32_e32 v39, v0
	v_mov_b32_e32 v44, v0
	v_mov_b32_e32 v45, v0
	v_mov_b32_e32 v46, v0
	v_mov_b32_e32 v47, v0
	v_mov_b32_e32 v52, v0
	v_mov_b32_e32 v53, v0
	v_mov_b32_e32 v54, v0
	v_mov_b32_e32 v55, v0
	v_mov_b32_e32 v8, v0
	v_mov_b32_e32 v9, v0
	v_mov_b32_e32 v10, v0
	v_mov_b32_e32 v11, v0
	v_mov_b32_e32 v16, v0
	v_mov_b32_e32 v17, v0
	v_mov_b32_e32 v18, v0
	v_mov_b32_e32 v19, v0
	v_mov_b32_e32 v24, v0
	v_mov_b32_e32 v25, v0
	v_mov_b32_e32 v26, v0
	v_mov_b32_e32 v27, v0
	v_mov_b32_e32 v32, v0
	v_mov_b32_e32 v33, v0
	v_mov_b32_e32 v34, v0
	v_mov_b32_e32 v35, v0
	v_mov_b32_e32 v40, v0
	v_mov_b32_e32 v41, v0
	v_mov_b32_e32 v42, v0
	v_mov_b32_e32 v43, v0
	v_mov_b32_e32 v48, v0
	v_mov_b32_e32 v49, v0
	v_mov_b32_e32 v50, v0
	v_mov_b32_e32 v51, v0
	v_mov_b32_e32 v56, v0
	v_mov_b32_e32 v57, v0
	v_mov_b32_e32 v58, v0
	v_mov_b32_e32 v59, v0
	v_mov_b32_e32 v60, v0
	v_mov_b32_e32 v61, v0
	v_mov_b32_e32 v62, v0
	v_mov_b32_e32 v63, v0
	v_mov_b32_e32 v64, v0
	v_mov_b32_e32 v65, v0
	v_mov_b32_e32 v66, v0
	v_mov_b32_e32 v67, v0
	v_mov_b32_e32 v68, v0
	v_mov_b32_e32 v69, v0
	v_mov_b32_e32 v70, v0
	v_mov_b32_e32 v71, v0
	v_mov_b32_e32 v76, v0
	v_mov_b32_e32 v77, v0
	v_mov_b32_e32 v78, v0
	v_mov_b32_e32 v79, v0
	v_mov_b32_e32 v84, v0
	v_mov_b32_e32 v85, v0
	v_mov_b32_e32 v86, v0
	v_mov_b32_e32 v87, v0
	v_mov_b32_e32 v92, v0
	v_mov_b32_e32 v93, v0
	v_mov_b32_e32 v94, v0
	v_mov_b32_e32 v95, v0
	v_mov_b32_e32 v100, v0
	v_mov_b32_e32 v101, v0
	v_mov_b32_e32 v102, v0
	v_mov_b32_e32 v103, v0
	v_mov_b32_e32 v108, v0
	v_mov_b32_e32 v109, v0
	v_mov_b32_e32 v110, v0
	v_mov_b32_e32 v111, v0
	v_mov_b32_e32 v112, v0
	v_mov_b32_e32 v113, v0
	v_mov_b32_e32 v114, v0
	v_mov_b32_e32 v115, v0
	v_mov_b32_e32 v72, v0
	v_mov_b32_e32 v73, v0
	v_mov_b32_e32 v74, v0
	v_mov_b32_e32 v75, v0
	v_mov_b32_e32 v80, v0
	v_mov_b32_e32 v81, v0
	v_mov_b32_e32 v82, v0
	v_mov_b32_e32 v83, v0
	v_mov_b32_e32 v88, v0
	v_mov_b32_e32 v89, v0
	v_mov_b32_e32 v90, v0
	v_mov_b32_e32 v91, v0
	v_mov_b32_e32 v96, v0
	v_mov_b32_e32 v97, v0
	v_mov_b32_e32 v98, v0
	v_mov_b32_e32 v99, v0
	v_mov_b32_e32 v104, v0
	v_mov_b32_e32 v105, v0
	v_mov_b32_e32 v106, v0
	v_mov_b32_e32 v107, v0
	v_mov_b32_e32 v116, v0
	v_mov_b32_e32 v117, v0
	v_mov_b32_e32 v118, v0
	v_mov_b32_e32 v119, v0
	v_mov_b32_e32 v120, v0
	v_mov_b32_e32 v121, v0
	v_mov_b32_e32 v122, v0
	v_mov_b32_e32 v123, v0
	v_mov_b32_e32 v124, v0
	v_mov_b32_e32 v125, v0
	v_mov_b32_e32 v126, v0
	v_mov_b32_e32 v127, v0
	v_readlane_b32 s70, v254, 44
	s_cmp_lt_u32 s70, 4
	s_cbranch_scc1 .Lsp_2
	s_setprio 1
.Lsp_2:
.LBB0_1167:
	ds_read_b128 v[148:151], v143
	ds_read_b128 v[152:155], v143 offset:1024
	ds_read_b128 v[156:159], v143 offset:2048
	ds_read_b128 v[160:163], v143 offset:3072
	s_add_u32 s24, s22, 0xfff80080
	s_addc_u32 s25, s23, -1
	s_cmp_eq_u32 s53, 28
	s_cselect_b32 s27, s15, s25
	s_cselect_b32 s26, s49, s24
	s_cselect_b32 s25, s13, s52
	s_cselect_b32 s24, s50, s51
	v_lshl_add_u64 v[136:137], s[22:23], 0, v[128:129]
	s_add_i32 m0, s21, 0xc000
	ds_read_b128 v[164:167], v145
	ds_read_b128 v[176:179], v145 offset:1024
	ds_read_b128 v[180:183], v145 offset:2048
	ds_read_b128 v[184:187], v145 offset:3072
	ds_read_b128 v[188:191], v145 offset:4096
	ds_read_b128 v[192:195], v145 offset:5120
	ds_read_b128 v[196:199], v145 offset:6144
	ds_read_b128 v[200:203], v145 offset:7168
	global_load_lds_dwordx4 v[136:137], off
	v_lshl_add_u64 v[136:137], s[22:23], 0, v[130:131]
	s_add_i32 m0, s21, 0xe000
	s_nop 0
	global_load_lds_dwordx4 v[136:137], off
	s_waitcnt lgkmcnt(8)
	s_barrier
	s_waitcnt lgkmcnt(0)

	s_waitcnt lgkmcnt(0)
	v_mfma_f32_16x16x32_bf16 v[124:127], v[148:151], v[164:167], v[124:127]
	v_mfma_f32_16x16x32_bf16 v[120:123], v[156:159], v[164:167], v[120:123]
	v_mfma_f32_16x16x32_bf16 v[116:119], v[148:151], v[180:183], v[116:119]
	v_mfma_f32_16x16x32_bf16 v[104:107], v[156:159], v[180:183], v[104:107]
	v_mfma_f32_16x16x32_bf16 v[96:99], v[148:151], v[188:191], v[96:99]
	v_mfma_f32_16x16x32_bf16 v[88:91], v[156:159], v[188:191], v[88:91]
	v_mfma_f32_16x16x32_bf16 v[80:83], v[148:151], v[196:199], v[80:83]
	v_mfma_f32_16x16x32_bf16 v[72:75], v[156:159], v[196:199], v[72:75]
	v_mfma_f32_16x16x32_bf16 v[124:127], v[152:155], v[176:179], v[124:127]
	v_mfma_f32_16x16x32_bf16 v[120:123], v[160:163], v[176:179], v[120:123]
	v_mfma_f32_16x16x32_bf16 v[116:119], v[152:155], v[184:187], v[116:119]
	v_mfma_f32_16x16x32_bf16 v[104:107], v[160:163], v[184:187], v[104:107]
	v_mfma_f32_16x16x32_bf16 v[96:99], v[152:155], v[192:195], v[96:99]
	v_mfma_f32_16x16x32_bf16 v[88:91], v[160:163], v[192:195], v[88:91]
	v_mfma_f32_16x16x32_bf16 v[80:83], v[152:155], v[200:203], v[80:83]
	v_mfma_f32_16x16x32_bf16 v[72:75], v[160:163], v[200:203], v[72:75]

	s_barrier
	s_add_i32 s54, s45, s31
	v_lshl_add_u64 v[136:137], s[24:25], 0, v[172:173]
	s_mov_b32 m0, s54
	ds_read_b128 v[204:207], v147
	ds_read_b128 v[218:221], v147 offset:1024
	ds_read_b128 v[222:225], v147 offset:2048
	ds_read_b128 v[226:229], v147 offset:3072
	global_load_lds_dwordx4 v[136:137], off
	v_lshl_add_u64 v[140:141], s[24:25], 0, v[174:175]
	s_add_i32 m0, s54, 0x2000
	s_nop 0
	global_load_lds_dwordx4 v[140:141], off
	s_barrier
	s_waitcnt lgkmcnt(0)

	s_waitcnt lgkmcnt(0)
	v_mfma_f32_16x16x32_bf16 v[112:115], v[204:207], v[164:167], v[112:115]
	v_mfma_f32_16x16x32_bf16 v[108:111], v[222:225], v[164:167], v[108:111]
	v_mfma_f32_16x16x32_bf16 v[100:103], v[204:207], v[180:183], v[100:103]
	v_mfma_f32_16x16x32_bf16 v[92:95], v[222:225], v[180:183], v[92:95]
	v_mfma_f32_16x16x32_bf16 v[84:87], v[204:207], v[188:191], v[84:87]
	v_mfma_f32_16x16x32_bf16 v[76:79], v[222:225], v[188:191], v[76:79]
	v_mfma_f32_16x16x32_bf16 v[68:71], v[204:207], v[196:199], v[68:71]
	v_mfma_f32_16x16x32_bf16 v[64:67], v[222:225], v[196:199], v[64:67]
	v_mfma_f32_16x16x32_bf16 v[112:115], v[218:221], v[176:179], v[112:115]
	v_mfma_f32_16x16x32_bf16 v[108:111], v[226:229], v[176:179], v[108:111]
	v_mfma_f32_16x16x32_bf16 v[100:103], v[218:221], v[184:187], v[100:103]
	v_mfma_f32_16x16x32_bf16 v[92:95], v[226:229], v[184:187], v[92:95]
	v_mfma_f32_16x16x32_bf16 v[84:87], v[218:221], v[192:195], v[84:87]
	v_mfma_f32_16x16x32_bf16 v[76:79], v[226:229], v[192:195], v[76:79]
	v_mfma_f32_16x16x32_bf16 v[68:71], v[218:221], v[200:203], v[68:71]
	v_mfma_f32_16x16x32_bf16 v[64:67], v[226:229], v[200:203], v[64:67]

	s_mov_b32 m0, s21
	v_lshl_add_u64 v[208:209], s[26:27], 0, v[172:173]
	s_barrier
	ds_read_b128 v[164:167], v145 offset:16384
	ds_read_b128 v[176:179], v145 offset:17408
	ds_read_b128 v[180:183], v145 offset:18432
	ds_read_b128 v[184:187], v145 offset:19456
	ds_read_b128 v[188:191], v145 offset:20480
	ds_read_b128 v[192:195], v145 offset:21504
	ds_read_b128 v[196:199], v145 offset:22528
	ds_read_b128 v[200:203], v145 offset:23552
	global_load_lds_dwordx4 v[208:209], off
	v_lshl_add_u64 v[230:231], s[26:27], 0, v[174:175]
	s_mov_b32 m0, s35
	s_nop 0
	global_load_lds_dwordx4 v[230:231], off
	s_barrier
	s_waitcnt lgkmcnt(0)

	s_waitcnt lgkmcnt(0)
	v_mfma_f32_16x16x32_bf16 v[60:63], v[148:151], v[164:167], v[60:63]
	v_mfma_f32_16x16x32_bf16 v[56:59], v[156:159], v[164:167], v[56:59]
	v_mfma_f32_16x16x32_bf16 v[48:51], v[148:151], v[180:183], v[48:51]
	v_mfma_f32_16x16x32_bf16 v[40:43], v[156:159], v[180:183], v[40:43]
	v_mfma_f32_16x16x32_bf16 v[32:35], v[148:151], v[188:191], v[32:35]
	v_mfma_f32_16x16x32_bf16 v[24:27], v[156:159], v[188:191], v[24:27]
	v_mfma_f32_16x16x32_bf16 v[16:19], v[148:151], v[196:199], v[16:19]
	v_mfma_f32_16x16x32_bf16 v[8:11], v[156:159], v[196:199], v[8:11]
	v_mfma_f32_16x16x32_bf16 v[60:63], v[152:155], v[176:179], v[60:63]
	v_mfma_f32_16x16x32_bf16 v[56:59], v[160:163], v[176:179], v[56:59]
	v_mfma_f32_16x16x32_bf16 v[48:51], v[152:155], v[184:187], v[48:51]
	v_mfma_f32_16x16x32_bf16 v[40:43], v[160:163], v[184:187], v[40:43]
	v_mfma_f32_16x16x32_bf16 v[32:35], v[152:155], v[192:195], v[32:35]
	v_mfma_f32_16x16x32_bf16 v[24:27], v[160:163], v[192:195], v[24:27]
	v_mfma_f32_16x16x32_bf16 v[16:19], v[152:155], v[200:203], v[16:19]
	v_mfma_f32_16x16x32_bf16 v[8:11], v[160:163], v[200:203], v[8:11]

	s_barrier
	s_add_u32 s54, s24, 0x80000
	s_addc_u32 s55, s25, 0
	s_add_i32 s56, s46, s31
	v_lshl_add_u64 v[148:149], s[54:55], 0, v[172:173]
	s_mov_b32 m0, s56
	s_nop 0
	global_load_lds_dwordx4 v[148:149], off
	v_lshl_add_u64 v[148:149], s[54:55], 0, v[174:175]
	s_add_i32 m0, s56, 0x2000
	s_nop 0
	global_load_lds_dwordx4 v[148:149], off
	s_waitcnt vmcnt(6)
	s_barrier

	v_mfma_f32_16x16x32_bf16 v[52:55], v[204:207], v[164:167], v[52:55]
	v_mfma_f32_16x16x32_bf16 v[44:47], v[222:225], v[164:167], v[44:47]
	v_mfma_f32_16x16x32_bf16 v[36:39], v[204:207], v[180:183], v[36:39]
	v_mfma_f32_16x16x32_bf16 v[28:31], v[222:225], v[180:183], v[28:31]
	v_mfma_f32_16x16x32_bf16 v[20:23], v[204:207], v[188:191], v[20:23]
	v_mfma_f32_16x16x32_bf16 v[12:15], v[222:225], v[188:191], v[12:15]
	v_mfma_f32_16x16x32_bf16 v[4:7], v[204:207], v[196:199], v[4:7]
	v_mfma_f32_16x16x32_bf16 v[0:3], v[222:225], v[196:199], v[0:3]
	v_mfma_f32_16x16x32_bf16 v[52:55], v[218:221], v[176:179], v[52:55]
	v_mfma_f32_16x16x32_bf16 v[44:47], v[226:229], v[176:179], v[44:47]
	v_mfma_f32_16x16x32_bf16 v[36:39], v[218:221], v[184:187], v[36:39]
	v_mfma_f32_16x16x32_bf16 v[28:31], v[226:229], v[184:187], v[28:31]
	v_mfma_f32_16x16x32_bf16 v[20:23], v[218:221], v[192:195], v[20:23]
	v_mfma_f32_16x16x32_bf16 v[12:15], v[226:229], v[192:195], v[12:15]
	v_mfma_f32_16x16x32_bf16 v[4:7], v[218:221], v[200:203], v[4:7]
	v_mfma_f32_16x16x32_bf16 v[0:3], v[226:229], v[200:203], v[0:3]

	s_add_i32 s54, 0, 0x18000
	v_add_u32_e32 v138, s54, v139
	s_barrier
	ds_read_b128 v[148:151], v138
	ds_read_b128 v[152:155], v138 offset:1024
	ds_read_b128 v[156:159], v138 offset:2048
	ds_read_b128 v[160:163], v138 offset:3072
	s_add_u32 s26, s26, 0x80000
	s_addc_u32 s27, s27, 0
	s_mov_b32 m0, s36
	v_lshl_add_u64 v[204:205], s[26:27], 0, v[172:173]
	ds_read_b128 v[164:167], v145 offset:32768
	ds_read_b128 v[176:179], v145 offset:33792
	ds_read_b128 v[180:183], v145 offset:34816
	ds_read_b128 v[184:187], v145 offset:35840
	ds_read_b128 v[188:191], v145 offset:36864
	ds_read_b128 v[192:195], v145 offset:37888
	ds_read_b128 v[196:199], v145 offset:38912
	ds_read_b128 v[200:203], v145 offset:39936
	global_load_lds_dwordx4 v[204:205], off
	v_lshl_add_u64 v[204:205], s[26:27], 0, v[174:175]
	s_mov_b32 m0, s37
	s_nop 0
	global_load_lds_dwordx4 v[204:205], off
	s_waitcnt lgkmcnt(8)
	s_barrier
	s_waitcnt lgkmcnt(0)

	s_waitcnt lgkmcnt(0)
	v_mfma_f32_16x16x32_bf16 v[124:127], v[148:151], v[164:167], v[124:127]
	v_mfma_f32_16x16x32_bf16 v[120:123], v[156:159], v[164:167], v[120:123]
	v_mfma_f32_16x16x32_bf16 v[116:119], v[148:151], v[180:183], v[116:119]
	v_mfma_f32_16x16x32_bf16 v[104:107], v[156:159], v[180:183], v[104:107]
	v_mfma_f32_16x16x32_bf16 v[96:99], v[148:151], v[188:191], v[96:99]
	v_mfma_f32_16x16x32_bf16 v[88:91], v[156:159], v[188:191], v[88:91]
	v_mfma_f32_16x16x32_bf16 v[80:83], v[148:151], v[196:199], v[80:83]
	v_mfma_f32_16x16x32_bf16 v[72:75], v[156:159], v[196:199], v[72:75]
	v_mfma_f32_16x16x32_bf16 v[124:127], v[152:155], v[176:179], v[124:127]
	v_mfma_f32_16x16x32_bf16 v[120:123], v[160:163], v[176:179], v[120:123]
	v_mfma_f32_16x16x32_bf16 v[116:119], v[152:155], v[184:187], v[116:119]
	v_mfma_f32_16x16x32_bf16 v[104:107], v[160:163], v[184:187], v[104:107]
	v_mfma_f32_16x16x32_bf16 v[96:99], v[152:155], v[192:195], v[96:99]
	v_mfma_f32_16x16x32_bf16 v[88:91], v[160:163], v[192:195], v[88:91]
	v_mfma_f32_16x16x32_bf16 v[80:83], v[152:155], v[200:203], v[80:83]
	v_mfma_f32_16x16x32_bf16 v[72:75], v[160:163], v[200:203], v[72:75]

	s_barrier
	s_add_i32 s26, 0, 0x1c000
	s_add_i32 s27, s54, s31
	v_add_u32_e32 v138, s26, v139
	v_lshl_add_u64 v[136:137], v[136:137], 0, s[10:11]
	s_mov_b32 m0, s27
	ds_read_b128 v[204:207], v138
	ds_read_b128 v[218:221], v138 offset:1024
	ds_read_b128 v[222:225], v138 offset:2048
	ds_read_b128 v[226:229], v138 offset:3072
	global_load_lds_dwordx4 v[136:137], off
	v_lshl_add_u64 v[136:137], v[140:141], 0, s[10:11]
	s_add_i32 m0, s27, 0x2000
	s_nop 0
	global_load_lds_dwordx4 v[136:137], off
	s_barrier
	s_waitcnt lgkmcnt(0)

	s_waitcnt lgkmcnt(0)
	v_mfma_f32_16x16x32_bf16 v[112:115], v[204:207], v[164:167], v[112:115]
	v_mfma_f32_16x16x32_bf16 v[108:111], v[222:225], v[164:167], v[108:111]
	v_mfma_f32_16x16x32_bf16 v[100:103], v[204:207], v[180:183], v[100:103]
	v_mfma_f32_16x16x32_bf16 v[92:95], v[222:225], v[180:183], v[92:95]
	v_mfma_f32_16x16x32_bf16 v[84:87], v[204:207], v[188:191], v[84:87]
	v_mfma_f32_16x16x32_bf16 v[76:79], v[222:225], v[188:191], v[76:79]
	v_mfma_f32_16x16x32_bf16 v[68:71], v[204:207], v[196:199], v[68:71]
	v_mfma_f32_16x16x32_bf16 v[64:67], v[222:225], v[196:199], v[64:67]
	v_mfma_f32_16x16x32_bf16 v[112:115], v[218:221], v[176:179], v[112:115]
	v_mfma_f32_16x16x32_bf16 v[108:111], v[226:229], v[176:179], v[108:111]
	v_mfma_f32_16x16x32_bf16 v[100:103], v[218:221], v[184:187], v[100:103]
	v_mfma_f32_16x16x32_bf16 v[92:95], v[226:229], v[184:187], v[92:95]
	v_mfma_f32_16x16x32_bf16 v[84:87], v[218:221], v[192:195], v[84:87]
	v_mfma_f32_16x16x32_bf16 v[76:79], v[226:229], v[192:195], v[76:79]
	v_mfma_f32_16x16x32_bf16 v[68:71], v[218:221], v[200:203], v[68:71]
	v_mfma_f32_16x16x32_bf16 v[64:67], v[226:229], v[200:203], v[64:67]

	s_mov_b32 m0, s41
	v_lshl_add_u64 v[136:137], v[208:209], 0, s[10:11]
	s_barrier
	ds_read_b128 v[164:167], v145 offset:49152
	ds_read_b128 v[176:179], v145 offset:50176
	ds_read_b128 v[180:183], v145 offset:51200
	ds_read_b128 v[184:187], v145 offset:52224
	ds_read_b128 v[188:191], v145 offset:53248
	ds_read_b128 v[192:195], v145 offset:54272
	ds_read_b128 v[196:199], v145 offset:55296
	ds_read_b128 v[200:203], v145 offset:56320
	global_load_lds_dwordx4 v[136:137], off
	v_lshl_add_u64 v[136:137], v[230:231], 0, s[10:11]
	s_mov_b32 m0, s42
	s_nop 0
	global_load_lds_dwordx4 v[136:137], off
	s_barrier
	s_waitcnt lgkmcnt(0)

	s_waitcnt lgkmcnt(0)
	v_mfma_f32_16x16x32_bf16 v[60:63], v[148:151], v[164:167], v[60:63]
	v_mfma_f32_16x16x32_bf16 v[56:59], v[156:159], v[164:167], v[56:59]
	v_mfma_f32_16x16x32_bf16 v[48:51], v[148:151], v[180:183], v[48:51]
	v_mfma_f32_16x16x32_bf16 v[40:43], v[156:159], v[180:183], v[40:43]
	v_mfma_f32_16x16x32_bf16 v[32:35], v[148:151], v[188:191], v[32:35]
	v_mfma_f32_16x16x32_bf16 v[24:27], v[156:159], v[188:191], v[24:27]
	v_mfma_f32_16x16x32_bf16 v[16:19], v[148:151], v[196:199], v[16:19]
	v_mfma_f32_16x16x32_bf16 v[8:11], v[156:159], v[196:199], v[8:11]
	v_mfma_f32_16x16x32_bf16 v[60:63], v[152:155], v[176:179], v[60:63]
	v_mfma_f32_16x16x32_bf16 v[56:59], v[160:163], v[176:179], v[56:59]
	v_mfma_f32_16x16x32_bf16 v[48:51], v[152:155], v[184:187], v[48:51]
	v_mfma_f32_16x16x32_bf16 v[40:43], v[160:163], v[184:187], v[40:43]
	v_mfma_f32_16x16x32_bf16 v[32:35], v[152:155], v[192:195], v[32:35]
	v_mfma_f32_16x16x32_bf16 v[24:27], v[160:163], v[192:195], v[24:27]
	v_mfma_f32_16x16x32_bf16 v[16:19], v[152:155], v[200:203], v[16:19]
	v_mfma_f32_16x16x32_bf16 v[8:11], v[160:163], v[200:203], v[8:11]

	s_barrier
	s_add_u32 s24, s24, 0x80080
	s_addc_u32 s25, s25, 0
	s_add_i32 s26, s26, s31
	v_lshl_add_u64 v[136:137], s[24:25], 0, v[172:173]
	s_mov_b32 m0, s26
	s_nop 0
	global_load_lds_dwordx4 v[136:137], off
	v_lshl_add_u64 v[136:137], s[24:25], 0, v[174:175]
	s_add_i32 m0, s26, 0x2000
	s_nop 0
	global_load_lds_dwordx4 v[136:137], off
	s_waitcnt vmcnt(6)
	s_barrier

	v_mfma_f32_16x16x32_bf16 v[52:55], v[204:207], v[164:167], v[52:55]
	v_mfma_f32_16x16x32_bf16 v[44:47], v[222:225], v[164:167], v[44:47]
	v_mfma_f32_16x16x32_bf16 v[36:39], v[204:207], v[180:183], v[36:39]
	v_mfma_f32_16x16x32_bf16 v[28:31], v[222:225], v[180:183], v[28:31]
	v_mfma_f32_16x16x32_bf16 v[20:23], v[204:207], v[188:191], v[20:23]
	v_mfma_f32_16x16x32_bf16 v[12:15], v[222:225], v[188:191], v[12:15]
	v_mfma_f32_16x16x32_bf16 v[4:7], v[204:207], v[196:199], v[4:7]
	v_mfma_f32_16x16x32_bf16 v[0:3], v[222:225], v[196:199], v[0:3]
	v_mfma_f32_16x16x32_bf16 v[52:55], v[218:221], v[176:179], v[52:55]
	v_mfma_f32_16x16x32_bf16 v[44:47], v[226:229], v[176:179], v[44:47]
	v_mfma_f32_16x16x32_bf16 v[36:39], v[218:221], v[184:187], v[36:39]
	v_mfma_f32_16x16x32_bf16 v[28:31], v[226:229], v[184:187], v[28:31]
	v_mfma_f32_16x16x32_bf16 v[20:23], v[218:221], v[192:195], v[20:23]
	v_mfma_f32_16x16x32_bf16 v[12:15], v[226:229], v[192:195], v[12:15]
	v_mfma_f32_16x16x32_bf16 v[4:7], v[218:221], v[200:203], v[4:7]
	v_mfma_f32_16x16x32_bf16 v[0:3], v[226:229], v[200:203], v[0:3]

	s_add_i32 s53, s53, 2
	s_add_u32 s22, s22, 0x100
	s_addc_u32 s23, s23, 0
	s_add_u32 s51, s51, 0x100
	s_addc_u32 s52, s52, 0
	s_cmp_gt_u32 s53, 29
	s_barrier
	s_cbranch_scc0 .LBB0_1167
	s_setprio 0
	s_lshl_b32 s13, s20, 8
	v_mov_b32_e32 v138, v210
	v_mov_b32_e32 v142, v169
	s_add_i32 s13, s13, s39
	s_lshl_b32 s15, s48, 7
	v_add_u32_e32 v136, s13, v142
	v_ashrrev_i32_e32 v137, 31, v136
	v_lshl_add_u64 v[140:141], v[136:137], 2, s[2:3]
	global_load_dword v154, v[140:141], off
	global_load_dword v152, v[140:141], off offset:64
	v_lshl_add_u32 v138, v138, 4, v142
	v_and_b32_e32 v142, 3, v142
	v_ashrrev_i32_e32 v144, 2, v138
	v_and_b32_e32 v138, -4, v138
	v_lshl_or_b32 v146, v142, 2, s15
	v_add_u32_e32 v151, s13, v144
	v_lshl_add_u32 v149, v142, 6, v138
	v_or_b32_e32 v156, s40, v146
	global_load_dword v150, v[140:141], off offset:128
	global_load_dword v148, v[140:141], off offset:192
	global_load_dword v146, v[140:141], off offset:512
	global_load_dword v144, v[140:141], off offset:576
	global_load_dword v142, v[140:141], off offset:640
	global_load_dword v138, v[140:141], off offset:704
	v_mov_b64_e32 v[136:137], s[0:1]
	v_ashrrev_i32_e32 v157, 31, v156
	v_mad_i64_i32 v[158:159], s[22:23], v151, s47, v[136:137]
	v_lshlrev_b64 v[140:141], 1, v[156:157]
	v_lshl_add_u64 v[156:157], v[158:159], 0, v[140:141]
	v_add_u32_e32 v153, 16, v151
	s_and_b64 vcc, exec, s[4:5]
	s_mov_b32 s48, s12
	s_mov_b32 s20, s14
	s_mov_b64 s[24:25], s[18:19]
	s_waitcnt vmcnt(0)
	v_pk_mul_f32 v[126:127], v[126:127], v[154:155] op_sel_hi:[1,0]
	v_pk_mul_f32 v[124:125], v[124:125], v[154:155] op_sel_hi:[1,0]
	v_pk_mul_f32 v[114:115], v[114:115], v[154:155] op_sel_hi:[1,0]
	v_pk_mul_f32 v[112:113], v[112:113], v[154:155] op_sel_hi:[1,0]
	v_pk_mul_f32 v[122:123], v[122:123], v[154:155] op_sel_hi:[1,0]
	v_pk_mul_f32 v[120:121], v[120:121], v[154:155] op_sel_hi:[1,0]
	v_pk_mul_f32 v[110:111], v[110:111], v[154:155] op_sel_hi:[1,0]
	v_pk_mul_f32 v[108:109], v[108:109], v[154:155] op_sel_hi:[1,0]
	v_mul_f32_e32 v154, 0xbfb8aa3b, v124
	v_mul_f32_e32 v155, 0xbfb8aa3b, v125
	v_mul_f32_e32 v158, 0xbfb8aa3b, v126
	v_mul_f32_e32 v159, 0xbfb8aa3b, v127
	v_mul_f32_e32 v160, 0xbfb8aa3b, v120
	v_mul_f32_e32 v161, 0xbfb8aa3b, v121
	v_mul_f32_e32 v162, 0xbfb8aa3b, v122
	v_mul_f32_e32 v163, 0xbfb8aa3b, v123
	v_exp_f32_e32 v154, v154
	v_exp_f32_e32 v155, v155
	v_exp_f32_e32 v158, v158
	v_exp_f32_e32 v159, v159
	v_exp_f32_e32 v160, v160
	v_exp_f32_e32 v161, v161
	v_exp_f32_e32 v162, v162
	v_exp_f32_e32 v163, v163
	v_add_f32_e32 v154, 1.0, v154
	v_add_f32_e32 v155, 1.0, v155
	v_add_f32_e32 v158, 1.0, v158
	v_add_f32_e32 v159, 1.0, v159
	v_add_f32_e32 v160, 1.0, v160
	v_add_f32_e32 v161, 1.0, v161
	v_add_f32_e32 v162, 1.0, v162
	v_add_f32_e32 v163, 1.0, v163
	v_rcp_f32_e32 v154, v154
	v_rcp_f32_e32 v155, v155
	v_rcp_f32_e32 v158, v158
	v_rcp_f32_e32 v159, v159
	v_rcp_f32_e32 v160, v160
	v_rcp_f32_e32 v161, v161
	v_rcp_f32_e32 v162, v162
	v_rcp_f32_e32 v163, v163
	v_pk_mul_f32 v[124:125], v[124:125], v[154:155]
	v_pk_mul_f32 v[126:127], v[126:127], v[158:159]
	v_pk_mul_f32 v[120:121], v[120:121], v[160:161]
	v_pk_mul_f32 v[122:123], v[122:123], v[162:163]
	v_pk_mul_f32 v[112:113], v[112:113], v[124:125]
	v_pk_mul_f32 v[114:115], v[114:115], v[126:127]
	v_pk_mul_f32 v[118:119], v[118:119], v[152:153] op_sel_hi:[1,0]
	v_pk_mul_f32 v[116:117], v[116:117], v[152:153] op_sel_hi:[1,0]
	v_pk_mul_f32 v[108:109], v[108:109], v[120:121]
	v_pk_mul_f32 v[110:111], v[110:111], v[122:123]
	v_cvt_pk_bf16_f32 v112, v112, v113
	v_cvt_pk_bf16_f32 v113, v114, v115
	v_mul_f32_e32 v164, 0xbfb8aa3b, v116
	v_mul_f32_e32 v165, 0xbfb8aa3b, v117
	v_mul_f32_e32 v166, 0xbfb8aa3b, v118
	v_mul_f32_e32 v167, 0xbfb8aa3b, v119
	v_cvt_pk_bf16_f32 v114, v108, v109
	v_cvt_pk_bf16_f32 v111, v110, v111
	ds_bpermute_b32 v108, v149, v112
	ds_bpermute_b32 v109, v149, v113
	v_exp_f32_e32 v164, v164
	v_exp_f32_e32 v165, v165
	v_exp_f32_e32 v166, v166
	v_exp_f32_e32 v167, v167
	ds_bpermute_b32 v110, v149, v114
	ds_bpermute_b32 v111, v149, v111
	v_add_f32_e32 v164, 1.0, v164
	v_add_f32_e32 v113, 1.0, v165
	s_waitcnt lgkmcnt(0)
	global_store_dwordx2 v[156:157], v[108:109], off
	global_store_dwordx2 v[156:157], v[110:111], off offset:32
	v_add_f32_e32 v108, 1.0, v166
	v_add_f32_e32 v109, 1.0, v167
	v_rcp_f32_e32 v112, v164
	v_rcp_f32_e32 v113, v113
	v_rcp_f32_e32 v108, v108
	v_rcp_f32_e32 v109, v109
	v_pk_mul_f32 v[102:103], v[102:103], v[152:153] op_sel_hi:[1,0]
	v_pk_mul_f32 v[100:101], v[100:101], v[152:153] op_sel_hi:[1,0]
	v_pk_mul_f32 v[110:111], v[116:117], v[112:113]
	v_pk_mul_f32 v[108:109], v[118:119], v[108:109]
	v_pk_mul_f32 v[100:101], v[100:101], v[110:111]
	v_pk_mul_f32 v[102:103], v[102:103], v[108:109]
	v_cvt_pk_bf16_f32 v100, v100, v101
	v_cvt_pk_bf16_f32 v101, v102, v103
	v_pk_mul_f32 v[102:103], v[106:107], v[152:153] op_sel_hi:[1,0]
	v_pk_mul_f32 v[104:105], v[104:105], v[152:153] op_sel_hi:[1,0]
	v_mul_f32_e32 v108, 0xbfb8aa3b, v102
	v_mul_f32_e32 v106, 0xbfb8aa3b, v104
	v_mul_f32_e32 v107, 0xbfb8aa3b, v105
	v_mul_f32_e32 v109, 0xbfb8aa3b, v103
	v_exp_f32_e32 v106, v106
	v_exp_f32_e32 v107, v107
	v_exp_f32_e32 v108, v108
	v_exp_f32_e32 v109, v109
	v_add_f32_e32 v106, 1.0, v106
	v_add_f32_e32 v107, 1.0, v107
	v_add_f32_e32 v108, 1.0, v108
	v_add_f32_e32 v109, 1.0, v109
	v_rcp_f32_e32 v106, v106
	v_rcp_f32_e32 v107, v107
	v_rcp_f32_e32 v108, v108
	v_rcp_f32_e32 v109, v109
	v_pk_mul_f32 v[94:95], v[94:95], v[152:153] op_sel_hi:[1,0]
	v_pk_mul_f32 v[92:93], v[92:93], v[152:153] op_sel_hi:[1,0]
	v_pk_mul_f32 v[104:105], v[104:105], v[106:107]
	v_pk_mul_f32 v[102:103], v[102:103], v[108:109]
	v_pk_mul_f32 v[92:93], v[92:93], v[104:105]
	v_pk_mul_f32 v[94:95], v[94:95], v[102:103]
	ds_bpermute_b32 v100, v149, v100
	ds_bpermute_b32 v101, v149, v101
	v_cvt_pk_bf16_f32 v92, v92, v93
	v_cvt_pk_bf16_f32 v93, v94, v95
	ds_bpermute_b32 v92, v149, v92
	ds_bpermute_b32 v93, v149, v93
	v_mad_i64_i32 v[94:95], s[22:23], v153, s47, v[136:137]
	v_lshl_add_u64 v[94:95], v[94:95], 0, v[140:141]
	s_waitcnt lgkmcnt(2)
	global_store_dwordx2 v[94:95], v[100:101], off
	s_waitcnt lgkmcnt(0)
	global_store_dwordx2 v[94:95], v[92:93], off offset:32
	v_pk_mul_f32 v[92:93], v[98:99], v[150:151] op_sel_hi:[1,0]
	v_pk_mul_f32 v[94:95], v[96:97], v[150:151] op_sel_hi:[1,0]
	v_mul_f32_e32 v98, 0xbfb8aa3b, v92
	v_mul_f32_e32 v96, 0xbfb8aa3b, v94
	v_mul_f32_e32 v97, 0xbfb8aa3b, v95
	v_mul_f32_e32 v99, 0xbfb8aa3b, v93
	v_exp_f32_e32 v96, v96
	v_exp_f32_e32 v97, v97
	v_exp_f32_e32 v98, v98
	v_exp_f32_e32 v99, v99
	v_add_f32_e32 v96, 1.0, v96
	v_add_f32_e32 v97, 1.0, v97
	v_add_f32_e32 v98, 1.0, v98
	v_add_f32_e32 v99, 1.0, v99
	v_rcp_f32_e32 v96, v96
	v_rcp_f32_e32 v97, v97
	v_rcp_f32_e32 v98, v98
	v_rcp_f32_e32 v99, v99
	v_pk_mul_f32 v[86:87], v[86:87], v[150:151] op_sel_hi:[1,0]
	v_pk_mul_f32 v[84:85], v[84:85], v[150:151] op_sel_hi:[1,0]
	v_pk_mul_f32 v[94:95], v[94:95], v[96:97]
	v_pk_mul_f32 v[92:93], v[92:93], v[98:99]
	v_pk_mul_f32 v[84:85], v[84:85], v[94:95]
	v_pk_mul_f32 v[86:87], v[86:87], v[92:93]
	v_cvt_pk_bf16_f32 v84, v84, v85
	v_cvt_pk_bf16_f32 v85, v86, v87
	v_pk_mul_f32 v[86:87], v[90:91], v[150:151] op_sel_hi:[1,0]
	v_pk_mul_f32 v[88:89], v[88:89], v[150:151] op_sel_hi:[1,0]
	v_mul_f32_e32 v92, 0xbfb8aa3b, v86
	v_mul_f32_e32 v90, 0xbfb8aa3b, v88
	v_mul_f32_e32 v91, 0xbfb8aa3b, v89
	v_mul_f32_e32 v93, 0xbfb8aa3b, v87
	v_exp_f32_e32 v90, v90
	v_exp_f32_e32 v91, v91
	v_exp_f32_e32 v92, v92
	v_exp_f32_e32 v93, v93
	v_add_f32_e32 v90, 1.0, v90
	v_add_f32_e32 v91, 1.0, v91
	v_add_f32_e32 v92, 1.0, v92
	v_add_f32_e32 v93, 1.0, v93
	v_rcp_f32_e32 v90, v90
	v_rcp_f32_e32 v91, v91
	v_rcp_f32_e32 v92, v92
	v_rcp_f32_e32 v93, v93
	v_pk_mul_f32 v[78:79], v[78:79], v[150:151] op_sel_hi:[1,0]
	v_pk_mul_f32 v[76:77], v[76:77], v[150:151] op_sel_hi:[1,0]
	v_pk_mul_f32 v[88:89], v[88:89], v[90:91]
	v_pk_mul_f32 v[86:87], v[86:87], v[92:93]
	v_pk_mul_f32 v[76:77], v[76:77], v[88:89]
	v_pk_mul_f32 v[78:79], v[78:79], v[86:87]
	ds_bpermute_b32 v84, v149, v84
	ds_bpermute_b32 v85, v149, v85
	v_cvt_pk_bf16_f32 v76, v76, v77
	v_cvt_pk_bf16_f32 v77, v78, v79
	ds_bpermute_b32 v76, v149, v76
	ds_bpermute_b32 v77, v149, v77
	v_add_u32_e32 v100, 32, v151
	v_mad_i64_i32 v[78:79], s[22:23], v100, s47, v[136:137]
	v_lshl_add_u64 v[78:79], v[78:79], 0, v[140:141]
	s_waitcnt lgkmcnt(2)
	global_store_dwordx2 v[78:79], v[84:85], off
	s_waitcnt lgkmcnt(0)
	global_store_dwordx2 v[78:79], v[76:77], off offset:32
	v_pk_mul_f32 v[76:77], v[82:83], v[148:149] op_sel_hi:[1,0]
	v_pk_mul_f32 v[78:79], v[80:81], v[148:149] op_sel_hi:[1,0]
	v_mul_f32_e32 v82, 0xbfb8aa3b, v76
	v_mul_f32_e32 v80, 0xbfb8aa3b, v78
	v_mul_f32_e32 v81, 0xbfb8aa3b, v79
	v_mul_f32_e32 v83, 0xbfb8aa3b, v77
	v_exp_f32_e32 v80, v80
	v_exp_f32_e32 v81, v81
	v_exp_f32_e32 v82, v82
	v_exp_f32_e32 v83, v83
	v_add_f32_e32 v80, 1.0, v80
	v_add_f32_e32 v81, 1.0, v81
	v_add_f32_e32 v82, 1.0, v82
	v_add_f32_e32 v83, 1.0, v83
	v_rcp_f32_e32 v80, v80
	v_rcp_f32_e32 v81, v81
	v_rcp_f32_e32 v82, v82
	v_rcp_f32_e32 v83, v83
	v_pk_mul_f32 v[70:71], v[70:71], v[148:149] op_sel_hi:[1,0]
	v_pk_mul_f32 v[68:69], v[68:69], v[148:149] op_sel_hi:[1,0]
	v_pk_mul_f32 v[78:79], v[78:79], v[80:81]
	v_pk_mul_f32 v[76:77], v[76:77], v[82:83]
	v_pk_mul_f32 v[68:69], v[68:69], v[78:79]
	v_pk_mul_f32 v[70:71], v[70:71], v[76:77]
	v_cvt_pk_bf16_f32 v68, v68, v69
	v_cvt_pk_bf16_f32 v69, v70, v71
	v_pk_mul_f32 v[70:71], v[74:75], v[148:149] op_sel_hi:[1,0]
	v_pk_mul_f32 v[72:73], v[72:73], v[148:149] op_sel_hi:[1,0]
	v_mul_f32_e32 v76, 0xbfb8aa3b, v70
	v_mul_f32_e32 v74, 0xbfb8aa3b, v72
	v_mul_f32_e32 v75, 0xbfb8aa3b, v73
	v_mul_f32_e32 v77, 0xbfb8aa3b, v71
	v_exp_f32_e32 v74, v74
	v_exp_f32_e32 v75, v75
	v_exp_f32_e32 v76, v76
	v_exp_f32_e32 v77, v77
	v_add_f32_e32 v74, 1.0, v74
	v_add_f32_e32 v75, 1.0, v75
	v_add_f32_e32 v76, 1.0, v76
	v_add_f32_e32 v77, 1.0, v77
	v_rcp_f32_e32 v74, v74
	v_rcp_f32_e32 v75, v75
	v_rcp_f32_e32 v76, v76
	v_rcp_f32_e32 v77, v77
	v_pk_mul_f32 v[66:67], v[66:67], v[148:149] op_sel_hi:[1,0]
	v_pk_mul_f32 v[64:65], v[64:65], v[148:149] op_sel_hi:[1,0]
	v_pk_mul_f32 v[72:73], v[72:73], v[74:75]
	v_pk_mul_f32 v[70:71], v[70:71], v[76:77]
	v_pk_mul_f32 v[64:65], v[64:65], v[72:73]
	v_pk_mul_f32 v[66:67], v[66:67], v[70:71]
	ds_bpermute_b32 v68, v149, v68
	ds_bpermute_b32 v69, v149, v69
	v_cvt_pk_bf16_f32 v64, v64, v65
	v_cvt_pk_bf16_f32 v65, v66, v67
	ds_bpermute_b32 v64, v149, v64
	ds_bpermute_b32 v65, v149, v65
	v_add_u32_e32 v84, 48, v151
	v_mad_i64_i32 v[66:67], s[22:23], v84, s47, v[136:137]
	v_lshl_add_u64 v[66:67], v[66:67], 0, v[140:141]
	v_pk_mul_f32 v[60:61], v[60:61], v[146:147] op_sel_hi:[1,0]
	s_waitcnt lgkmcnt(2)
	global_store_dwordx2 v[66:67], v[68:69], off
	s_waitcnt lgkmcnt(0)
	global_store_dwordx2 v[66:67], v[64:65], off offset:32
	v_pk_mul_f32 v[62:63], v[62:63], v[146:147] op_sel_hi:[1,0]
	v_mul_f32_e32 v64, 0xbfb8aa3b, v60
	v_mul_f32_e32 v65, 0xbfb8aa3b, v61
	v_exp_f32_e32 v64, v64
	v_exp_f32_e32 v65, v65
	v_mul_f32_e32 v66, 0xbfb8aa3b, v62
	v_mul_f32_e32 v67, 0xbfb8aa3b, v63
	v_exp_f32_e32 v66, v66
	v_exp_f32_e32 v67, v67
	v_add_f32_e32 v64, 1.0, v64
	v_add_f32_e32 v65, 1.0, v65
	v_rcp_f32_e32 v64, v64
	v_rcp_f32_e32 v65, v65
	v_add_f32_e32 v66, 1.0, v66
	v_add_f32_e32 v67, 1.0, v67
	v_rcp_f32_e32 v66, v66
	v_rcp_f32_e32 v67, v67
	v_pk_mul_f32 v[52:53], v[52:53], v[146:147] op_sel_hi:[1,0]
	v_pk_mul_f32 v[60:61], v[60:61], v[64:65]
	v_pk_mul_f32 v[54:55], v[54:55], v[146:147] op_sel_hi:[1,0]
	v_pk_mul_f32 v[52:53], v[52:53], v[60:61]
	v_pk_mul_f32 v[60:61], v[62:63], v[66:67]
	v_cvt_pk_bf16_f32 v52, v52, v53
	v_pk_mul_f32 v[54:55], v[54:55], v[60:61]
	v_pk_mul_f32 v[56:57], v[56:57], v[146:147] op_sel_hi:[1,0]
	v_cvt_pk_bf16_f32 v53, v54, v55
	v_pk_mul_f32 v[54:55], v[58:59], v[146:147] op_sel_hi:[1,0]
	v_mul_f32_e32 v58, 0xbfb8aa3b, v56
	v_mul_f32_e32 v59, 0xbfb8aa3b, v57
	v_mul_f32_e32 v60, 0xbfb8aa3b, v54
	v_mul_f32_e32 v61, 0xbfb8aa3b, v55
	v_exp_f32_e32 v58, v58
	v_exp_f32_e32 v59, v59
	v_exp_f32_e32 v60, v60
	v_exp_f32_e32 v61, v61
	v_add_f32_e32 v58, 1.0, v58
	v_add_f32_e32 v59, 1.0, v59
	v_add_f32_e32 v60, 1.0, v60
	v_add_f32_e32 v61, 1.0, v61
	v_rcp_f32_e32 v58, v58
	v_rcp_f32_e32 v59, v59
	v_rcp_f32_e32 v60, v60
	v_rcp_f32_e32 v61, v61
	v_pk_mul_f32 v[46:47], v[46:47], v[146:147] op_sel_hi:[1,0]
	v_pk_mul_f32 v[44:45], v[44:45], v[146:147] op_sel_hi:[1,0]
	v_pk_mul_f32 v[56:57], v[56:57], v[58:59]
	v_pk_mul_f32 v[54:55], v[54:55], v[60:61]
	v_pk_mul_f32 v[44:45], v[44:45], v[56:57]
	v_pk_mul_f32 v[46:47], v[46:47], v[54:55]
	ds_bpermute_b32 v52, v149, v52
	ds_bpermute_b32 v53, v149, v53
	v_cvt_pk_bf16_f32 v44, v44, v45
	v_cvt_pk_bf16_f32 v45, v46, v47
	ds_bpermute_b32 v44, v149, v44
	ds_bpermute_b32 v45, v149, v45
	v_add_u32_e32 v68, 0x80, v151
	v_mad_i64_i32 v[46:47], s[22:23], v68, s47, v[136:137]
	v_lshl_add_u64 v[46:47], v[46:47], 0, v[140:141]
	s_waitcnt lgkmcnt(2)
	global_store_dwordx2 v[46:47], v[52:53], off
	s_waitcnt lgkmcnt(0)
	global_store_dwordx2 v[46:47], v[44:45], off offset:32
	v_pk_mul_f32 v[44:45], v[50:51], v[144:145] op_sel_hi:[1,0]
	v_pk_mul_f32 v[46:47], v[48:49], v[144:145] op_sel_hi:[1,0]
	v_mul_f32_e32 v50, 0xbfb8aa3b, v44
	v_mul_f32_e32 v48, 0xbfb8aa3b, v46
	v_mul_f32_e32 v49, 0xbfb8aa3b, v47
	v_mul_f32_e32 v51, 0xbfb8aa3b, v45
	v_exp_f32_e32 v48, v48
	v_exp_f32_e32 v49, v49
	v_exp_f32_e32 v50, v50
	v_exp_f32_e32 v51, v51
	v_add_f32_e32 v48, 1.0, v48
	v_add_f32_e32 v49, 1.0, v49
	v_add_f32_e32 v50, 1.0, v50
	v_add_f32_e32 v51, 1.0, v51
	v_rcp_f32_e32 v48, v48
	v_rcp_f32_e32 v49, v49
	v_rcp_f32_e32 v50, v50
	v_rcp_f32_e32 v51, v51
	v_pk_mul_f32 v[38:39], v[38:39], v[144:145] op_sel_hi:[1,0]
	v_pk_mul_f32 v[36:37], v[36:37], v[144:145] op_sel_hi:[1,0]
	v_pk_mul_f32 v[46:47], v[46:47], v[48:49]
	v_pk_mul_f32 v[44:45], v[44:45], v[50:51]
	v_pk_mul_f32 v[36:37], v[36:37], v[46:47]
	v_pk_mul_f32 v[38:39], v[38:39], v[44:45]
	v_cvt_pk_bf16_f32 v36, v36, v37
	v_cvt_pk_bf16_f32 v37, v38, v39
	v_pk_mul_f32 v[38:39], v[42:43], v[144:145] op_sel_hi:[1,0]
	v_pk_mul_f32 v[40:41], v[40:41], v[144:145] op_sel_hi:[1,0]
	v_mul_f32_e32 v44, 0xbfb8aa3b, v38
	v_mul_f32_e32 v42, 0xbfb8aa3b, v40
	v_mul_f32_e32 v43, 0xbfb8aa3b, v41
	v_mul_f32_e32 v45, 0xbfb8aa3b, v39
	v_exp_f32_e32 v42, v42
	v_exp_f32_e32 v43, v43
	v_exp_f32_e32 v44, v44
	v_exp_f32_e32 v45, v45
	v_add_f32_e32 v42, 1.0, v42
	v_add_f32_e32 v43, 1.0, v43
	v_add_f32_e32 v44, 1.0, v44
	v_add_f32_e32 v45, 1.0, v45
	v_rcp_f32_e32 v42, v42
	v_rcp_f32_e32 v43, v43
	v_rcp_f32_e32 v44, v44
	v_rcp_f32_e32 v45, v45
	v_pk_mul_f32 v[30:31], v[30:31], v[144:145] op_sel_hi:[1,0]
	v_pk_mul_f32 v[28:29], v[28:29], v[144:145] op_sel_hi:[1,0]
	v_pk_mul_f32 v[40:41], v[40:41], v[42:43]
	v_pk_mul_f32 v[38:39], v[38:39], v[44:45]
	v_pk_mul_f32 v[28:29], v[28:29], v[40:41]
	v_pk_mul_f32 v[30:31], v[30:31], v[38:39]
	ds_bpermute_b32 v36, v149, v36
	ds_bpermute_b32 v37, v149, v37
	v_cvt_pk_bf16_f32 v28, v28, v29
	v_cvt_pk_bf16_f32 v29, v30, v31
	ds_bpermute_b32 v28, v149, v28
	ds_bpermute_b32 v29, v149, v29
	v_add_u32_e32 v52, 0x90, v151
	v_mad_i64_i32 v[30:31], s[22:23], v52, s47, v[136:137]
	v_lshl_add_u64 v[30:31], v[30:31], 0, v[140:141]
	s_waitcnt lgkmcnt(2)
	global_store_dwordx2 v[30:31], v[36:37], off
	s_waitcnt lgkmcnt(0)
	global_store_dwordx2 v[30:31], v[28:29], off offset:32
	v_pk_mul_f32 v[28:29], v[34:35], v[142:143] op_sel_hi:[1,0]
	v_pk_mul_f32 v[30:31], v[32:33], v[142:143] op_sel_hi:[1,0]
	v_mul_f32_e32 v34, 0xbfb8aa3b, v28
	v_mul_f32_e32 v32, 0xbfb8aa3b, v30
	v_mul_f32_e32 v33, 0xbfb8aa3b, v31
	v_mul_f32_e32 v35, 0xbfb8aa3b, v29
	v_exp_f32_e32 v32, v32
	v_exp_f32_e32 v33, v33
	v_exp_f32_e32 v34, v34
	v_exp_f32_e32 v35, v35
	v_add_f32_e32 v32, 1.0, v32
	v_add_f32_e32 v33, 1.0, v33
	v_add_f32_e32 v34, 1.0, v34
	v_add_f32_e32 v35, 1.0, v35
	v_rcp_f32_e32 v32, v32
	v_rcp_f32_e32 v33, v33
	v_rcp_f32_e32 v34, v34
	v_rcp_f32_e32 v35, v35
	v_pk_mul_f32 v[22:23], v[22:23], v[142:143] op_sel_hi:[1,0]
	v_pk_mul_f32 v[20:21], v[20:21], v[142:143] op_sel_hi:[1,0]
	v_pk_mul_f32 v[30:31], v[30:31], v[32:33]
	v_pk_mul_f32 v[28:29], v[28:29], v[34:35]
	v_pk_mul_f32 v[20:21], v[20:21], v[30:31]
	v_pk_mul_f32 v[22:23], v[22:23], v[28:29]
	v_cvt_pk_bf16_f32 v20, v20, v21
	v_cvt_pk_bf16_f32 v21, v22, v23
	v_pk_mul_f32 v[22:23], v[26:27], v[142:143] op_sel_hi:[1,0]
	v_pk_mul_f32 v[24:25], v[24:25], v[142:143] op_sel_hi:[1,0]
	v_mul_f32_e32 v28, 0xbfb8aa3b, v22
	v_mul_f32_e32 v26, 0xbfb8aa3b, v24
	v_mul_f32_e32 v27, 0xbfb8aa3b, v25
	v_mul_f32_e32 v29, 0xbfb8aa3b, v23
	v_exp_f32_e32 v26, v26
	v_exp_f32_e32 v27, v27
	v_exp_f32_e32 v28, v28
	v_exp_f32_e32 v29, v29
	v_add_f32_e32 v26, 1.0, v26
	v_add_f32_e32 v27, 1.0, v27
	v_add_f32_e32 v28, 1.0, v28
	v_add_f32_e32 v29, 1.0, v29
	v_rcp_f32_e32 v26, v26
	v_rcp_f32_e32 v27, v27
	v_rcp_f32_e32 v28, v28
	v_rcp_f32_e32 v29, v29
	v_pk_mul_f32 v[14:15], v[14:15], v[142:143] op_sel_hi:[1,0]
	v_pk_mul_f32 v[12:13], v[12:13], v[142:143] op_sel_hi:[1,0]
	v_pk_mul_f32 v[24:25], v[24:25], v[26:27]
	v_pk_mul_f32 v[22:23], v[22:23], v[28:29]
	v_pk_mul_f32 v[12:13], v[12:13], v[24:25]
	v_pk_mul_f32 v[14:15], v[14:15], v[22:23]
	ds_bpermute_b32 v20, v149, v20
	ds_bpermute_b32 v21, v149, v21
	v_cvt_pk_bf16_f32 v12, v12, v13
	v_cvt_pk_bf16_f32 v13, v14, v15
	ds_bpermute_b32 v12, v149, v12
	ds_bpermute_b32 v13, v149, v13
	v_add_u32_e32 v36, 0xa0, v151
	v_mad_i64_i32 v[14:15], s[22:23], v36, s47, v[136:137]
	v_lshl_add_u64 v[14:15], v[14:15], 0, v[140:141]
	s_waitcnt lgkmcnt(2)
	global_store_dwordx2 v[14:15], v[20:21], off
	s_waitcnt lgkmcnt(0)
	global_store_dwordx2 v[14:15], v[12:13], off offset:32
	v_pk_mul_f32 v[12:13], v[18:19], v[138:139] op_sel_hi:[1,0]
	v_pk_mul_f32 v[14:15], v[16:17], v[138:139] op_sel_hi:[1,0]
	v_mul_f32_e32 v18, 0xbfb8aa3b, v12
	v_mul_f32_e32 v16, 0xbfb8aa3b, v14
	v_mul_f32_e32 v17, 0xbfb8aa3b, v15
	v_mul_f32_e32 v19, 0xbfb8aa3b, v13
	v_exp_f32_e32 v16, v16
	v_exp_f32_e32 v17, v17
	v_exp_f32_e32 v18, v18
	v_exp_f32_e32 v19, v19
	v_add_f32_e32 v16, 1.0, v16
	v_add_f32_e32 v17, 1.0, v17
	v_add_f32_e32 v18, 1.0, v18
	v_add_f32_e32 v19, 1.0, v19
	v_rcp_f32_e32 v16, v16
	v_rcp_f32_e32 v17, v17
	v_rcp_f32_e32 v18, v18
	v_rcp_f32_e32 v19, v19
	v_pk_mul_f32 v[6:7], v[6:7], v[138:139] op_sel_hi:[1,0]
	v_pk_mul_f32 v[4:5], v[4:5], v[138:139] op_sel_hi:[1,0]
	v_pk_mul_f32 v[14:15], v[14:15], v[16:17]
	v_pk_mul_f32 v[12:13], v[12:13], v[18:19]
	v_pk_mul_f32 v[4:5], v[4:5], v[14:15]
	v_pk_mul_f32 v[6:7], v[6:7], v[12:13]
	v_cvt_pk_bf16_f32 v4, v4, v5
	v_cvt_pk_bf16_f32 v5, v6, v7
	v_pk_mul_f32 v[6:7], v[10:11], v[138:139] op_sel_hi:[1,0]
	v_pk_mul_f32 v[8:9], v[8:9], v[138:139] op_sel_hi:[1,0]
	v_mul_f32_e32 v12, 0xbfb8aa3b, v6
	v_mul_f32_e32 v10, 0xbfb8aa3b, v8
	v_mul_f32_e32 v11, 0xbfb8aa3b, v9
	v_mul_f32_e32 v13, 0xbfb8aa3b, v7
	v_exp_f32_e32 v10, v10
	v_exp_f32_e32 v11, v11
	v_exp_f32_e32 v12, v12
	v_exp_f32_e32 v13, v13
	v_add_f32_e32 v10, 1.0, v10
	v_add_f32_e32 v11, 1.0, v11
	v_add_f32_e32 v12, 1.0, v12
	v_add_f32_e32 v13, 1.0, v13
	v_rcp_f32_e32 v10, v10
	v_rcp_f32_e32 v11, v11
	v_rcp_f32_e32 v12, v12
	v_rcp_f32_e32 v13, v13
	v_pk_mul_f32 v[2:3], v[2:3], v[138:139] op_sel_hi:[1,0]
	v_pk_mul_f32 v[0:1], v[0:1], v[138:139] op_sel_hi:[1,0]
	v_pk_mul_f32 v[8:9], v[8:9], v[10:11]
	v_pk_mul_f32 v[6:7], v[6:7], v[12:13]
	v_pk_mul_f32 v[0:1], v[0:1], v[8:9]
	v_pk_mul_f32 v[2:3], v[2:3], v[6:7]
	ds_bpermute_b32 v4, v149, v4
	ds_bpermute_b32 v5, v149, v5
	v_cvt_pk_bf16_f32 v0, v0, v1
	v_cvt_pk_bf16_f32 v1, v2, v3
	ds_bpermute_b32 v0, v149, v0
	ds_bpermute_b32 v1, v149, v1
	v_add_u32_e32 v20, 0xb0, v151
	v_mad_i64_i32 v[2:3], s[22:23], v20, s47, v[136:137]
	v_lshl_add_u64 v[2:3], v[2:3], 0, v[140:141]
	s_mov_b64 s[22:23], s[16:17]
	s_waitcnt lgkmcnt(2)
	global_store_dwordx2 v[2:3], v[4:5], off
	s_waitcnt lgkmcnt(0)
	global_store_dwordx2 v[2:3], v[0:1], off offset:32
	s_cbranch_vccz .LBB0_1164
	s_waitcnt vmcnt(0)
	s_cmpk_gt_u32 s28, 0xff
	s_cbranch_scc1 .LBB0_1171
	s_barrier

.LBB0_1257:
	s_add_i32 s13, s51, -2
	s_add_u32 s16, s16, 0x160080
	s_addc_u32 s17, s17, 0
	s_add_u32 s52, s18, 0x100
	v_mov_b32_e32 v0, 0
	s_addc_u32 s53, s19, 0
	s_mov_b32 s18, 0
	v_mov_b32_e32 v1, v0
	v_mov_b32_e32 v2, v0
	v_mov_b32_e32 v3, v0
	v_mov_b32_e32 v4, v0
	v_mov_b32_e32 v5, v0
	v_mov_b32_e32 v6, v0
	v_mov_b32_e32 v7, v0
	v_mov_b32_e32 v12, v0
	v_mov_b32_e32 v13, v0
	v_mov_b32_e32 v14, v0
	v_mov_b32_e32 v15, v0
	v_mov_b32_e32 v16, v0
	v_mov_b32_e32 v17, v0
	v_mov_b32_e32 v18, v0
	v_mov_b32_e32 v19, v0
	v_mov_b32_e32 v28, v0
	v_mov_b32_e32 v29, v0
	v_mov_b32_e32 v30, v0
	v_mov_b32_e32 v31, v0
	v_mov_b32_e32 v32, v0
	v_mov_b32_e32 v33, v0
	v_mov_b32_e32 v34, v0
	v_mov_b32_e32 v35, v0
	v_mov_b32_e32 v44, v0
	v_mov_b32_e32 v45, v0
	v_mov_b32_e32 v46, v0
	v_mov_b32_e32 v47, v0
	v_mov_b32_e32 v48, v0
	v_mov_b32_e32 v49, v0
	v_mov_b32_e32 v50, v0
	v_mov_b32_e32 v51, v0
	v_mov_b32_e32 v8, v0
	v_mov_b32_e32 v9, v0
	v_mov_b32_e32 v10, v0
	v_mov_b32_e32 v11, v0
	v_mov_b32_e32 v20, v0
	v_mov_b32_e32 v21, v0
	v_mov_b32_e32 v22, v0
	v_mov_b32_e32 v23, v0
	v_mov_b32_e32 v24, v0
	v_mov_b32_e32 v25, v0
	v_mov_b32_e32 v26, v0
	v_mov_b32_e32 v27, v0
	v_mov_b32_e32 v36, v0
	v_mov_b32_e32 v37, v0
	v_mov_b32_e32 v38, v0
	v_mov_b32_e32 v39, v0
	v_mov_b32_e32 v40, v0
	v_mov_b32_e32 v41, v0
	v_mov_b32_e32 v42, v0
	v_mov_b32_e32 v43, v0
	v_mov_b32_e32 v52, v0
	v_mov_b32_e32 v53, v0
	v_mov_b32_e32 v54, v0
	v_mov_b32_e32 v55, v0
	v_mov_b32_e32 v56, v0
	v_mov_b32_e32 v57, v0
	v_mov_b32_e32 v58, v0
	v_mov_b32_e32 v59, v0
	v_mov_b32_e32 v60, v0
	v_mov_b32_e32 v61, v0
	v_mov_b32_e32 v62, v0
	v_mov_b32_e32 v63, v0
	v_mov_b32_e32 v64, v0
	v_mov_b32_e32 v65, v0
	v_mov_b32_e32 v66, v0
	v_mov_b32_e32 v67, v0
	v_mov_b32_e32 v68, v0
	v_mov_b32_e32 v69, v0
	v_mov_b32_e32 v70, v0
	v_mov_b32_e32 v71, v0
	v_mov_b32_e32 v76, v0
	v_mov_b32_e32 v77, v0
	v_mov_b32_e32 v78, v0
	v_mov_b32_e32 v79, v0
	v_mov_b32_e32 v84, v0
	v_mov_b32_e32 v85, v0
	v_mov_b32_e32 v86, v0
	v_mov_b32_e32 v87, v0
	v_mov_b32_e32 v92, v0
	v_mov_b32_e32 v93, v0
	v_mov_b32_e32 v94, v0
	v_mov_b32_e32 v95, v0
	v_mov_b32_e32 v100, v0
	v_mov_b32_e32 v101, v0
	v_mov_b32_e32 v102, v0
	v_mov_b32_e32 v103, v0
	v_mov_b32_e32 v108, v0
	v_mov_b32_e32 v109, v0
	v_mov_b32_e32 v110, v0
	v_mov_b32_e32 v111, v0
	v_mov_b32_e32 v112, v0
	v_mov_b32_e32 v113, v0
	v_mov_b32_e32 v114, v0
	v_mov_b32_e32 v115, v0
	v_mov_b32_e32 v72, v0
	v_mov_b32_e32 v73, v0
	v_mov_b32_e32 v74, v0
	v_mov_b32_e32 v75, v0
	v_mov_b32_e32 v80, v0
	v_mov_b32_e32 v81, v0
	v_mov_b32_e32 v82, v0
	v_mov_b32_e32 v83, v0
	v_mov_b32_e32 v88, v0
	v_mov_b32_e32 v89, v0
	v_mov_b32_e32 v90, v0
	v_mov_b32_e32 v91, v0
	v_mov_b32_e32 v96, v0
	v_mov_b32_e32 v97, v0
	v_mov_b32_e32 v98, v0
	v_mov_b32_e32 v99, v0
	v_mov_b32_e32 v104, v0
	v_mov_b32_e32 v105, v0
	v_mov_b32_e32 v106, v0
	v_mov_b32_e32 v107, v0
	v_mov_b32_e32 v116, v0
	v_mov_b32_e32 v117, v0
	v_mov_b32_e32 v118, v0
	v_mov_b32_e32 v119, v0
	v_mov_b32_e32 v120, v0
	v_mov_b32_e32 v121, v0
	v_mov_b32_e32 v122, v0
	v_mov_b32_e32 v123, v0
	v_mov_b32_e32 v124, v0
	v_mov_b32_e32 v125, v0
	v_mov_b32_e32 v126, v0
	v_mov_b32_e32 v127, v0
	v_readlane_b32 s70, v254, 44
	s_cmp_lt_u32 s70, 4
	s_cbranch_scc1 .Lsp_3
	s_setprio 1
.Lsp_3:
.LBB0_1258:
	ds_read_b128 v[128:131], v159
	ds_read_b128 v[132:135], v159 offset:1024
	ds_read_b128 v[136:139], v159 offset:2048
	ds_read_b128 v[150:153], v159 offset:3072
	s_add_i32 s54, s18, 2
	s_add_u32 s19, s16, 0xffea0080
	s_addc_u32 s20, s17, -1
	s_cmp_eq_u32 s13, s18
	s_cselect_b32 s18, s4, s52
	s_cselect_b32 s21, s15, s20
	s_cselect_b32 s20, s14, s19
	s_cselect_b32 s19, s5, s53
	v_lshl_add_u64 v[166:167], s[16:17], 0, v[146:147]
	s_add_i32 m0, s26, 0xc000
	ds_read_b128 v[154:157], v160
	ds_read_b128 v[162:165], v160 offset:1024
	ds_read_b128 v[172:175], v160 offset:2048
	ds_read_b128 v[176:179], v160 offset:3072
	ds_read_b128 v[180:183], v160 offset:4096
	ds_read_b128 v[184:187], v160 offset:5120
	ds_read_b128 v[188:191], v160 offset:6144
	ds_read_b128 v[192:195], v160 offset:7168
	global_load_lds_dwordx4 v[166:167], off
	v_lshl_add_u64 v[166:167], s[16:17], 0, v[148:149]
	s_add_i32 m0, s26, 0xe000
	s_nop 0
	global_load_lds_dwordx4 v[166:167], off
	s_waitcnt lgkmcnt(8)
	s_barrier
	s_waitcnt lgkmcnt(0)

	s_waitcnt lgkmcnt(0)
	v_mfma_f32_16x16x32_bf16 v[124:127], v[128:131], v[154:157], v[124:127]
	v_mfma_f32_16x16x32_bf16 v[120:123], v[136:139], v[154:157], v[120:123]
	v_mfma_f32_16x16x32_bf16 v[116:119], v[128:131], v[172:175], v[116:119]
	v_mfma_f32_16x16x32_bf16 v[104:107], v[136:139], v[172:175], v[104:107]
	v_mfma_f32_16x16x32_bf16 v[96:99], v[128:131], v[180:183], v[96:99]
	v_mfma_f32_16x16x32_bf16 v[88:91], v[136:139], v[180:183], v[88:91]
	v_mfma_f32_16x16x32_bf16 v[80:83], v[128:131], v[188:191], v[80:83]
	v_mfma_f32_16x16x32_bf16 v[72:75], v[136:139], v[188:191], v[72:75]
	v_mfma_f32_16x16x32_bf16 v[124:127], v[132:135], v[162:165], v[124:127]
	v_mfma_f32_16x16x32_bf16 v[120:123], v[150:153], v[162:165], v[120:123]
	v_mfma_f32_16x16x32_bf16 v[116:119], v[132:135], v[176:179], v[116:119]
	v_mfma_f32_16x16x32_bf16 v[104:107], v[150:153], v[176:179], v[104:107]
	v_mfma_f32_16x16x32_bf16 v[96:99], v[132:135], v[184:187], v[96:99]
	v_mfma_f32_16x16x32_bf16 v[88:91], v[150:153], v[184:187], v[88:91]
	v_mfma_f32_16x16x32_bf16 v[80:83], v[132:135], v[192:195], v[80:83]
	v_mfma_f32_16x16x32_bf16 v[72:75], v[150:153], v[192:195], v[72:75]

	s_barrier
	s_add_i32 s55, s35, s25
	v_lshl_add_u64 v[166:167], s[18:19], 0, v[140:141]
	s_mov_b32 m0, s55
	ds_read_b128 v[196:199], v161
	ds_read_b128 v[200:203], v161 offset:1024
	ds_read_b128 v[204:207], v161 offset:2048
	ds_read_b128 v[212:215], v161 offset:3072
	global_load_lds_dwordx4 v[166:167], off
	v_lshl_add_u64 v[208:209], s[18:19], 0, v[142:143]
	s_add_i32 m0, s55, 0x2000
	s_nop 0
	global_load_lds_dwordx4 v[208:209], off
	s_barrier
	s_waitcnt lgkmcnt(0)

	s_waitcnt lgkmcnt(0)
	v_mfma_f32_16x16x32_bf16 v[112:115], v[196:199], v[154:157], v[112:115]
	v_mfma_f32_16x16x32_bf16 v[108:111], v[204:207], v[154:157], v[108:111]
	v_mfma_f32_16x16x32_bf16 v[100:103], v[196:199], v[172:175], v[100:103]
	v_mfma_f32_16x16x32_bf16 v[92:95], v[204:207], v[172:175], v[92:95]
	v_mfma_f32_16x16x32_bf16 v[84:87], v[196:199], v[180:183], v[84:87]
	v_mfma_f32_16x16x32_bf16 v[76:79], v[204:207], v[180:183], v[76:79]
	v_mfma_f32_16x16x32_bf16 v[68:71], v[196:199], v[188:191], v[68:71]
	v_mfma_f32_16x16x32_bf16 v[64:67], v[204:207], v[188:191], v[64:67]
	v_mfma_f32_16x16x32_bf16 v[112:115], v[200:203], v[162:165], v[112:115]
	v_mfma_f32_16x16x32_bf16 v[108:111], v[212:215], v[162:165], v[108:111]
	v_mfma_f32_16x16x32_bf16 v[100:103], v[200:203], v[176:179], v[100:103]
	v_mfma_f32_16x16x32_bf16 v[92:95], v[212:215], v[176:179], v[92:95]
	v_mfma_f32_16x16x32_bf16 v[84:87], v[200:203], v[184:187], v[84:87]
	v_mfma_f32_16x16x32_bf16 v[76:79], v[212:215], v[184:187], v[76:79]
	v_mfma_f32_16x16x32_bf16 v[68:71], v[200:203], v[192:195], v[68:71]
	v_mfma_f32_16x16x32_bf16 v[64:67], v[212:215], v[192:195], v[64:67]

	s_mov_b32 m0, s26
	v_lshl_add_u64 v[216:217], s[20:21], 0, v[140:141]
	s_barrier
	ds_read_b128 v[154:157], v160 offset:16384
	ds_read_b128 v[162:165], v160 offset:17408
	ds_read_b128 v[172:175], v160 offset:18432
	ds_read_b128 v[176:179], v160 offset:19456
	ds_read_b128 v[180:183], v160 offset:20480
	ds_read_b128 v[184:187], v160 offset:21504
	ds_read_b128 v[188:191], v160 offset:22528
	ds_read_b128 v[192:195], v160 offset:23552
	global_load_lds_dwordx4 v[216:217], off
	v_lshl_add_u64 v[218:219], s[20:21], 0, v[142:143]
	s_mov_b32 m0, s27
	s_nop 0
	global_load_lds_dwordx4 v[218:219], off
	s_barrier
	s_waitcnt lgkmcnt(0)

	s_waitcnt lgkmcnt(0)
	v_mfma_f32_16x16x32_bf16 v[60:63], v[128:131], v[154:157], v[60:63]
	v_mfma_f32_16x16x32_bf16 v[56:59], v[136:139], v[154:157], v[56:59]
	v_mfma_f32_16x16x32_bf16 v[52:55], v[128:131], v[172:175], v[52:55]
	v_mfma_f32_16x16x32_bf16 v[40:43], v[136:139], v[172:175], v[40:43]
	v_mfma_f32_16x16x32_bf16 v[36:39], v[128:131], v[180:183], v[36:39]
	v_mfma_f32_16x16x32_bf16 v[24:27], v[136:139], v[180:183], v[24:27]
	v_mfma_f32_16x16x32_bf16 v[20:23], v[128:131], v[188:191], v[20:23]
	v_mfma_f32_16x16x32_bf16 v[8:11], v[136:139], v[188:191], v[8:11]
	v_mfma_f32_16x16x32_bf16 v[60:63], v[132:135], v[162:165], v[60:63]
	v_mfma_f32_16x16x32_bf16 v[56:59], v[150:153], v[162:165], v[56:59]
	v_mfma_f32_16x16x32_bf16 v[52:55], v[132:135], v[176:179], v[52:55]
	v_mfma_f32_16x16x32_bf16 v[40:43], v[150:153], v[176:179], v[40:43]
	v_mfma_f32_16x16x32_bf16 v[36:39], v[132:135], v[184:187], v[36:39]
	v_mfma_f32_16x16x32_bf16 v[24:27], v[150:153], v[184:187], v[24:27]
	v_mfma_f32_16x16x32_bf16 v[20:23], v[132:135], v[192:195], v[20:23]
	v_mfma_f32_16x16x32_bf16 v[8:11], v[150:153], v[192:195], v[8:11]

	s_barrier
	s_add_u32 s56, s18, 0x160000
	s_addc_u32 s57, s19, 0
	s_add_i32 s55, s36, s25
	v_lshl_add_u64 v[128:129], s[56:57], 0, v[140:141]
	s_mov_b32 m0, s55
	s_nop 0
	global_load_lds_dwordx4 v[128:129], off
	v_lshl_add_u64 v[128:129], s[56:57], 0, v[142:143]
	s_add_i32 m0, s55, 0x2000
	s_nop 0
	global_load_lds_dwordx4 v[128:129], off
	s_waitcnt vmcnt(6)
	s_barrier

	v_mfma_f32_16x16x32_bf16 v[48:51], v[196:199], v[154:157], v[48:51]
	v_mfma_f32_16x16x32_bf16 v[44:47], v[204:207], v[154:157], v[44:47]
	v_mfma_f32_16x16x32_bf16 v[32:35], v[196:199], v[172:175], v[32:35]
	v_mfma_f32_16x16x32_bf16 v[28:31], v[204:207], v[172:175], v[28:31]
	v_mfma_f32_16x16x32_bf16 v[16:19], v[196:199], v[180:183], v[16:19]
	v_mfma_f32_16x16x32_bf16 v[12:15], v[204:207], v[180:183], v[12:15]
	v_mfma_f32_16x16x32_bf16 v[4:7], v[196:199], v[188:191], v[4:7]
	v_mfma_f32_16x16x32_bf16 v[0:3], v[204:207], v[188:191], v[0:3]
	v_mfma_f32_16x16x32_bf16 v[48:51], v[200:203], v[162:165], v[48:51]
	v_mfma_f32_16x16x32_bf16 v[44:47], v[212:215], v[162:165], v[44:47]
	v_mfma_f32_16x16x32_bf16 v[32:35], v[200:203], v[176:179], v[32:35]
	v_mfma_f32_16x16x32_bf16 v[28:31], v[212:215], v[176:179], v[28:31]
	v_mfma_f32_16x16x32_bf16 v[16:19], v[200:203], v[184:187], v[16:19]
	v_mfma_f32_16x16x32_bf16 v[12:15], v[212:215], v[184:187], v[12:15]
	v_mfma_f32_16x16x32_bf16 v[4:7], v[200:203], v[192:195], v[4:7]
	v_mfma_f32_16x16x32_bf16 v[0:3], v[212:215], v[192:195], v[0:3]

	s_add_i32 s55, 0, 0x18000
	v_add_u32_e32 v144, s55, v158
	s_barrier
	ds_read_b128 v[128:131], v144
	ds_read_b128 v[132:135], v144 offset:1024
	ds_read_b128 v[136:139], v144 offset:2048
	ds_read_b128 v[150:153], v144 offset:3072
	s_add_u32 s20, s20, 0x160000
	s_addc_u32 s21, s21, 0
	s_mov_b32 m0, s28
	v_lshl_add_u64 v[196:197], s[20:21], 0, v[140:141]
	ds_read_b128 v[154:157], v160 offset:32768
	ds_read_b128 v[162:165], v160 offset:33792
	ds_read_b128 v[172:175], v160 offset:34816
	ds_read_b128 v[176:179], v160 offset:35840
	ds_read_b128 v[180:183], v160 offset:36864
	ds_read_b128 v[184:187], v160 offset:37888
	ds_read_b128 v[188:191], v160 offset:38912
	ds_read_b128 v[192:195], v160 offset:39936
	global_load_lds_dwordx4 v[196:197], off
	v_lshl_add_u64 v[196:197], s[20:21], 0, v[142:143]
	s_mov_b32 m0, s29
	s_nop 0
	global_load_lds_dwordx4 v[196:197], off
	s_waitcnt lgkmcnt(8)
	s_barrier
	s_waitcnt lgkmcnt(0)

	s_waitcnt lgkmcnt(0)
	v_mfma_f32_16x16x32_bf16 v[124:127], v[128:131], v[154:157], v[124:127]
	v_mfma_f32_16x16x32_bf16 v[120:123], v[136:139], v[154:157], v[120:123]
	v_mfma_f32_16x16x32_bf16 v[116:119], v[128:131], v[172:175], v[116:119]
	v_mfma_f32_16x16x32_bf16 v[104:107], v[136:139], v[172:175], v[104:107]
	v_mfma_f32_16x16x32_bf16 v[96:99], v[128:131], v[180:183], v[96:99]
	v_mfma_f32_16x16x32_bf16 v[88:91], v[136:139], v[180:183], v[88:91]
	v_mfma_f32_16x16x32_bf16 v[80:83], v[128:131], v[188:191], v[80:83]
	v_mfma_f32_16x16x32_bf16 v[72:75], v[136:139], v[188:191], v[72:75]
	v_mfma_f32_16x16x32_bf16 v[124:127], v[132:135], v[162:165], v[124:127]
	v_mfma_f32_16x16x32_bf16 v[120:123], v[150:153], v[162:165], v[120:123]
	v_mfma_f32_16x16x32_bf16 v[116:119], v[132:135], v[176:179], v[116:119]
	v_mfma_f32_16x16x32_bf16 v[104:107], v[150:153], v[176:179], v[104:107]
	v_mfma_f32_16x16x32_bf16 v[96:99], v[132:135], v[184:187], v[96:99]
	v_mfma_f32_16x16x32_bf16 v[88:91], v[150:153], v[184:187], v[88:91]
	v_mfma_f32_16x16x32_bf16 v[80:83], v[132:135], v[192:195], v[80:83]
	v_mfma_f32_16x16x32_bf16 v[72:75], v[150:153], v[192:195], v[72:75]

	s_barrier
	s_add_i32 s20, 0, 0x1c000
	s_add_i32 s21, s55, s25
	v_add_u32_e32 v144, s20, v158
	v_lshl_add_u64 v[166:167], v[166:167], 0, s[6:7]
	s_mov_b32 m0, s21
	ds_read_b128 v[196:199], v144
	ds_read_b128 v[200:203], v144 offset:1024
	ds_read_b128 v[204:207], v144 offset:2048
	ds_read_b128 v[212:215], v144 offset:3072
	global_load_lds_dwordx4 v[166:167], off
	v_lshl_add_u64 v[166:167], v[208:209], 0, s[6:7]
	s_add_i32 m0, s21, 0x2000
	s_nop 0
	global_load_lds_dwordx4 v[166:167], off
	s_barrier
	s_waitcnt lgkmcnt(0)

	s_waitcnt lgkmcnt(0)
	v_mfma_f32_16x16x32_bf16 v[112:115], v[196:199], v[154:157], v[112:115]
	v_mfma_f32_16x16x32_bf16 v[108:111], v[204:207], v[154:157], v[108:111]
	v_mfma_f32_16x16x32_bf16 v[100:103], v[196:199], v[172:175], v[100:103]
	v_mfma_f32_16x16x32_bf16 v[92:95], v[204:207], v[172:175], v[92:95]
	v_mfma_f32_16x16x32_bf16 v[84:87], v[196:199], v[180:183], v[84:87]
	v_mfma_f32_16x16x32_bf16 v[76:79], v[204:207], v[180:183], v[76:79]
	v_mfma_f32_16x16x32_bf16 v[68:71], v[196:199], v[188:191], v[68:71]
	v_mfma_f32_16x16x32_bf16 v[64:67], v[204:207], v[188:191], v[64:67]
	v_mfma_f32_16x16x32_bf16 v[112:115], v[200:203], v[162:165], v[112:115]
	v_mfma_f32_16x16x32_bf16 v[108:111], v[212:215], v[162:165], v[108:111]
	v_mfma_f32_16x16x32_bf16 v[100:103], v[200:203], v[176:179], v[100:103]
	v_mfma_f32_16x16x32_bf16 v[92:95], v[212:215], v[176:179], v[92:95]
	v_mfma_f32_16x16x32_bf16 v[84:87], v[200:203], v[184:187], v[84:87]
	v_mfma_f32_16x16x32_bf16 v[76:79], v[212:215], v[184:187], v[76:79]
	v_mfma_f32_16x16x32_bf16 v[68:71], v[200:203], v[192:195], v[68:71]
	v_mfma_f32_16x16x32_bf16 v[64:67], v[212:215], v[192:195], v[64:67]

	s_mov_b32 m0, s33
	v_lshl_add_u64 v[166:167], v[216:217], 0, s[6:7]
	s_barrier
	ds_read_b128 v[154:157], v160 offset:49152
	ds_read_b128 v[162:165], v160 offset:50176
	ds_read_b128 v[172:175], v160 offset:51200
	ds_read_b128 v[176:179], v160 offset:52224
	ds_read_b128 v[180:183], v160 offset:53248
	ds_read_b128 v[184:187], v160 offset:54272
	ds_read_b128 v[188:191], v160 offset:55296
	ds_read_b128 v[192:195], v160 offset:56320
	global_load_lds_dwordx4 v[166:167], off
	v_lshl_add_u64 v[166:167], v[218:219], 0, s[6:7]
	s_mov_b32 m0, s34
	s_nop 0
	global_load_lds_dwordx4 v[166:167], off
	s_barrier
	s_waitcnt lgkmcnt(0)

	s_waitcnt lgkmcnt(0)
	v_mfma_f32_16x16x32_bf16 v[60:63], v[128:131], v[154:157], v[60:63]
	v_mfma_f32_16x16x32_bf16 v[56:59], v[136:139], v[154:157], v[56:59]
	v_mfma_f32_16x16x32_bf16 v[52:55], v[128:131], v[172:175], v[52:55]
	v_mfma_f32_16x16x32_bf16 v[40:43], v[136:139], v[172:175], v[40:43]
	v_mfma_f32_16x16x32_bf16 v[36:39], v[128:131], v[180:183], v[36:39]
	v_mfma_f32_16x16x32_bf16 v[24:27], v[136:139], v[180:183], v[24:27]
	v_mfma_f32_16x16x32_bf16 v[20:23], v[128:131], v[188:191], v[20:23]
	v_mfma_f32_16x16x32_bf16 v[8:11], v[136:139], v[188:191], v[8:11]
	v_mfma_f32_16x16x32_bf16 v[60:63], v[132:135], v[162:165], v[60:63]
	v_mfma_f32_16x16x32_bf16 v[56:59], v[150:153], v[162:165], v[56:59]
	v_mfma_f32_16x16x32_bf16 v[52:55], v[132:135], v[176:179], v[52:55]
	v_mfma_f32_16x16x32_bf16 v[40:43], v[150:153], v[176:179], v[40:43]
	v_mfma_f32_16x16x32_bf16 v[36:39], v[132:135], v[184:187], v[36:39]
	v_mfma_f32_16x16x32_bf16 v[24:27], v[150:153], v[184:187], v[24:27]
	v_mfma_f32_16x16x32_bf16 v[20:23], v[132:135], v[192:195], v[20:23]
	v_mfma_f32_16x16x32_bf16 v[8:11], v[150:153], v[192:195], v[8:11]

	s_barrier
	s_add_u32 s18, s18, 0x160080
	s_addc_u32 s19, s19, 0
	s_add_i32 s20, s20, s25
	v_lshl_add_u64 v[128:129], s[18:19], 0, v[140:141]
	s_mov_b32 m0, s20
	s_nop 0
	global_load_lds_dwordx4 v[128:129], off
	v_lshl_add_u64 v[128:129], s[18:19], 0, v[142:143]
	s_add_i32 m0, s20, 0x2000
	s_nop 0
	global_load_lds_dwordx4 v[128:129], off
	s_waitcnt vmcnt(6)
	s_barrier

	v_mfma_f32_16x16x32_bf16 v[48:51], v[196:199], v[154:157], v[48:51]
	v_mfma_f32_16x16x32_bf16 v[44:47], v[204:207], v[154:157], v[44:47]
	v_mfma_f32_16x16x32_bf16 v[32:35], v[196:199], v[172:175], v[32:35]
	v_mfma_f32_16x16x32_bf16 v[28:31], v[204:207], v[172:175], v[28:31]
	v_mfma_f32_16x16x32_bf16 v[16:19], v[196:199], v[180:183], v[16:19]
	v_mfma_f32_16x16x32_bf16 v[12:15], v[204:207], v[180:183], v[12:15]
	v_mfma_f32_16x16x32_bf16 v[4:7], v[196:199], v[188:191], v[4:7]
	v_mfma_f32_16x16x32_bf16 v[0:3], v[204:207], v[188:191], v[0:3]
	v_mfma_f32_16x16x32_bf16 v[48:51], v[200:203], v[162:165], v[48:51]
	v_mfma_f32_16x16x32_bf16 v[44:47], v[212:215], v[162:165], v[44:47]
	v_mfma_f32_16x16x32_bf16 v[32:35], v[200:203], v[176:179], v[32:35]
	v_mfma_f32_16x16x32_bf16 v[28:31], v[212:215], v[176:179], v[28:31]
	v_mfma_f32_16x16x32_bf16 v[16:19], v[200:203], v[184:187], v[16:19]
	v_mfma_f32_16x16x32_bf16 v[12:15], v[212:215], v[184:187], v[12:15]
	v_mfma_f32_16x16x32_bf16 v[4:7], v[200:203], v[192:195], v[4:7]
	v_mfma_f32_16x16x32_bf16 v[0:3], v[212:215], v[192:195], v[0:3]

	s_add_u32 s16, s16, 0x100
	s_addc_u32 s17, s17, 0
	s_add_u32 s52, s52, 0x100
	s_addc_u32 s53, s53, 0
	s_cmp_ge_i32 s54, s51
	s_mov_b32 s18, s54
	s_barrier
	s_cbranch_scc0 .LBB0_1258
	s_setprio 0
	v_mov_b32_e32 v128, v210
	v_mov_b32_e32 v129, v169
	s_mov_b64 s[16:17], -1
	v_lshl_add_u32 v128, v128, 4, v129
	v_ashrrev_i32_e32 v150, 2, v128
	v_and_b32_e32 v129, 3, v129
	v_and_b32_e32 v128, -4, v128
	v_lshl_add_u32 v162, v129, 6, v128
	s_cmp_lt_i32 s2, 0
	v_lshlrev_b32_e32 v144, 4, v129
	s_cbranch_scc0 .LBB0_1261
	s_lshl_b32 s13, s50, 8
	s_add_i32 s13, s13, s30
	v_add_u32_e32 v128, s13, v150
	v_ashrrev_i32_e32 v129, 31, v128
	v_readlane_b32 s52, v254, 22
	v_lshlrev_b64 v[128:129], 13, v[128:129]
	v_readlane_b32 s66, v254, 36
	v_readlane_b32 s67, v254, 37
	s_lshl_b32 s16, s49, 8
	s_ashr_i32 s17, s16, 31
	v_lshl_add_u64 v[128:129], s[66:67], 0, v[128:129]
	v_lshl_add_u64 v[128:129], s[16:17], 2, v[128:129]
	s_lshl_b32 s16, s31, 2
	s_mov_b32 s17, s3
	v_lshl_add_u64 v[128:129], v[128:129], 0, s[16:17]
	v_lshl_add_u64 v[152:153], v[128:129], 0, v[144:145]
	global_load_dwordx4 v[164:167], v[152:153], off
	global_load_dwordx4 v[172:175], v[152:153], off offset:64
	global_load_dwordx4 v[176:179], v[152:153], off offset:512
	global_load_dwordx4 v[180:183], v[152:153], off offset:576
	v_add_co_u32_e32 v136, vcc, s37, v152
	ds_bpermute_b32 v138, v162, v124
	s_nop 0
	v_addc_co_u32_e32 v137, vcc, 0, v153, vcc
	global_load_dwordx4 v[184:187], v[136:137], off
	global_load_dwordx4 v[188:191], v[136:137], off offset:64
	global_load_dwordx4 v[192:195], v[136:137], off offset:512
	global_load_dwordx4 v[132:135], v[136:137], off offset:576
	v_add_co_u32_e32 v208, vcc, s38, v152
	ds_bpermute_b32 v139, v162, v125
	s_nop 0
	v_addc_co_u32_e32 v209, vcc, 0, v153, vcc
	global_load_dwordx4 v[196:199], v[208:209], off
	global_load_dwordx4 v[200:203], v[208:209], off offset:64
	global_load_dwordx4 v[204:207], v[208:209], off offset:512
	global_load_dwordx4 v[212:215], v[208:209], off offset:576
	v_add_co_u32_e32 v154, vcc, s39, v152
	ds_bpermute_b32 v156, v162, v126
	s_nop 0
	v_addc_co_u32_e32 v155, vcc, 0, v153, vcc
	global_load_dwordx4 v[216:219], v[154:155], off
	global_load_dwordx4 v[220:223], v[154:155], off offset:64
	global_load_dwordx4 v[224:227], v[154:155], off offset:512
	global_load_dwordx4 v[128:131], v[154:155], off offset:576
	ds_bpermute_b32 v157, v162, v127
	ds_bpermute_b32 v228, v162, v120
	ds_bpermute_b32 v229, v162, v121
	ds_bpermute_b32 v230, v162, v122
	ds_bpermute_b32 v231, v162, v123
	ds_bpermute_b32 v232, v162, v112
	ds_bpermute_b32 v233, v162, v113
	ds_bpermute_b32 v234, v162, v114
	ds_bpermute_b32 v235, v162, v115
	ds_bpermute_b32 v236, v162, v108
	ds_bpermute_b32 v237, v162, v109
	ds_bpermute_b32 v238, v162, v110
	ds_bpermute_b32 v239, v162, v111
	ds_bpermute_b32 v240, v162, v116
	ds_bpermute_b32 v241, v162, v117
	ds_bpermute_b32 v242, v162, v118
	ds_bpermute_b32 v243, v162, v119
	ds_bpermute_b32 v244, v162, v104
	ds_bpermute_b32 v245, v162, v105
	ds_bpermute_b32 v246, v162, v106
	ds_bpermute_b32 v247, v162, v107
	ds_bpermute_b32 v248, v162, v100
	ds_bpermute_b32 v249, v162, v101
	ds_bpermute_b32 v250, v162, v102
	ds_bpermute_b32 v251, v162, v103
	ds_bpermute_b32 v252, v162, v94
	ds_bpermute_b32 v253, v162, v95
	v_readlane_b32 s53, v254, 23
	v_readlane_b32 s54, v254, 24
	v_readlane_b32 s55, v254, 25
	v_readlane_b32 s56, v254, 26
	v_readlane_b32 s57, v254, 27
	v_readlane_b32 s58, v254, 28
	v_readlane_b32 s59, v254, 29
	v_readlane_b32 s60, v254, 30
	v_readlane_b32 s61, v254, 31
	v_readlane_b32 s62, v254, 32
	v_readlane_b32 s63, v254, 33
	v_readlane_b32 s64, v254, 34
	v_readlane_b32 s65, v254, 35
	s_mov_b64 s[16:17], 0
	s_waitcnt vmcnt(0) lgkmcnt(0)
	v_pk_add_f32 v[164:165], v[164:165], v[138:139]
	ds_bpermute_b32 v138, v162, v92
	ds_bpermute_b32 v139, v162, v93
	v_pk_add_f32 v[166:167], v[166:167], v[156:157]
	v_pk_add_f32 v[172:173], v[172:173], v[228:229]
	v_pk_add_f32 v[174:175], v[174:175], v[230:231]
	v_pk_add_f32 v[178:179], v[178:179], v[234:235]
	v_pk_add_f32 v[176:177], v[176:177], v[232:233]
	v_pk_add_f32 v[182:183], v[182:183], v[238:239]
	v_pk_add_f32 v[180:181], v[180:181], v[236:237]
	global_store_dwordx4 v[152:153], v[164:167], off
	global_store_dwordx4 v[152:153], v[172:175], off offset:64
	global_store_dwordx4 v[152:153], v[176:179], off offset:512
	global_store_dwordx4 v[152:153], v[180:183], off offset:576
	v_pk_add_f32 v[166:167], v[186:187], v[242:243]
	v_pk_add_f32 v[164:165], v[184:185], v[240:241]
	v_pk_add_f32 v[172:173], v[188:189], v[244:245]
	v_add_co_u32_e32 v156, vcc, s40, v152
	v_pk_add_f32 v[174:175], v[190:191], v[246:247]
	v_pk_add_f32 v[178:179], v[194:195], v[250:251]
	v_pk_add_f32 v[176:177], v[192:193], v[248:249]
	global_store_dwordx4 v[136:137], v[164:167], off
	global_store_dwordx4 v[136:137], v[172:175], off offset:64
	global_store_dwordx4 v[136:137], v[176:179], off offset:512
	v_addc_co_u32_e32 v157, vcc, 0, v153, vcc
	ds_bpermute_b32 v172, v162, v98
	ds_bpermute_b32 v173, v162, v99
	v_pk_add_f32 v[134:135], v[134:135], v[252:253]
	global_load_dwordx4 v[164:167], v[156:157], off
	s_waitcnt lgkmcnt(2)
	v_pk_add_f32 v[132:133], v[132:133], v[138:139]
	global_store_dwordx4 v[136:137], v[132:135], off offset:576
	ds_bpermute_b32 v132, v162, v96
	ds_bpermute_b32 v133, v162, v97
	ds_bpermute_b32 v136, v162, v90
	ds_bpermute_b32 v137, v162, v91
	ds_bpermute_b32 v138, v162, v88
	ds_bpermute_b32 v139, v162, v89
	s_waitcnt lgkmcnt(6)
	v_pk_add_f32 v[134:135], v[198:199], v[172:173]
	global_load_dwordx4 v[172:175], v[156:157], off offset:64
	s_waitcnt lgkmcnt(4)
	v_pk_add_f32 v[132:133], v[196:197], v[132:133]
	global_store_dwordx4 v[208:209], v[132:135], off
	ds_bpermute_b32 v180, v162, v76
	ds_bpermute_b32 v182, v162, v78
	s_waitcnt lgkmcnt(4)
	v_pk_add_f32 v[134:135], v[202:203], v[136:137]
	ds_bpermute_b32 v136, v162, v86
	ds_bpermute_b32 v137, v162, v87
	s_waitcnt lgkmcnt(4)
	v_pk_add_f32 v[132:133], v[200:201], v[138:139]
	ds_bpermute_b32 v138, v162, v84
	ds_bpermute_b32 v139, v162, v85
	global_store_dwordx4 v[208:209], v[132:135], off offset:64
	global_load_dwordx4 v[132:135], v[156:157], off offset:512
	s_waitcnt lgkmcnt(2)
	v_pk_add_f32 v[178:179], v[206:207], v[136:137]
	ds_bpermute_b32 v183, v162, v79
	s_waitcnt lgkmcnt(1)
	v_pk_add_f32 v[176:177], v[204:205], v[138:139]
	global_load_dwordx4 v[136:139], v[156:157], off offset:576
	ds_bpermute_b32 v181, v162, v77
	global_store_dwordx4 v[208:209], v[176:179], off offset:512
	v_add_co_u32_e32 v204, vcc, s41, v152
	s_waitcnt lgkmcnt(1)
	v_pk_add_f32 v[178:179], v[214:215], v[182:183]
	s_waitcnt lgkmcnt(0)
	v_pk_add_f32 v[176:177], v[212:213], v[180:181]
	ds_bpermute_b32 v180, v162, v80
	ds_bpermute_b32 v181, v162, v81
	ds_bpermute_b32 v182, v162, v82
	ds_bpermute_b32 v183, v162, v83
	v_addc_co_u32_e32 v205, vcc, 0, v153, vcc
	global_store_dwordx4 v[208:209], v[176:179], off offset:576
	global_load_dwordx4 v[176:179], v[204:205], off
	s_waitcnt lgkmcnt(0)
	v_pk_add_f32 v[182:183], v[218:219], v[182:183]
	global_load_dwordx4 v[184:187], v[204:205], off offset:64
	v_pk_add_f32 v[180:181], v[216:217], v[180:181]
	ds_bpermute_b32 v188, v162, v74
	ds_bpermute_b32 v189, v162, v75
	global_store_dwordx4 v[154:155], v[180:183], off
	ds_bpermute_b32 v180, v162, v72
	ds_bpermute_b32 v181, v162, v73
	ds_bpermute_b32 v192, v162, v68
	s_waitcnt lgkmcnt(3)
	v_pk_add_f32 v[182:183], v[222:223], v[188:189]
	global_load_dwordx4 v[188:191], v[204:205], off offset:512
	ds_bpermute_b32 v193, v162, v69
	s_waitcnt lgkmcnt(2)
	v_pk_add_f32 v[180:181], v[220:221], v[180:181]
	ds_bpermute_b32 v194, v162, v70
	ds_bpermute_b32 v195, v162, v71
	global_store_dwordx4 v[154:155], v[180:183], off offset:64
	global_load_dwordx4 v[180:183], v[204:205], off offset:576
	ds_bpermute_b32 v200, v162, v64
	ds_bpermute_b32 v196, v162, v66
	ds_bpermute_b32 v197, v162, v67
	ds_bpermute_b32 v201, v162, v65
	v_add_co_u32_e32 v206, vcc, s42, v152
	s_waitcnt lgkmcnt(4)
	v_pk_add_f32 v[194:195], v[226:227], v[194:195]
	v_pk_add_f32 v[192:193], v[224:225], v[192:193]
	v_addc_co_u32_e32 v207, vcc, 0, v153, vcc
	global_store_dwordx4 v[154:155], v[192:195], off offset:512
	global_load_dwordx4 v[192:195], v[206:207], off
	s_waitcnt lgkmcnt(1)
	v_pk_add_f32 v[130:131], v[130:131], v[196:197]
	s_waitcnt lgkmcnt(0)
	v_pk_add_f32 v[128:129], v[128:129], v[200:201]
	global_load_dwordx4 v[196:199], v[206:207], off offset:64
	ds_bpermute_b32 v202, v162, v62
	ds_bpermute_b32 v203, v162, v63
	global_store_dwordx4 v[154:155], v[128:131], off offset:576
	ds_bpermute_b32 v128, v162, v60
	ds_bpermute_b32 v129, v162, v61
	ds_bpermute_b32 v208, v162, v58
	ds_bpermute_b32 v209, v162, v59
	s_waitcnt vmcnt(18) lgkmcnt(4)
	v_pk_add_f32 v[130:131], v[166:167], v[202:203]
	ds_bpermute_b32 v154, v162, v56
	global_load_dwordx4 v[200:203], v[206:207], off offset:512
	ds_bpermute_b32 v155, v162, v57
	s_waitcnt lgkmcnt(4)
	v_pk_add_f32 v[128:129], v[164:165], v[128:129]
	global_load_dwordx4 v[164:167], v[206:207], off offset:576
	ds_bpermute_b32 v212, v162, v44
	global_store_dwordx4 v[156:157], v[128:131], off
	ds_bpermute_b32 v214, v162, v46
	ds_bpermute_b32 v215, v162, v47
	s_waitcnt vmcnt(19) lgkmcnt(5)
	v_pk_add_f32 v[130:131], v[174:175], v[208:209]
	v_add_co_u32_e32 v208, vcc, s43, v152
	s_waitcnt lgkmcnt(3)
	v_pk_add_f32 v[128:129], v[172:173], v[154:155]
	v_addc_co_u32_e32 v209, vcc, 0, v153, vcc
	global_store_dwordx4 v[156:157], v[128:131], off offset:64
	ds_bpermute_b32 v172, v162, v48
	ds_bpermute_b32 v173, v162, v49
	global_load_dwordx4 v[128:131], v[208:209], off
	global_load_dwordx4 v[152:155], v[208:209], off offset:64
	ds_bpermute_b32 v174, v162, v50
	ds_bpermute_b32 v175, v162, v51
	ds_bpermute_b32 v213, v162, v45
	s_waitcnt vmcnt(19) lgkmcnt(3)
	v_pk_add_f32 v[132:133], v[132:133], v[172:173]
	ds_bpermute_b32 v172, v162, v54
	ds_bpermute_b32 v173, v162, v55
	s_waitcnt lgkmcnt(3)
	v_pk_add_f32 v[134:135], v[134:135], v[174:175]
	global_store_dwordx4 v[156:157], v[132:135], off offset:512
	s_waitcnt vmcnt(16) lgkmcnt(0)
	v_pk_add_f32 v[174:175], v[178:179], v[172:173]
	v_pk_add_f32 v[134:135], v[138:139], v[214:215]
	v_pk_add_f32 v[132:133], v[136:137], v[212:213]
	global_store_dwordx4 v[156:157], v[132:135], off offset:576
	global_load_dwordx4 v[132:135], v[208:209], off offset:512
	ds_bpermute_b32 v156, v162, v52
	global_load_dwordx4 v[136:139], v[208:209], off offset:576
	ds_bpermute_b32 v157, v162, v53
	ds_bpermute_b32 v212, v162, v40
	ds_bpermute_b32 v214, v162, v42
	ds_bpermute_b32 v215, v162, v43
	ds_bpermute_b32 v213, v162, v41
	s_waitcnt lgkmcnt(4)
	v_pk_add_f32 v[172:173], v[176:177], v[156:157]
	global_store_dwordx4 v[204:205], v[172:175], off
	ds_bpermute_b32 v156, v162, v32
	ds_bpermute_b32 v157, v162, v33
	s_waitcnt vmcnt(19) lgkmcnt(3)
	v_pk_add_f32 v[174:175], v[186:187], v[214:215]
	s_waitcnt lgkmcnt(2)
	v_pk_add_f32 v[172:173], v[184:185], v[212:213]
	global_store_dwordx4 v[204:205], v[172:175], off offset:64
	ds_bpermute_b32 v172, v162, v34
	ds_bpermute_b32 v173, v162, v35
	ds_bpermute_b32 v176, v162, v28
	ds_bpermute_b32 v178, v162, v30
	ds_bpermute_b32 v179, v162, v31
	ds_bpermute_b32 v177, v162, v29
	s_waitcnt vmcnt(18) lgkmcnt(4)
	v_pk_add_f32 v[174:175], v[190:191], v[172:173]
	v_pk_add_f32 v[172:173], v[188:189], v[156:157]
	global_store_dwordx4 v[204:205], v[172:175], off offset:512
	ds_bpermute_b32 v156, v162, v36
	ds_bpermute_b32 v157, v162, v37
	s_waitcnt vmcnt(17) lgkmcnt(3)
	v_pk_add_f32 v[174:175], v[182:183], v[178:179]
	s_waitcnt lgkmcnt(2)
	v_pk_add_f32 v[172:173], v[180:181], v[176:177]
	global_store_dwordx4 v[204:205], v[172:175], off offset:576
	ds_bpermute_b32 v172, v162, v38
	ds_bpermute_b32 v173, v162, v39
	ds_bpermute_b32 v176, v162, v24
	ds_bpermute_b32 v178, v162, v26
	ds_bpermute_b32 v179, v162, v27
	ds_bpermute_b32 v177, v162, v25
	s_waitcnt vmcnt(16) lgkmcnt(4)
	v_pk_add_f32 v[174:175], v[194:195], v[172:173]
	v_pk_add_f32 v[172:173], v[192:193], v[156:157]
	global_store_dwordx4 v[206:207], v[172:175], off
	ds_bpermute_b32 v156, v162, v16
	ds_bpermute_b32 v157, v162, v17
	s_waitcnt vmcnt(16) lgkmcnt(3)
	v_pk_add_f32 v[174:175], v[198:199], v[178:179]
	s_waitcnt lgkmcnt(2)
	v_pk_add_f32 v[172:173], v[196:197], v[176:177]
	ds_bpermute_b32 v176, v162, v12
	ds_bpermute_b32 v178, v162, v14
	ds_bpermute_b32 v179, v162, v15
	ds_bpermute_b32 v177, v162, v13
	global_store_dwordx4 v[206:207], v[172:175], off offset:64
	ds_bpermute_b32 v172, v162, v18
	ds_bpermute_b32 v173, v162, v19
	s_waitcnt vmcnt(14) lgkmcnt(3)
	v_pk_add_f32 v[166:167], v[166:167], v[178:179]
	s_waitcnt lgkmcnt(2)
	v_pk_add_f32 v[164:165], v[164:165], v[176:177]
	global_store_dwordx4 v[206:207], v[164:167], off offset:576
	ds_bpermute_b32 v164, v162, v22
	s_waitcnt lgkmcnt(1)
	v_pk_add_f32 v[174:175], v[202:203], v[172:173]
	v_pk_add_f32 v[172:173], v[200:201], v[156:157]
	ds_bpermute_b32 v156, v162, v20
	ds_bpermute_b32 v157, v162, v21
	ds_bpermute_b32 v165, v162, v23
	global_store_dwordx4 v[206:207], v[172:175], off offset:512
	ds_bpermute_b32 v166, v162, v8
	ds_bpermute_b32 v172, v162, v10
	ds_bpermute_b32 v173, v162, v11
	ds_bpermute_b32 v167, v162, v9
	s_waitcnt vmcnt(13) lgkmcnt(4)
	v_pk_add_f32 v[130:131], v[130:131], v[164:165]
	v_pk_add_f32 v[128:129], v[128:129], v[156:157]
	global_store_dwordx4 v[208:209], v[128:131], off
	s_waitcnt vmcnt(13) lgkmcnt(1)
	s_nop 0
	v_pk_add_f32 v[130:131], v[154:155], v[172:173]
	s_waitcnt lgkmcnt(0)
	v_pk_add_f32 v[128:129], v[152:153], v[166:167]
	global_store_dwordx4 v[208:209], v[128:131], off offset:64
	ds_bpermute_b32 v128, v162, v4
	ds_bpermute_b32 v129, v162, v5
	ds_bpermute_b32 v130, v162, v6
	ds_bpermute_b32 v131, v162, v7
	ds_bpermute_b32 v152, v162, v0
	ds_bpermute_b32 v154, v162, v2
	ds_bpermute_b32 v155, v162, v3
	ds_bpermute_b32 v153, v162, v1
	s_waitcnt vmcnt(11) lgkmcnt(4)
	v_pk_add_f32 v[130:131], v[134:135], v[130:131]
	v_pk_add_f32 v[128:129], v[132:133], v[128:129]
	global_store_dwordx4 v[208:209], v[128:131], off offset:512
	s_waitcnt vmcnt(11) lgkmcnt(1)
	s_nop 0
	v_pk_add_f32 v[130:131], v[138:139], v[154:155]
	s_waitcnt lgkmcnt(0)
	v_pk_add_f32 v[128:129], v[136:137], v[152:153]
	global_store_dwordx4 v[208:209], v[128:131], off offset:576
